# t2 + all per-phase s_setprio flips deleted in every GEMM K-loop (doc 7.4 step b as its own experiment)
# speedup vs baseline: 1.0039x; 1.0039x over previous
; #define PG8_STAGE(bufoff, gbase, voff) do { _Pragma("unroll") for (int _i = 0; _i < 2; ++_i) \
;         __builtin_amdgcn_global_load_lds((const unsigned*)((const char*)(gbase) + (voff)[_i]), (LAS unsigned*)(lds + (bufoff) + ldsw + _i * 8192), 16, 0, 0); } while (0)
; #define PG8_LDA(dst, b, h) do { _Pragma("unroll") for (int m = 0; m < 4; ++m) _Pragma("unroll") for (int k = 0; k < 2; ++k) dst[m][k] = *(const LAS bf16x8*)(lds + PG8_SA(b, h) + aoff + m * 2048 + k * 1024); } while (0)
; #define PG8_LDB(dst, b, h) do { _Pragma("unroll") for (int n = 0; n < 2; ++n) _Pragma("unroll") for (int k = 0; k < 2; ++k) dst[n][k] = *(const LAS bf16x8*)(lds + PG8_SB(b, h) + boff + n * 2048 + k * 1024); } while (0)
; #define PG8_MMA(ai, bj, At, Bt) do { __builtin_amdgcn_s_setprio(1); _Pragma("unroll") for (int m = 0; m < 4; ++m) _Pragma("unroll") for (int n = 0; n < 2; ++n) _Pragma("unroll") for (int k = 0; k < 2; ++k) \
;         acc[ai][bj][m][n] = __builtin_amdgcn_mfma_f32_16x16x32_bf16(Bt[n][k], At[m][k], acc[ai][bj][m][n], 0, 0, 0); __builtin_amdgcn_s_setprio(0); } while (0)
; #define PG8_WAIT_V(n) asm volatile("s_waitcnt vmcnt(" #n ")" ::: "memory")
; #define PG8_WAIT_L(n) asm volatile("s_waitcnt lgkmcnt(" #n ")" ::: "memory")
; template <class Epi, class Sched, bool ALIGN_EPI, class Hook = NoHook>
; __device__ __forceinline__ void gemm_phase(LAS unsigned char* lds, const Gemm g, const Sched& S, const Epi& E, const Hook& H = Hook()) {
;     ...
;         for (int t = tb; t < te; t += 2) {
;             const bool last = (t == nt - 2);
;             const char* a1 = cA + (size_t)(t + 1) * kstep;
;             const char* a2 = last ? nA : cA + (size_t)(t + 2) * kstep; const char* b2 = last ? nB : cB + (size_t)(t + 2) * kstep;
;             const char* a3 = a2 + kstep; const char* b3 = b2 + kstep;
;             if (last && has_next) S.a_ready(nxt);
;             PG8_LDB(B0, 0, 0); PG8_LDB(B1, 0, 1); PG8_SCHED; PG8_LDA(At, 0, 0); PG8_STAGE(PG8_SA(1, 1), a1 + hA, voffA);
;             PG8_WAIT_V(8); PG8_WAIT_L(0); PG8_BAR; PG8_MMA(0, 0, At, B0); PG8_MMA(0, 1, At, B1); PG8_BAR; PG8_SCHED;
;             PG8_LDA(At, 0, 1); PG8_STAGE(PG8_SB(0, 0), b2, voffB); PG8_STAGE(PG8_SB(0, 1), b2 + hB, voffB); PG8_STAGE(PG8_SA(0, 0), a2, voffA);
;             PG8_WAIT_V(8); PG8_WAIT_L(0); PG8_BAR; PG8_MMA(1, 0, At, B0); PG8_MMA(1, 1, At, B1); PG8_BAR; PG8_SCHED;
.LBB0_199:
	ds_read_b128 v[130:133], v217
	ds_read_b128 v[134:137], v217 offset:1024
	s_add_i32 m0, s40, 0xc000
	s_nop 0
	global_load_lds_dwordx4 v172, s[4:5]
	ds_read_b128 v[138:141], v217 offset:2048
	ds_read_b128 v[142:145], v217 offset:3072
	ds_read_b128 v[146:149], v218
	ds_read_b128 v[150:153], v218 offset:1024
	ds_read_b128 v[154:157], v218 offset:2048
	ds_read_b128 v[158:161], v218 offset:3072
	ds_read_b128 v[180:183], v219
	s_add_i32 m0, s40, 0xe000
	s_nop 0
	global_load_lds_dwordx4 v174, s[4:5]
	s_add_u32 s34, s4, 0x100
	s_addc_u32 s35, s5, 0
	s_cmp_eq_u32 s64, 60
	s_cselect_b32 s39, s7, s35
	s_cselect_b32 s38, s8, s34
	s_cselect_b32 s37, s23, s63
	s_cselect_b32 s36, s25, s31
	ds_read_b128 v[184:187], v219 offset:1024
	ds_read_b128 v[188:191], v219 offset:2048
	ds_read_b128 v[192:195], v219 offset:3072
	ds_read_b128 v[196:199], v219 offset:4096
	ds_read_b128 v[200:203], v219 offset:5120
	ds_read_b128 v[204:207], v219 offset:6144
	ds_read_b128 v[208:211], v219 offset:7168
	s_barrier
	s_waitcnt lgkmcnt(0)
	v_mfma_f32_16x16x32_bf16 v[126:129], v[130:133], v[180:183], v[126:129]
	v_mfma_f32_16x16x32_bf16 v[94:97], v[138:141], v[180:183], v[94:97]
	v_mfma_f32_16x16x32_bf16 v[122:125], v[130:133], v[188:191], v[122:125]
	v_mfma_f32_16x16x32_bf16 v[90:93], v[138:141], v[188:191], v[90:93]
	v_mfma_f32_16x16x32_bf16 v[118:121], v[130:133], v[196:199], v[118:121]
	v_mfma_f32_16x16x32_bf16 v[86:89], v[138:141], v[196:199], v[86:89]
	v_mfma_f32_16x16x32_bf16 v[114:117], v[130:133], v[204:207], v[114:117]
	v_mfma_f32_16x16x32_bf16 v[82:85], v[138:141], v[204:207], v[82:85]
	v_mfma_f32_16x16x32_bf16 v[126:129], v[134:137], v[184:187], v[126:129]
	v_mfma_f32_16x16x32_bf16 v[94:97], v[142:145], v[184:187], v[94:97]
	v_mfma_f32_16x16x32_bf16 v[122:125], v[134:137], v[192:195], v[122:125]
	v_mfma_f32_16x16x32_bf16 v[90:93], v[142:145], v[192:195], v[90:93]
	v_mfma_f32_16x16x32_bf16 v[118:121], v[134:137], v[200:203], v[118:121]
	v_mfma_f32_16x16x32_bf16 v[86:89], v[142:145], v[200:203], v[86:89]
	v_mfma_f32_16x16x32_bf16 v[114:117], v[134:137], v[208:211], v[114:117]
	v_mfma_f32_16x16x32_bf16 v[82:85], v[142:145], v[208:211], v[82:85]
	v_mfma_f32_16x16x32_bf16 v[62:65], v[146:149], v[180:183], v[62:65]
	v_mfma_f32_16x16x32_bf16 v[30:33], v[154:157], v[180:183], v[30:33]
	v_mfma_f32_16x16x32_bf16 v[58:61], v[146:149], v[188:191], v[58:61]
	v_mfma_f32_16x16x32_bf16 v[26:29], v[154:157], v[188:191], v[26:29]
	v_mfma_f32_16x16x32_bf16 v[54:57], v[146:149], v[196:199], v[54:57]
	v_mfma_f32_16x16x32_bf16 v[22:25], v[154:157], v[196:199], v[22:25]
	v_mfma_f32_16x16x32_bf16 v[50:53], v[146:149], v[204:207], v[50:53]
	v_mfma_f32_16x16x32_bf16 v[18:21], v[154:157], v[204:207], v[18:21]
	v_mfma_f32_16x16x32_bf16 v[62:65], v[150:153], v[184:187], v[62:65]
	v_mfma_f32_16x16x32_bf16 v[30:33], v[158:161], v[184:187], v[30:33]
	v_mfma_f32_16x16x32_bf16 v[58:61], v[150:153], v[192:195], v[58:61]
	v_mfma_f32_16x16x32_bf16 v[26:29], v[158:161], v[192:195], v[26:29]
	v_mfma_f32_16x16x32_bf16 v[54:57], v[150:153], v[200:203], v[54:57]
	v_mfma_f32_16x16x32_bf16 v[22:25], v[158:161], v[200:203], v[22:25]
	v_mfma_f32_16x16x32_bf16 v[50:53], v[150:153], v[208:211], v[50:53]
	v_mfma_f32_16x16x32_bf16 v[18:21], v[158:161], v[208:211], v[18:21]
	s_waitcnt vmcnt(8)
	s_barrier
	s_add_i32 s4, s59, s21
	s_mov_b32 m0, s4
	ds_read_b128 v[180:183], v219 offset:16384
	ds_read_b128 v[184:187], v219 offset:17408
	global_load_lds_dwordx4 v164, s[36:37]
	ds_read_b128 v[188:191], v219 offset:18432
	s_add_i32 m0, s4, 0x2000
	s_add_u32 s4, s36, 0x100000
	s_addc_u32 s5, s37, 0
	s_add_i32 s65, s60, s21
	global_load_lds_dwordx4 v168, s[36:37]
	ds_read_b128 v[192:195], v219 offset:19456
	s_mov_b32 m0, s65
	s_nop 0
	global_load_lds_dwordx4 v164, s[4:5]
	ds_read_b128 v[196:199], v219 offset:20480
	s_add_i32 m0, s65, 0x2000
	s_nop 0
	global_load_lds_dwordx4 v168, s[4:5]
	ds_read_b128 v[200:203], v219 offset:21504
	s_mov_b32 m0, s40
	s_nop 0
	global_load_lds_dwordx4 v162, s[38:39]
	ds_read_b128 v[204:207], v219 offset:22528
	s_mov_b32 m0, s41
	s_nop 0
	global_load_lds_dwordx4 v166, s[38:39]
	ds_read_b128 v[208:211], v219 offset:23552
	s_barrier
	s_waitcnt lgkmcnt(0)
	v_mfma_f32_16x16x32_bf16 v[110:113], v[130:133], v[180:183], v[110:113]
	v_mfma_f32_16x16x32_bf16 v[78:81], v[138:141], v[180:183], v[78:81]
	v_mfma_f32_16x16x32_bf16 v[106:109], v[130:133], v[188:191], v[106:109]
	v_mfma_f32_16x16x32_bf16 v[74:77], v[138:141], v[188:191], v[74:77]
	v_mfma_f32_16x16x32_bf16 v[102:105], v[130:133], v[196:199], v[102:105]
	v_mfma_f32_16x16x32_bf16 v[70:73], v[138:141], v[196:199], v[70:73]
	v_mfma_f32_16x16x32_bf16 v[98:101], v[130:133], v[204:207], v[98:101]
	v_mfma_f32_16x16x32_bf16 v[66:69], v[138:141], v[204:207], v[66:69]
	v_mfma_f32_16x16x32_bf16 v[110:113], v[134:137], v[184:187], v[110:113]
	v_mfma_f32_16x16x32_bf16 v[78:81], v[142:145], v[184:187], v[78:81]
	v_mfma_f32_16x16x32_bf16 v[106:109], v[134:137], v[192:195], v[106:109]
	v_mfma_f32_16x16x32_bf16 v[74:77], v[142:145], v[192:195], v[74:77]
	v_mfma_f32_16x16x32_bf16 v[102:105], v[134:137], v[200:203], v[102:105]
	v_mfma_f32_16x16x32_bf16 v[70:73], v[142:145], v[200:203], v[70:73]
	v_mfma_f32_16x16x32_bf16 v[98:101], v[134:137], v[208:211], v[98:101]
	v_mfma_f32_16x16x32_bf16 v[66:69], v[142:145], v[208:211], v[66:69]
	v_mfma_f32_16x16x32_bf16 v[46:49], v[146:149], v[180:183], v[46:49]
	v_mfma_f32_16x16x32_bf16 v[14:17], v[154:157], v[180:183], v[14:17]
	v_mfma_f32_16x16x32_bf16 v[42:45], v[146:149], v[188:191], v[42:45]
	v_mfma_f32_16x16x32_bf16 v[10:13], v[154:157], v[188:191], v[10:13]
	v_mfma_f32_16x16x32_bf16 v[38:41], v[146:149], v[196:199], v[38:41]
	v_mfma_f32_16x16x32_bf16 v[6:9], v[154:157], v[196:199], v[6:9]
	v_mfma_f32_16x16x32_bf16 v[34:37], v[146:149], v[204:207], v[34:37]
	v_mfma_f32_16x16x32_bf16 v[2:5], v[154:157], v[204:207], v[2:5]
	v_mfma_f32_16x16x32_bf16 v[46:49], v[150:153], v[184:187], v[46:49]
	v_mfma_f32_16x16x32_bf16 v[14:17], v[158:161], v[184:187], v[14:17]
	v_mfma_f32_16x16x32_bf16 v[42:45], v[150:153], v[192:195], v[42:45]
	v_mfma_f32_16x16x32_bf16 v[10:13], v[158:161], v[192:195], v[10:13]
	v_mfma_f32_16x16x32_bf16 v[38:41], v[150:153], v[200:203], v[38:41]
	v_mfma_f32_16x16x32_bf16 v[6:9], v[158:161], v[200:203], v[6:9]
	v_mfma_f32_16x16x32_bf16 v[34:37], v[150:153], v[208:211], v[34:37]
	v_mfma_f32_16x16x32_bf16 v[2:5], v[158:161], v[208:211], v[2:5]
	s_waitcnt vmcnt(8)
	s_barrier
; #define PG8_STAGE(bufoff, gbase, voff) do { _Pragma("unroll") for (int _i = 0; _i < 2; ++_i) \
;         __builtin_amdgcn_global_load_lds((const unsigned*)((const char*)(gbase) + (voff)[_i]), (LAS unsigned*)(lds + (bufoff) + ldsw + _i * 8192), 16, 0, 0); } while (0)
; #define PG8_LDA(dst, b, h) do { _Pragma("unroll") for (int m = 0; m < 4; ++m) _Pragma("unroll") for (int k = 0; k < 2; ++k) dst[m][k] = *(const LAS bf16x8*)(lds + PG8_SA(b, h) + aoff + m * 2048 + k * 1024); } while (0)
; #define PG8_LDB(dst, b, h) do { _Pragma("unroll") for (int n = 0; n < 2; ++n) _Pragma("unroll") for (int k = 0; k < 2; ++k) dst[n][k] = *(const LAS bf16x8*)(lds + PG8_SB(b, h) + boff + n * 2048 + k * 1024); } while (0)
; #define PG8_MMA(ai, bj, At, Bt) do { __builtin_amdgcn_s_setprio(1); _Pragma("unroll") for (int m = 0; m < 4; ++m) _Pragma("unroll") for (int n = 0; n < 2; ++n) _Pragma("unroll") for (int k = 0; k < 2; ++k) \
;         acc[ai][bj][m][n] = __builtin_amdgcn_mfma_f32_16x16x32_bf16(Bt[n][k], At[m][k], acc[ai][bj][m][n], 0, 0, 0); __builtin_amdgcn_s_setprio(0); } while (0)
; #define PG8_WAIT_V(n) asm volatile("s_waitcnt vmcnt(" #n ")" ::: "memory")
; #define PG8_WAIT_L(n) asm volatile("s_waitcnt lgkmcnt(" #n ")" ::: "memory")
; #define PG8_BAR __builtin_amdgcn_s_barrier()
; #define PG8_SCHED __builtin_amdgcn_sched_barrier(0)
; template <class Epi, class Sched, bool ALIGN_EPI, class Hook = NoHook>
; __device__ __forceinline__ void gemm_phase(LAS unsigned char* lds, const Gemm g, const Sched& S, const Epi& E, const Hook& H = Hook()) {
;     ...
;             PG8_LDB(B0, 1, 0); PG8_LDB(B1, 1, 1); PG8_SCHED; PG8_LDA(At, 1, 0); PG8_STAGE(PG8_SA(0, 1), a2 + hA, voffA);
;             PG8_WAIT_V(8); PG8_WAIT_L(0); PG8_BAR; PG8_MMA(0, 0, At, B0); PG8_MMA(0, 1, At, B1); PG8_BAR; PG8_SCHED;
;             PG8_LDA(At, 1, 1); PG8_STAGE(PG8_SB(1, 0), b3, voffB); PG8_STAGE(PG8_SB(1, 1), b3 + hB, voffB); PG8_STAGE(PG8_SA(1, 0), a3, voffA);
;             PG8_WAIT_V(8); PG8_WAIT_L(0); PG8_BAR; PG8_MMA(1, 0, At, B0); PG8_MMA(1, 1, At, B1); PG8_BAR; PG8_SCHED;
;         }
	s_add_i32 s65, 0, 0x18000
	s_add_i32 s66, 0, 0x1c000
	v_add_u32_e32 v142, s65, v213
	v_add_u32_e32 v158, s66, v213
	ds_read_b128 v[130:133], v142
	ds_read_b128 v[134:137], v142 offset:1024
	s_add_u32 s4, s38, 0x8000
	s_addc_u32 s5, s39, 0
	s_mov_b32 m0, s42
	s_nop 0
	global_load_lds_dwordx4 v162, s[4:5]
	ds_read_b128 v[138:141], v142 offset:2048
	ds_read_b128 v[142:145], v142 offset:3072
	ds_read_b128 v[146:149], v158
	ds_read_b128 v[150:153], v158 offset:1024
	ds_read_b128 v[154:157], v158 offset:2048
	ds_read_b128 v[158:161], v158 offset:3072
	ds_read_b128 v[180:183], v219 offset:32768
	s_mov_b32 m0, s43
	s_nop 0
	global_load_lds_dwordx4 v166, s[4:5]
	ds_read_b128 v[184:187], v219 offset:33792
	ds_read_b128 v[188:191], v219 offset:34816
	ds_read_b128 v[192:195], v219 offset:35840
	ds_read_b128 v[196:199], v219 offset:36864
	ds_read_b128 v[200:203], v219 offset:37888
	ds_read_b128 v[204:207], v219 offset:38912
	ds_read_b128 v[208:211], v219 offset:39936
	s_barrier
	s_waitcnt lgkmcnt(0)
	v_mfma_f32_16x16x32_bf16 v[126:129], v[130:133], v[180:183], v[126:129]
	v_mfma_f32_16x16x32_bf16 v[94:97], v[138:141], v[180:183], v[94:97]
	v_mfma_f32_16x16x32_bf16 v[122:125], v[130:133], v[188:191], v[122:125]
	v_mfma_f32_16x16x32_bf16 v[90:93], v[138:141], v[188:191], v[90:93]
	v_mfma_f32_16x16x32_bf16 v[118:121], v[130:133], v[196:199], v[118:121]
	v_mfma_f32_16x16x32_bf16 v[86:89], v[138:141], v[196:199], v[86:89]
	v_mfma_f32_16x16x32_bf16 v[114:117], v[130:133], v[204:207], v[114:117]
	v_mfma_f32_16x16x32_bf16 v[82:85], v[138:141], v[204:207], v[82:85]
	v_mfma_f32_16x16x32_bf16 v[126:129], v[134:137], v[184:187], v[126:129]
	v_mfma_f32_16x16x32_bf16 v[94:97], v[142:145], v[184:187], v[94:97]
	v_mfma_f32_16x16x32_bf16 v[122:125], v[134:137], v[192:195], v[122:125]
	v_mfma_f32_16x16x32_bf16 v[90:93], v[142:145], v[192:195], v[90:93]
	v_mfma_f32_16x16x32_bf16 v[118:121], v[134:137], v[200:203], v[118:121]
	v_mfma_f32_16x16x32_bf16 v[86:89], v[142:145], v[200:203], v[86:89]
	v_mfma_f32_16x16x32_bf16 v[114:117], v[134:137], v[208:211], v[114:117]
	v_mfma_f32_16x16x32_bf16 v[82:85], v[142:145], v[208:211], v[82:85]
	v_mfma_f32_16x16x32_bf16 v[62:65], v[146:149], v[180:183], v[62:65]
	v_mfma_f32_16x16x32_bf16 v[30:33], v[154:157], v[180:183], v[30:33]
	v_mfma_f32_16x16x32_bf16 v[58:61], v[146:149], v[188:191], v[58:61]
	v_mfma_f32_16x16x32_bf16 v[26:29], v[154:157], v[188:191], v[26:29]
	v_mfma_f32_16x16x32_bf16 v[54:57], v[146:149], v[196:199], v[54:57]
	v_mfma_f32_16x16x32_bf16 v[22:25], v[154:157], v[196:199], v[22:25]
	v_mfma_f32_16x16x32_bf16 v[50:53], v[146:149], v[204:207], v[50:53]
	v_mfma_f32_16x16x32_bf16 v[18:21], v[154:157], v[204:207], v[18:21]
	v_mfma_f32_16x16x32_bf16 v[62:65], v[150:153], v[184:187], v[62:65]
	v_mfma_f32_16x16x32_bf16 v[30:33], v[158:161], v[184:187], v[30:33]
	v_mfma_f32_16x16x32_bf16 v[58:61], v[150:153], v[192:195], v[58:61]
	v_mfma_f32_16x16x32_bf16 v[26:29], v[158:161], v[192:195], v[26:29]
	v_mfma_f32_16x16x32_bf16 v[54:57], v[150:153], v[200:203], v[54:57]
	v_mfma_f32_16x16x32_bf16 v[22:25], v[158:161], v[200:203], v[22:25]
	v_mfma_f32_16x16x32_bf16 v[50:53], v[150:153], v[208:211], v[50:53]
	v_mfma_f32_16x16x32_bf16 v[18:21], v[158:161], v[208:211], v[18:21]
	s_waitcnt vmcnt(8)
	s_barrier
	s_add_i32 s4, s65, s21
	s_add_u32 s68, s36, s14
	s_addc_u32 s69, s37, s15
	s_mov_b32 m0, s4
	ds_read_b128 v[180:183], v219 offset:49152
	ds_read_b128 v[184:187], v219 offset:50176
	global_load_lds_dwordx4 v164, s[68:69]
	ds_read_b128 v[188:191], v219 offset:51200
	s_add_i32 m0, s4, 0x2000
	s_add_u32 s4, s36, 0x100080
	s_addc_u32 s5, s37, 0
	s_add_i32 s36, s66, s21
	global_load_lds_dwordx4 v168, s[68:69]
	ds_read_b128 v[192:195], v219 offset:52224
	s_mov_b32 m0, s36
	s_nop 0
	global_load_lds_dwordx4 v164, s[4:5]
	ds_read_b128 v[196:199], v219 offset:53248
	s_add_i32 m0, s36, 0x2000
	s_nop 0
	global_load_lds_dwordx4 v168, s[4:5]
	ds_read_b128 v[200:203], v219 offset:54272
	s_add_u32 s70, s38, s14
	s_addc_u32 s71, s39, s15
	s_mov_b32 m0, s51
	s_nop 0
	global_load_lds_dwordx4 v162, s[70:71]
	ds_read_b128 v[204:207], v219 offset:55296
	s_mov_b32 m0, s52
	s_nop 0
	global_load_lds_dwordx4 v166, s[70:71]
	s_add_i32 s64, s64, 2
	s_add_u32 s31, s31, 0x100
	s_addc_u32 s63, s63, 0
	s_cmp_gt_u32 s64, 61
	s_mov_b64 s[4:5], s[34:35]
	ds_read_b128 v[208:211], v219 offset:56320
	s_barrier
	s_waitcnt lgkmcnt(0)
	v_mfma_f32_16x16x32_bf16 v[110:113], v[130:133], v[180:183], v[110:113]
	v_mfma_f32_16x16x32_bf16 v[78:81], v[138:141], v[180:183], v[78:81]
	v_mfma_f32_16x16x32_bf16 v[106:109], v[130:133], v[188:191], v[106:109]
	v_mfma_f32_16x16x32_bf16 v[74:77], v[138:141], v[188:191], v[74:77]
	v_mfma_f32_16x16x32_bf16 v[102:105], v[130:133], v[196:199], v[102:105]
	v_mfma_f32_16x16x32_bf16 v[70:73], v[138:141], v[196:199], v[70:73]
	v_mfma_f32_16x16x32_bf16 v[98:101], v[130:133], v[204:207], v[98:101]
	v_mfma_f32_16x16x32_bf16 v[66:69], v[138:141], v[204:207], v[66:69]
	v_mfma_f32_16x16x32_bf16 v[110:113], v[134:137], v[184:187], v[110:113]
	v_mfma_f32_16x16x32_bf16 v[78:81], v[142:145], v[184:187], v[78:81]
	v_mfma_f32_16x16x32_bf16 v[106:109], v[134:137], v[192:195], v[106:109]
	v_mfma_f32_16x16x32_bf16 v[74:77], v[142:145], v[192:195], v[74:77]
	v_mfma_f32_16x16x32_bf16 v[102:105], v[134:137], v[200:203], v[102:105]
	v_mfma_f32_16x16x32_bf16 v[70:73], v[142:145], v[200:203], v[70:73]
	v_mfma_f32_16x16x32_bf16 v[98:101], v[134:137], v[208:211], v[98:101]
	v_mfma_f32_16x16x32_bf16 v[66:69], v[142:145], v[208:211], v[66:69]
	v_mfma_f32_16x16x32_bf16 v[46:49], v[146:149], v[180:183], v[46:49]
	v_mfma_f32_16x16x32_bf16 v[14:17], v[154:157], v[180:183], v[14:17]
	v_mfma_f32_16x16x32_bf16 v[42:45], v[146:149], v[188:191], v[42:45]
	v_mfma_f32_16x16x32_bf16 v[10:13], v[154:157], v[188:191], v[10:13]
	v_mfma_f32_16x16x32_bf16 v[38:41], v[146:149], v[196:199], v[38:41]
	v_mfma_f32_16x16x32_bf16 v[6:9], v[154:157], v[196:199], v[6:9]
	v_mfma_f32_16x16x32_bf16 v[34:37], v[146:149], v[204:207], v[34:37]
	v_mfma_f32_16x16x32_bf16 v[2:5], v[154:157], v[204:207], v[2:5]
	v_mfma_f32_16x16x32_bf16 v[46:49], v[150:153], v[184:187], v[46:49]
	v_mfma_f32_16x16x32_bf16 v[14:17], v[158:161], v[184:187], v[14:17]
	v_mfma_f32_16x16x32_bf16 v[42:45], v[150:153], v[192:195], v[42:45]
	v_mfma_f32_16x16x32_bf16 v[10:13], v[158:161], v[192:195], v[10:13]
	v_mfma_f32_16x16x32_bf16 v[38:41], v[150:153], v[200:203], v[38:41]
	v_mfma_f32_16x16x32_bf16 v[6:9], v[158:161], v[200:203], v[6:9]
	v_mfma_f32_16x16x32_bf16 v[34:37], v[150:153], v[208:211], v[34:37]
	v_mfma_f32_16x16x32_bf16 v[2:5], v[158:161], v[208:211], v[2:5]
	s_waitcnt vmcnt(8)
	s_barrier
	s_cbranch_scc0 .LBB0_199
	s_branch .Lmy_d199X
; #define PG8_STAGE(bufoff, gbase, voff) do { _Pragma("unroll") for (int _i = 0; _i < 2; ++_i) \
;         __builtin_amdgcn_global_load_lds((const unsigned*)((const char*)(gbase) + (voff)[_i]), (LAS unsigned*)(lds + (bufoff) + ldsw + _i * 8192), 16, 0, 0); } while (0)
; #define PG8_LDA(dst, b, h) do { _Pragma("unroll") for (int m = 0; m < 4; ++m) _Pragma("unroll") for (int k = 0; k < 2; ++k) dst[m][k] = *(const LAS bf16x8*)(lds + PG8_SA(b, h) + aoff + m * 2048 + k * 1024); } while (0)
; #define PG8_LDB(dst, b, h) do { _Pragma("unroll") for (int n = 0; n < 2; ++n) _Pragma("unroll") for (int k = 0; k < 2; ++k) dst[n][k] = *(const LAS bf16x8*)(lds + PG8_SB(b, h) + boff + n * 2048 + k * 1024); } while (0)
; #define PG8_MMA(ai, bj, At, Bt) do { __builtin_amdgcn_s_setprio(1); _Pragma("unroll") for (int m = 0; m < 4; ++m) _Pragma("unroll") for (int n = 0; n < 2; ++n) _Pragma("unroll") for (int k = 0; k < 2; ++k) \
;         acc[ai][bj][m][n] = __builtin_amdgcn_mfma_f32_16x16x32_bf16(Bt[n][k], At[m][k], acc[ai][bj][m][n], 0, 0, 0); __builtin_amdgcn_s_setprio(0); } while (0)
; #define PG8_WAIT_V(n) asm volatile("s_waitcnt vmcnt(" #n ")" ::: "memory")
; #define PG8_WAIT_L(n) asm volatile("s_waitcnt lgkmcnt(" #n ")" ::: "memory")
; template <class Epi, class Sched, bool ALIGN_EPI, class Hook = NoHook>
; __device__ __forceinline__ void gemm_phase(LAS unsigned char* lds, const Gemm g, const Sched& S, const Epi& E, const Hook& H = Hook()) {
;     ...
;         for (int t = tb; t < te; t += 2) {
;             const bool last = (t == nt - 2);
;             const char* a1 = cA + (size_t)(t + 1) * kstep;
;             const char* a2 = last ? nA : cA + (size_t)(t + 2) * kstep; const char* b2 = last ? nB : cB + (size_t)(t + 2) * kstep;
;             const char* a3 = a2 + kstep; const char* b3 = b2 + kstep;
;             if (last && has_next) S.a_ready(nxt);
;             PG8_LDB(B0, 0, 0); PG8_LDB(B1, 0, 1); PG8_SCHED; PG8_LDA(At, 0, 0); PG8_STAGE(PG8_SA(1, 1), a1 + hA, voffA);
;             PG8_WAIT_V(8); PG8_WAIT_L(0); PG8_BAR; PG8_MMA(0, 0, At, B0); PG8_MMA(0, 1, At, B1); PG8_BAR; PG8_SCHED;
;             PG8_LDA(At, 0, 1); PG8_STAGE(PG8_SB(0, 0), b2, voffB); PG8_STAGE(PG8_SB(0, 1), b2 + hB, voffB); PG8_STAGE(PG8_SA(0, 0), a2, voffA);
;             PG8_WAIT_V(8); PG8_WAIT_L(0); PG8_BAR; PG8_MMA(1, 0, At, B0); PG8_MMA(1, 1, At, B1); PG8_BAR; PG8_SCHED;
.Lmy_d199B:
	ds_read_b128 v[130:133], v217
	ds_read_b128 v[134:137], v217 offset:1024
	s_add_i32 m0, s40, 0xc000
	s_nop 0
	global_load_lds_dwordx4 v172, s[4:5]
	ds_read_b128 v[138:141], v217 offset:2048
	ds_read_b128 v[142:145], v217 offset:3072
	ds_read_b128 v[146:149], v218
	ds_read_b128 v[150:153], v218 offset:1024
	ds_read_b128 v[154:157], v218 offset:2048
	ds_read_b128 v[158:161], v218 offset:3072
	ds_read_b128 v[180:183], v219
	s_add_i32 m0, s40, 0xe000
	s_nop 0
	global_load_lds_dwordx4 v174, s[4:5]
	s_add_u32 s34, s4, 0x100
	s_addc_u32 s35, s5, 0
	s_cmp_eq_u32 s64, 60
	s_cselect_b32 s39, s7, s35
	s_cselect_b32 s38, s8, s34
	s_cselect_b32 s37, s23, s63
	s_cselect_b32 s36, s25, s31
	ds_read_b128 v[184:187], v219 offset:1024
	ds_read_b128 v[188:191], v219 offset:2048
	ds_read_b128 v[192:195], v219 offset:3072
	ds_read_b128 v[196:199], v219 offset:4096
	ds_read_b128 v[200:203], v219 offset:5120
	ds_read_b128 v[204:207], v219 offset:6144
	ds_read_b128 v[208:211], v219 offset:7168
	s_waitcnt vmcnt(8) lgkmcnt(0)
	s_barrier
	v_mfma_f32_16x16x32_bf16 v[126:129], v[130:133], v[180:183], v[126:129]
	v_mfma_f32_16x16x32_bf16 v[94:97], v[138:141], v[180:183], v[94:97]
	v_mfma_f32_16x16x32_bf16 v[122:125], v[130:133], v[188:191], v[122:125]
	v_mfma_f32_16x16x32_bf16 v[90:93], v[138:141], v[188:191], v[90:93]
	v_mfma_f32_16x16x32_bf16 v[118:121], v[130:133], v[196:199], v[118:121]
	v_mfma_f32_16x16x32_bf16 v[86:89], v[138:141], v[196:199], v[86:89]
	v_mfma_f32_16x16x32_bf16 v[114:117], v[130:133], v[204:207], v[114:117]
	v_mfma_f32_16x16x32_bf16 v[82:85], v[138:141], v[204:207], v[82:85]
	v_mfma_f32_16x16x32_bf16 v[126:129], v[134:137], v[184:187], v[126:129]
	v_mfma_f32_16x16x32_bf16 v[94:97], v[142:145], v[184:187], v[94:97]
	v_mfma_f32_16x16x32_bf16 v[122:125], v[134:137], v[192:195], v[122:125]
	v_mfma_f32_16x16x32_bf16 v[90:93], v[142:145], v[192:195], v[90:93]
	v_mfma_f32_16x16x32_bf16 v[118:121], v[134:137], v[200:203], v[118:121]
	v_mfma_f32_16x16x32_bf16 v[86:89], v[142:145], v[200:203], v[86:89]
	v_mfma_f32_16x16x32_bf16 v[114:117], v[134:137], v[208:211], v[114:117]
	v_mfma_f32_16x16x32_bf16 v[82:85], v[142:145], v[208:211], v[82:85]
	v_mfma_f32_16x16x32_bf16 v[62:65], v[146:149], v[180:183], v[62:65]
	v_mfma_f32_16x16x32_bf16 v[30:33], v[154:157], v[180:183], v[30:33]
	v_mfma_f32_16x16x32_bf16 v[58:61], v[146:149], v[188:191], v[58:61]
	v_mfma_f32_16x16x32_bf16 v[26:29], v[154:157], v[188:191], v[26:29]
	v_mfma_f32_16x16x32_bf16 v[54:57], v[146:149], v[196:199], v[54:57]
	v_mfma_f32_16x16x32_bf16 v[22:25], v[154:157], v[196:199], v[22:25]
	v_mfma_f32_16x16x32_bf16 v[50:53], v[146:149], v[204:207], v[50:53]
	v_mfma_f32_16x16x32_bf16 v[18:21], v[154:157], v[204:207], v[18:21]
	v_mfma_f32_16x16x32_bf16 v[62:65], v[150:153], v[184:187], v[62:65]
	v_mfma_f32_16x16x32_bf16 v[30:33], v[158:161], v[184:187], v[30:33]
	v_mfma_f32_16x16x32_bf16 v[58:61], v[150:153], v[192:195], v[58:61]
	v_mfma_f32_16x16x32_bf16 v[26:29], v[158:161], v[192:195], v[26:29]
	v_mfma_f32_16x16x32_bf16 v[54:57], v[150:153], v[200:203], v[54:57]
	v_mfma_f32_16x16x32_bf16 v[22:25], v[158:161], v[200:203], v[22:25]
	v_mfma_f32_16x16x32_bf16 v[50:53], v[150:153], v[208:211], v[50:53]
	v_mfma_f32_16x16x32_bf16 v[18:21], v[158:161], v[208:211], v[18:21]
	s_barrier
	s_add_i32 s4, s59, s21
	s_mov_b32 m0, s4
	ds_read_b128 v[180:183], v219 offset:16384
	ds_read_b128 v[184:187], v219 offset:17408
	global_load_lds_dwordx4 v164, s[36:37]
	ds_read_b128 v[188:191], v219 offset:18432
	s_add_i32 m0, s4, 0x2000
	s_add_u32 s4, s36, 0x100000
	s_addc_u32 s5, s37, 0
	s_add_i32 s65, s60, s21
	global_load_lds_dwordx4 v168, s[36:37]
	ds_read_b128 v[192:195], v219 offset:19456
	s_mov_b32 m0, s65
	s_nop 0
	global_load_lds_dwordx4 v164, s[4:5]
	ds_read_b128 v[196:199], v219 offset:20480
	s_add_i32 m0, s65, 0x2000
	s_nop 0
	global_load_lds_dwordx4 v168, s[4:5]
	ds_read_b128 v[200:203], v219 offset:21504
	s_mov_b32 m0, s40
	s_nop 0
	global_load_lds_dwordx4 v162, s[38:39]
	ds_read_b128 v[204:207], v219 offset:22528
	s_mov_b32 m0, s41
	s_nop 0
	global_load_lds_dwordx4 v166, s[38:39]
	ds_read_b128 v[208:211], v219 offset:23552
	s_waitcnt vmcnt(8) lgkmcnt(0)
	s_barrier
	v_mfma_f32_16x16x32_bf16 v[110:113], v[130:133], v[180:183], v[110:113]
	v_mfma_f32_16x16x32_bf16 v[78:81], v[138:141], v[180:183], v[78:81]
	v_mfma_f32_16x16x32_bf16 v[106:109], v[130:133], v[188:191], v[106:109]
	v_mfma_f32_16x16x32_bf16 v[74:77], v[138:141], v[188:191], v[74:77]
	v_mfma_f32_16x16x32_bf16 v[102:105], v[130:133], v[196:199], v[102:105]
	v_mfma_f32_16x16x32_bf16 v[70:73], v[138:141], v[196:199], v[70:73]
	v_mfma_f32_16x16x32_bf16 v[98:101], v[130:133], v[204:207], v[98:101]
	v_mfma_f32_16x16x32_bf16 v[66:69], v[138:141], v[204:207], v[66:69]
	v_mfma_f32_16x16x32_bf16 v[110:113], v[134:137], v[184:187], v[110:113]
	v_mfma_f32_16x16x32_bf16 v[78:81], v[142:145], v[184:187], v[78:81]
	v_mfma_f32_16x16x32_bf16 v[106:109], v[134:137], v[192:195], v[106:109]
	v_mfma_f32_16x16x32_bf16 v[74:77], v[142:145], v[192:195], v[74:77]
	v_mfma_f32_16x16x32_bf16 v[102:105], v[134:137], v[200:203], v[102:105]
	v_mfma_f32_16x16x32_bf16 v[70:73], v[142:145], v[200:203], v[70:73]
	v_mfma_f32_16x16x32_bf16 v[98:101], v[134:137], v[208:211], v[98:101]
	v_mfma_f32_16x16x32_bf16 v[66:69], v[142:145], v[208:211], v[66:69]
	v_mfma_f32_16x16x32_bf16 v[46:49], v[146:149], v[180:183], v[46:49]
	v_mfma_f32_16x16x32_bf16 v[14:17], v[154:157], v[180:183], v[14:17]
	v_mfma_f32_16x16x32_bf16 v[42:45], v[146:149], v[188:191], v[42:45]
	v_mfma_f32_16x16x32_bf16 v[10:13], v[154:157], v[188:191], v[10:13]
	v_mfma_f32_16x16x32_bf16 v[38:41], v[146:149], v[196:199], v[38:41]
	v_mfma_f32_16x16x32_bf16 v[6:9], v[154:157], v[196:199], v[6:9]
	v_mfma_f32_16x16x32_bf16 v[34:37], v[146:149], v[204:207], v[34:37]
	v_mfma_f32_16x16x32_bf16 v[2:5], v[154:157], v[204:207], v[2:5]
	v_mfma_f32_16x16x32_bf16 v[46:49], v[150:153], v[184:187], v[46:49]
	v_mfma_f32_16x16x32_bf16 v[14:17], v[158:161], v[184:187], v[14:17]
	v_mfma_f32_16x16x32_bf16 v[42:45], v[150:153], v[192:195], v[42:45]
	v_mfma_f32_16x16x32_bf16 v[10:13], v[158:161], v[192:195], v[10:13]
	v_mfma_f32_16x16x32_bf16 v[38:41], v[150:153], v[200:203], v[38:41]
	v_mfma_f32_16x16x32_bf16 v[6:9], v[158:161], v[200:203], v[6:9]
	v_mfma_f32_16x16x32_bf16 v[34:37], v[150:153], v[208:211], v[34:37]
	v_mfma_f32_16x16x32_bf16 v[2:5], v[158:161], v[208:211], v[2:5]
	s_barrier
; #define PG8_STAGE(bufoff, gbase, voff) do { _Pragma("unroll") for (int _i = 0; _i < 2; ++_i) \
;         __builtin_amdgcn_global_load_lds((const unsigned*)((const char*)(gbase) + (voff)[_i]), (LAS unsigned*)(lds + (bufoff) + ldsw + _i * 8192), 16, 0, 0); } while (0)
; #define PG8_LDA(dst, b, h) do { _Pragma("unroll") for (int m = 0; m < 4; ++m) _Pragma("unroll") for (int k = 0; k < 2; ++k) dst[m][k] = *(const LAS bf16x8*)(lds + PG8_SA(b, h) + aoff + m * 2048 + k * 1024); } while (0)
; #define PG8_LDB(dst, b, h) do { _Pragma("unroll") for (int n = 0; n < 2; ++n) _Pragma("unroll") for (int k = 0; k < 2; ++k) dst[n][k] = *(const LAS bf16x8*)(lds + PG8_SB(b, h) + boff + n * 2048 + k * 1024); } while (0)
; #define PG8_MMA(ai, bj, At, Bt) do { __builtin_amdgcn_s_setprio(1); _Pragma("unroll") for (int m = 0; m < 4; ++m) _Pragma("unroll") for (int n = 0; n < 2; ++n) _Pragma("unroll") for (int k = 0; k < 2; ++k) \
;         acc[ai][bj][m][n] = __builtin_amdgcn_mfma_f32_16x16x32_bf16(Bt[n][k], At[m][k], acc[ai][bj][m][n], 0, 0, 0); __builtin_amdgcn_s_setprio(0); } while (0)
; #define PG8_WAIT_V(n) asm volatile("s_waitcnt vmcnt(" #n ")" ::: "memory")
; #define PG8_WAIT_L(n) asm volatile("s_waitcnt lgkmcnt(" #n ")" ::: "memory")
; #define PG8_BAR __builtin_amdgcn_s_barrier()
; #define PG8_SCHED __builtin_amdgcn_sched_barrier(0)
; template <class Epi, class Sched, bool ALIGN_EPI, class Hook = NoHook>
; __device__ __forceinline__ void gemm_phase(LAS unsigned char* lds, const Gemm g, const Sched& S, const Epi& E, const Hook& H = Hook()) {
;     ...
;             PG8_LDB(B0, 1, 0); PG8_LDB(B1, 1, 1); PG8_SCHED; PG8_LDA(At, 1, 0); PG8_STAGE(PG8_SA(0, 1), a2 + hA, voffA);
;             PG8_WAIT_V(8); PG8_WAIT_L(0); PG8_BAR; PG8_MMA(0, 0, At, B0); PG8_MMA(0, 1, At, B1); PG8_BAR; PG8_SCHED;
;             PG8_LDA(At, 1, 1); PG8_STAGE(PG8_SB(1, 0), b3, voffB); PG8_STAGE(PG8_SB(1, 1), b3 + hB, voffB); PG8_STAGE(PG8_SA(1, 0), a3, voffA);
;             PG8_WAIT_V(8); PG8_WAIT_L(0); PG8_BAR; PG8_MMA(1, 0, At, B0); PG8_MMA(1, 1, At, B1); PG8_BAR; PG8_SCHED;
;         }
	s_add_i32 s65, 0, 0x18000
	s_add_i32 s66, 0, 0x1c000
	v_add_u32_e32 v142, s65, v213
	v_add_u32_e32 v158, s66, v213
	ds_read_b128 v[130:133], v142
	ds_read_b128 v[134:137], v142 offset:1024
	s_add_u32 s4, s38, 0x8000
	s_addc_u32 s5, s39, 0
	s_mov_b32 m0, s42
	s_nop 0
	global_load_lds_dwordx4 v162, s[4:5]
	ds_read_b128 v[138:141], v142 offset:2048
	ds_read_b128 v[142:145], v142 offset:3072
	ds_read_b128 v[146:149], v158
	ds_read_b128 v[150:153], v158 offset:1024
	ds_read_b128 v[154:157], v158 offset:2048
	ds_read_b128 v[158:161], v158 offset:3072
	ds_read_b128 v[180:183], v219 offset:32768
	s_mov_b32 m0, s43
	s_nop 0
	global_load_lds_dwordx4 v166, s[4:5]
	ds_read_b128 v[184:187], v219 offset:33792
	ds_read_b128 v[188:191], v219 offset:34816
	ds_read_b128 v[192:195], v219 offset:35840
	ds_read_b128 v[196:199], v219 offset:36864
	ds_read_b128 v[200:203], v219 offset:37888
	ds_read_b128 v[204:207], v219 offset:38912
	ds_read_b128 v[208:211], v219 offset:39936
	s_waitcnt vmcnt(8) lgkmcnt(0)
	s_barrier
	v_mfma_f32_16x16x32_bf16 v[126:129], v[130:133], v[180:183], v[126:129]
	v_mfma_f32_16x16x32_bf16 v[94:97], v[138:141], v[180:183], v[94:97]
	v_mfma_f32_16x16x32_bf16 v[122:125], v[130:133], v[188:191], v[122:125]
	v_mfma_f32_16x16x32_bf16 v[90:93], v[138:141], v[188:191], v[90:93]
	v_mfma_f32_16x16x32_bf16 v[118:121], v[130:133], v[196:199], v[118:121]
	v_mfma_f32_16x16x32_bf16 v[86:89], v[138:141], v[196:199], v[86:89]
	v_mfma_f32_16x16x32_bf16 v[114:117], v[130:133], v[204:207], v[114:117]
	v_mfma_f32_16x16x32_bf16 v[82:85], v[138:141], v[204:207], v[82:85]
	v_mfma_f32_16x16x32_bf16 v[126:129], v[134:137], v[184:187], v[126:129]
	v_mfma_f32_16x16x32_bf16 v[94:97], v[142:145], v[184:187], v[94:97]
	v_mfma_f32_16x16x32_bf16 v[122:125], v[134:137], v[192:195], v[122:125]
	v_mfma_f32_16x16x32_bf16 v[90:93], v[142:145], v[192:195], v[90:93]
	v_mfma_f32_16x16x32_bf16 v[118:121], v[134:137], v[200:203], v[118:121]
	v_mfma_f32_16x16x32_bf16 v[86:89], v[142:145], v[200:203], v[86:89]
	v_mfma_f32_16x16x32_bf16 v[114:117], v[134:137], v[208:211], v[114:117]
	v_mfma_f32_16x16x32_bf16 v[82:85], v[142:145], v[208:211], v[82:85]
	v_mfma_f32_16x16x32_bf16 v[62:65], v[146:149], v[180:183], v[62:65]
	v_mfma_f32_16x16x32_bf16 v[30:33], v[154:157], v[180:183], v[30:33]
	v_mfma_f32_16x16x32_bf16 v[58:61], v[146:149], v[188:191], v[58:61]
	v_mfma_f32_16x16x32_bf16 v[26:29], v[154:157], v[188:191], v[26:29]
	v_mfma_f32_16x16x32_bf16 v[54:57], v[146:149], v[196:199], v[54:57]
	v_mfma_f32_16x16x32_bf16 v[22:25], v[154:157], v[196:199], v[22:25]
	v_mfma_f32_16x16x32_bf16 v[50:53], v[146:149], v[204:207], v[50:53]
	v_mfma_f32_16x16x32_bf16 v[18:21], v[154:157], v[204:207], v[18:21]
	v_mfma_f32_16x16x32_bf16 v[62:65], v[150:153], v[184:187], v[62:65]
	v_mfma_f32_16x16x32_bf16 v[30:33], v[158:161], v[184:187], v[30:33]
	v_mfma_f32_16x16x32_bf16 v[58:61], v[150:153], v[192:195], v[58:61]
	v_mfma_f32_16x16x32_bf16 v[26:29], v[158:161], v[192:195], v[26:29]
	v_mfma_f32_16x16x32_bf16 v[54:57], v[150:153], v[200:203], v[54:57]
	v_mfma_f32_16x16x32_bf16 v[22:25], v[158:161], v[200:203], v[22:25]
	v_mfma_f32_16x16x32_bf16 v[50:53], v[150:153], v[208:211], v[50:53]
	v_mfma_f32_16x16x32_bf16 v[18:21], v[158:161], v[208:211], v[18:21]
	s_barrier
	s_add_i32 s4, s65, s21
	s_add_u32 s68, s36, s14
	s_addc_u32 s69, s37, s15
	s_mov_b32 m0, s4
	ds_read_b128 v[180:183], v219 offset:49152
	ds_read_b128 v[184:187], v219 offset:50176
	global_load_lds_dwordx4 v164, s[68:69]
	ds_read_b128 v[188:191], v219 offset:51200
	s_add_i32 m0, s4, 0x2000
	s_add_u32 s4, s36, 0x100080
	s_addc_u32 s5, s37, 0
	s_add_i32 s36, s66, s21
	global_load_lds_dwordx4 v168, s[68:69]
	ds_read_b128 v[192:195], v219 offset:52224
	s_mov_b32 m0, s36
	s_nop 0
	global_load_lds_dwordx4 v164, s[4:5]
	ds_read_b128 v[196:199], v219 offset:53248
	s_add_i32 m0, s36, 0x2000
	s_nop 0
	global_load_lds_dwordx4 v168, s[4:5]
	ds_read_b128 v[200:203], v219 offset:54272
	s_add_u32 s70, s38, s14
	s_addc_u32 s71, s39, s15
	s_mov_b32 m0, s51
	s_nop 0
	global_load_lds_dwordx4 v162, s[70:71]
	ds_read_b128 v[204:207], v219 offset:55296
	s_mov_b32 m0, s52
	s_nop 0
	global_load_lds_dwordx4 v166, s[70:71]
	s_add_i32 s64, s64, 2
	s_add_u32 s31, s31, 0x100
	s_addc_u32 s63, s63, 0
	s_cmp_gt_u32 s64, 61
	s_mov_b64 s[4:5], s[34:35]
	ds_read_b128 v[208:211], v219 offset:56320
	s_waitcnt vmcnt(8) lgkmcnt(0)
	s_barrier
	v_mfma_f32_16x16x32_bf16 v[110:113], v[130:133], v[180:183], v[110:113]
	v_mfma_f32_16x16x32_bf16 v[78:81], v[138:141], v[180:183], v[78:81]
	v_mfma_f32_16x16x32_bf16 v[106:109], v[130:133], v[188:191], v[106:109]
	v_mfma_f32_16x16x32_bf16 v[74:77], v[138:141], v[188:191], v[74:77]
	v_mfma_f32_16x16x32_bf16 v[102:105], v[130:133], v[196:199], v[102:105]
	v_mfma_f32_16x16x32_bf16 v[70:73], v[138:141], v[196:199], v[70:73]
	v_mfma_f32_16x16x32_bf16 v[98:101], v[130:133], v[204:207], v[98:101]
	v_mfma_f32_16x16x32_bf16 v[66:69], v[138:141], v[204:207], v[66:69]
	v_mfma_f32_16x16x32_bf16 v[110:113], v[134:137], v[184:187], v[110:113]
	v_mfma_f32_16x16x32_bf16 v[78:81], v[142:145], v[184:187], v[78:81]
	v_mfma_f32_16x16x32_bf16 v[106:109], v[134:137], v[192:195], v[106:109]
	v_mfma_f32_16x16x32_bf16 v[74:77], v[142:145], v[192:195], v[74:77]
	v_mfma_f32_16x16x32_bf16 v[102:105], v[134:137], v[200:203], v[102:105]
	v_mfma_f32_16x16x32_bf16 v[70:73], v[142:145], v[200:203], v[70:73]
	v_mfma_f32_16x16x32_bf16 v[98:101], v[134:137], v[208:211], v[98:101]
	v_mfma_f32_16x16x32_bf16 v[66:69], v[142:145], v[208:211], v[66:69]
	v_mfma_f32_16x16x32_bf16 v[46:49], v[146:149], v[180:183], v[46:49]
	v_mfma_f32_16x16x32_bf16 v[14:17], v[154:157], v[180:183], v[14:17]
	v_mfma_f32_16x16x32_bf16 v[42:45], v[146:149], v[188:191], v[42:45]
	v_mfma_f32_16x16x32_bf16 v[10:13], v[154:157], v[188:191], v[10:13]
	v_mfma_f32_16x16x32_bf16 v[38:41], v[146:149], v[196:199], v[38:41]
	v_mfma_f32_16x16x32_bf16 v[6:9], v[154:157], v[196:199], v[6:9]
	v_mfma_f32_16x16x32_bf16 v[34:37], v[146:149], v[204:207], v[34:37]
	v_mfma_f32_16x16x32_bf16 v[2:5], v[154:157], v[204:207], v[2:5]
	v_mfma_f32_16x16x32_bf16 v[46:49], v[150:153], v[184:187], v[46:49]
	v_mfma_f32_16x16x32_bf16 v[14:17], v[158:161], v[184:187], v[14:17]
	v_mfma_f32_16x16x32_bf16 v[42:45], v[150:153], v[192:195], v[42:45]
	v_mfma_f32_16x16x32_bf16 v[10:13], v[158:161], v[192:195], v[10:13]
	v_mfma_f32_16x16x32_bf16 v[38:41], v[150:153], v[200:203], v[38:41]
	v_mfma_f32_16x16x32_bf16 v[6:9], v[158:161], v[200:203], v[6:9]
	v_mfma_f32_16x16x32_bf16 v[34:37], v[150:153], v[208:211], v[34:37]
	v_mfma_f32_16x16x32_bf16 v[2:5], v[158:161], v[208:211], v[2:5]
	s_barrier
	s_cbranch_scc0 .Lmy_d199B

; #define PG8_STAGE(bufoff, gbase, voff) do { _Pragma("unroll") for (int _i = 0; _i < 2; ++_i) \
;         __builtin_amdgcn_global_load_lds((const unsigned*)((const char*)(gbase) + (voff)[_i]), (LAS unsigned*)(lds + (bufoff) + ldsw + _i * 8192), 16, 0, 0); } while (0)
; #define PG8_LDA(dst, b, h) do { _Pragma("unroll") for (int m = 0; m < 4; ++m) _Pragma("unroll") for (int k = 0; k < 2; ++k) dst[m][k] = *(const LAS bf16x8*)(lds + PG8_SA(b, h) + aoff + m * 2048 + k * 1024); } while (0)
; #define PG8_LDB(dst, b, h) do { _Pragma("unroll") for (int n = 0; n < 2; ++n) _Pragma("unroll") for (int k = 0; k < 2; ++k) dst[n][k] = *(const LAS bf16x8*)(lds + PG8_SB(b, h) + boff + n * 2048 + k * 1024); } while (0)
; #define PG8_MMA(ai, bj, At, Bt) do { __builtin_amdgcn_s_setprio(1); _Pragma("unroll") for (int m = 0; m < 4; ++m) _Pragma("unroll") for (int n = 0; n < 2; ++n) _Pragma("unroll") for (int k = 0; k < 2; ++k) \
;         acc[ai][bj][m][n] = __builtin_amdgcn_mfma_f32_16x16x32_bf16(Bt[n][k], At[m][k], acc[ai][bj][m][n], 0, 0, 0); __builtin_amdgcn_s_setprio(0); } while (0)
; #define PG8_WAIT_V(n) asm volatile("s_waitcnt vmcnt(" #n ")" ::: "memory")
; #define PG8_WAIT_L(n) asm volatile("s_waitcnt lgkmcnt(" #n ")" ::: "memory")
; template <class Epi, class Sched, bool ALIGN_EPI, class Hook = NoHook>
; __device__ __forceinline__ void gemm_phase(LAS unsigned char* lds, const Gemm g, const Sched& S, const Epi& E, const Hook& H = Hook()) {
;     ...
;         for (int t = tb; t < te; t += 2) {
;             const bool last = (t == nt - 2);
;             const char* a1 = cA + (size_t)(t + 1) * kstep;
;             const char* a2 = last ? nA : cA + (size_t)(t + 2) * kstep; const char* b2 = last ? nB : cB + (size_t)(t + 2) * kstep;
;             const char* a3 = a2 + kstep; const char* b3 = b2 + kstep;
;             if (last && has_next) S.a_ready(nxt);
;             PG8_LDB(B0, 0, 0); PG8_LDB(B1, 0, 1); PG8_SCHED; PG8_LDA(At, 0, 0); PG8_STAGE(PG8_SA(1, 1), a1 + hA, voffA);
;             PG8_WAIT_V(8); PG8_WAIT_L(0); PG8_BAR; PG8_MMA(0, 0, At, B0); PG8_MMA(0, 1, At, B1); PG8_BAR; PG8_SCHED;
;             PG8_LDA(At, 0, 1); PG8_STAGE(PG8_SB(0, 0), b2, voffB); PG8_STAGE(PG8_SB(0, 1), b2 + hB, voffB); PG8_STAGE(PG8_SA(0, 0), a2, voffA);
;             PG8_WAIT_V(8); PG8_WAIT_L(0); PG8_BAR; PG8_MMA(1, 0, At, B0); PG8_MMA(1, 1, At, B1); PG8_BAR; PG8_SCHED;
.LBB0_262:
	ds_read_b128 v[148:151], v145
	ds_read_b128 v[152:155], v145 offset:1024
	s_add_u32 s22, s20, 0xfff00080
	s_addc_u32 s23, s21, -1
	s_cmp_eq_u32 s50, 4
	s_cselect_b32 s25, s11, s23
	s_cselect_b32 s24, s13, s22
	s_cselect_b32 s23, s40, s43
	s_cselect_b32 s22, s41, s42
	s_add_i32 m0, s5, 0xc000
	s_nop 0
	global_load_lds_dwordx4 v136, s[20:21]
	ds_read_b128 v[156:159], v145 offset:2048
	ds_read_b128 v[160:163], v145 offset:3072
	ds_read_b128 v[164:167], v146
	ds_read_b128 v[168:171], v146 offset:1024
	ds_read_b128 v[172:175], v146 offset:2048
	ds_read_b128 v[176:179], v146 offset:3072
	ds_read_b128 v[180:183], v147
	s_add_i32 m0, s5, 0xe000
	s_nop 0
	global_load_lds_dwordx4 v138, s[20:21]
	ds_read_b128 v[184:187], v147 offset:1024
	ds_read_b128 v[188:191], v147 offset:2048
	ds_read_b128 v[192:195], v147 offset:3072
	ds_read_b128 v[196:199], v147 offset:4096
	ds_read_b128 v[200:203], v147 offset:5120
	ds_read_b128 v[204:207], v147 offset:6144
	ds_read_b128 v[208:211], v147 offset:7168
	s_waitcnt vmcnt(8) lgkmcnt(0)
	s_barrier
	v_mfma_f32_16x16x32_bf16 v[126:129], v[148:151], v[180:183], v[126:129]
	v_mfma_f32_16x16x32_bf16 v[122:125], v[156:159], v[180:183], v[122:125]
	v_mfma_f32_16x16x32_bf16 v[118:121], v[148:151], v[188:191], v[118:121]
	v_mfma_f32_16x16x32_bf16 v[114:117], v[156:159], v[188:191], v[114:117]
	v_mfma_f32_16x16x32_bf16 v[106:109], v[148:151], v[196:199], v[106:109]
	v_mfma_f32_16x16x32_bf16 v[98:101], v[156:159], v[196:199], v[98:101]
	v_mfma_f32_16x16x32_bf16 v[90:93], v[148:151], v[204:207], v[90:93]
	v_mfma_f32_16x16x32_bf16 v[82:85], v[156:159], v[204:207], v[82:85]
	v_mfma_f32_16x16x32_bf16 v[126:129], v[152:155], v[184:187], v[126:129]
	v_mfma_f32_16x16x32_bf16 v[122:125], v[160:163], v[184:187], v[122:125]
	v_mfma_f32_16x16x32_bf16 v[118:121], v[152:155], v[192:195], v[118:121]
	v_mfma_f32_16x16x32_bf16 v[114:117], v[160:163], v[192:195], v[114:117]
	v_mfma_f32_16x16x32_bf16 v[106:109], v[152:155], v[200:203], v[106:109]
	v_mfma_f32_16x16x32_bf16 v[98:101], v[160:163], v[200:203], v[98:101]
	v_mfma_f32_16x16x32_bf16 v[90:93], v[152:155], v[208:211], v[90:93]
	v_mfma_f32_16x16x32_bf16 v[82:85], v[160:163], v[208:211], v[82:85]
	v_mfma_f32_16x16x32_bf16 v[110:113], v[164:167], v[180:183], v[110:113]
	v_mfma_f32_16x16x32_bf16 v[102:105], v[172:175], v[180:183], v[102:105]
	v_mfma_f32_16x16x32_bf16 v[94:97], v[164:167], v[188:191], v[94:97]
	v_mfma_f32_16x16x32_bf16 v[86:89], v[172:175], v[188:191], v[86:89]
	v_mfma_f32_16x16x32_bf16 v[78:81], v[164:167], v[196:199], v[78:81]
	v_mfma_f32_16x16x32_bf16 v[74:77], v[172:175], v[196:199], v[74:77]
	v_mfma_f32_16x16x32_bf16 v[70:73], v[164:167], v[204:207], v[70:73]
	v_mfma_f32_16x16x32_bf16 v[66:69], v[172:175], v[204:207], v[66:69]
	v_mfma_f32_16x16x32_bf16 v[110:113], v[168:171], v[184:187], v[110:113]
	v_mfma_f32_16x16x32_bf16 v[102:105], v[176:179], v[184:187], v[102:105]
	v_mfma_f32_16x16x32_bf16 v[94:97], v[168:171], v[192:195], v[94:97]
	v_mfma_f32_16x16x32_bf16 v[86:89], v[176:179], v[192:195], v[86:89]
	v_mfma_f32_16x16x32_bf16 v[78:81], v[168:171], v[200:203], v[78:81]
	v_mfma_f32_16x16x32_bf16 v[74:77], v[176:179], v[200:203], v[74:77]
	v_mfma_f32_16x16x32_bf16 v[70:73], v[168:171], v[208:211], v[70:73]
	v_mfma_f32_16x16x32_bf16 v[66:69], v[176:179], v[208:211], v[66:69]
	s_barrier
	s_add_i32 s51, s38, s29
	s_mov_b32 m0, s51
	ds_read_b128 v[180:183], v147 offset:16384
	ds_read_b128 v[184:187], v147 offset:17408
	global_load_lds_dwordx4 v132, s[22:23]
	ds_read_b128 v[188:191], v147 offset:18432
	s_add_i32 m0, s51, 0x2000
	s_add_u32 s52, s22, 0x100000
	s_addc_u32 s53, s23, 0
	s_add_i32 s51, s39, s29
	global_load_lds_dwordx4 v130, s[22:23]
	ds_read_b128 v[192:195], v147 offset:19456
	s_mov_b32 m0, s51
	s_nop 0
	global_load_lds_dwordx4 v132, s[52:53]
	ds_read_b128 v[196:199], v147 offset:20480
	s_add_i32 m0, s51, 0x2000
	s_nop 0
	global_load_lds_dwordx4 v130, s[52:53]
	ds_read_b128 v[200:203], v147 offset:21504
	s_add_u32 s56, s24, s8
	s_addc_u32 s57, s25, s9
	s_mov_b32 m0, s5
	s_nop 0
	global_load_lds_dwordx4 v132, s[24:25]
	ds_read_b128 v[204:207], v147 offset:22528
	s_mov_b32 m0, s7
	s_nop 0
	global_load_lds_dwordx4 v130, s[24:25]
	ds_read_b128 v[208:211], v147 offset:23552
	s_waitcnt vmcnt(8) lgkmcnt(0)
	s_barrier
	v_mfma_f32_16x16x32_bf16 v[62:65], v[148:151], v[180:183], v[62:65]
	v_mfma_f32_16x16x32_bf16 v[58:61], v[156:159], v[180:183], v[58:61]
	v_mfma_f32_16x16x32_bf16 v[54:57], v[148:151], v[188:191], v[54:57]
	v_mfma_f32_16x16x32_bf16 v[50:53], v[156:159], v[188:191], v[50:53]
	v_mfma_f32_16x16x32_bf16 v[38:41], v[148:151], v[196:199], v[38:41]
	v_mfma_f32_16x16x32_bf16 v[34:37], v[156:159], v[196:199], v[34:37]
	v_mfma_f32_16x16x32_bf16 v[22:25], v[148:151], v[204:207], v[22:25]
	v_mfma_f32_16x16x32_bf16 v[18:21], v[156:159], v[204:207], v[18:21]
	v_mfma_f32_16x16x32_bf16 v[62:65], v[152:155], v[184:187], v[62:65]
	v_mfma_f32_16x16x32_bf16 v[58:61], v[160:163], v[184:187], v[58:61]
	v_mfma_f32_16x16x32_bf16 v[54:57], v[152:155], v[192:195], v[54:57]
	v_mfma_f32_16x16x32_bf16 v[50:53], v[160:163], v[192:195], v[50:53]
	v_mfma_f32_16x16x32_bf16 v[38:41], v[152:155], v[200:203], v[38:41]
	v_mfma_f32_16x16x32_bf16 v[34:37], v[160:163], v[200:203], v[34:37]
	v_mfma_f32_16x16x32_bf16 v[22:25], v[152:155], v[208:211], v[22:25]
	v_mfma_f32_16x16x32_bf16 v[18:21], v[160:163], v[208:211], v[18:21]
	v_mfma_f32_16x16x32_bf16 v[46:49], v[164:167], v[180:183], v[46:49]
	v_mfma_f32_16x16x32_bf16 v[42:45], v[172:175], v[180:183], v[42:45]
	v_mfma_f32_16x16x32_bf16 v[30:33], v[164:167], v[188:191], v[30:33]
	v_mfma_f32_16x16x32_bf16 v[26:29], v[172:175], v[188:191], v[26:29]
	v_mfma_f32_16x16x32_bf16 v[14:17], v[164:167], v[196:199], v[14:17]
	v_mfma_f32_16x16x32_bf16 v[10:13], v[172:175], v[196:199], v[10:13]
	v_mfma_f32_16x16x32_bf16 v[6:9], v[164:167], v[204:207], v[6:9]
	v_mfma_f32_16x16x32_bf16 v[2:5], v[172:175], v[204:207], v[2:5]
	v_mfma_f32_16x16x32_bf16 v[46:49], v[168:171], v[184:187], v[46:49]
	v_mfma_f32_16x16x32_bf16 v[42:45], v[176:179], v[184:187], v[42:45]
	v_mfma_f32_16x16x32_bf16 v[30:33], v[168:171], v[192:195], v[30:33]
	v_mfma_f32_16x16x32_bf16 v[26:29], v[176:179], v[192:195], v[26:29]
	v_mfma_f32_16x16x32_bf16 v[14:17], v[168:171], v[200:203], v[14:17]
	v_mfma_f32_16x16x32_bf16 v[10:13], v[176:179], v[200:203], v[10:13]
	v_mfma_f32_16x16x32_bf16 v[6:9], v[168:171], v[208:211], v[6:9]
	v_mfma_f32_16x16x32_bf16 v[2:5], v[176:179], v[208:211], v[2:5]
	s_barrier
; #define PG8_STAGE(bufoff, gbase, voff) do { _Pragma("unroll") for (int _i = 0; _i < 2; ++_i) \
;         __builtin_amdgcn_global_load_lds((const unsigned*)((const char*)(gbase) + (voff)[_i]), (LAS unsigned*)(lds + (bufoff) + ldsw + _i * 8192), 16, 0, 0); } while (0)
; #define PG8_LDA(dst, b, h) do { _Pragma("unroll") for (int m = 0; m < 4; ++m) _Pragma("unroll") for (int k = 0; k < 2; ++k) dst[m][k] = *(const LAS bf16x8*)(lds + PG8_SA(b, h) + aoff + m * 2048 + k * 1024); } while (0)
; #define PG8_LDB(dst, b, h) do { _Pragma("unroll") for (int n = 0; n < 2; ++n) _Pragma("unroll") for (int k = 0; k < 2; ++k) dst[n][k] = *(const LAS bf16x8*)(lds + PG8_SB(b, h) + boff + n * 2048 + k * 1024); } while (0)
; #define PG8_MMA(ai, bj, At, Bt) do { __builtin_amdgcn_s_setprio(1); _Pragma("unroll") for (int m = 0; m < 4; ++m) _Pragma("unroll") for (int n = 0; n < 2; ++n) _Pragma("unroll") for (int k = 0; k < 2; ++k) \
;         acc[ai][bj][m][n] = __builtin_amdgcn_mfma_f32_16x16x32_bf16(Bt[n][k], At[m][k], acc[ai][bj][m][n], 0, 0, 0); __builtin_amdgcn_s_setprio(0); } while (0)
; #define PG8_WAIT_V(n) asm volatile("s_waitcnt vmcnt(" #n ")" ::: "memory")
; #define PG8_WAIT_L(n) asm volatile("s_waitcnt lgkmcnt(" #n ")" ::: "memory")
; #define PG8_BAR __builtin_amdgcn_s_barrier()
; #define PG8_SCHED __builtin_amdgcn_sched_barrier(0)
; template <class Epi, class Sched, bool ALIGN_EPI, class Hook = NoHook>
; __device__ __forceinline__ void gemm_phase(LAS unsigned char* lds, const Gemm g, const Sched& S, const Epi& E, const Hook& H = Hook()) {
;     ...
;             PG8_LDB(B0, 1, 0); PG8_LDB(B1, 1, 1); PG8_SCHED; PG8_LDA(At, 1, 0); PG8_STAGE(PG8_SA(0, 1), a2 + hA, voffA);
;             PG8_WAIT_V(8); PG8_WAIT_L(0); PG8_BAR; PG8_MMA(0, 0, At, B0); PG8_MMA(0, 1, At, B1); PG8_BAR; PG8_SCHED;
;             PG8_LDA(At, 1, 1); PG8_STAGE(PG8_SB(1, 0), b3, voffB); PG8_STAGE(PG8_SB(1, 1), b3 + hB, voffB); PG8_STAGE(PG8_SA(1, 0), a3, voffA);
;             PG8_WAIT_V(8); PG8_WAIT_L(0); PG8_BAR; PG8_MMA(1, 0, At, B0); PG8_MMA(1, 1, At, B1); PG8_BAR; PG8_SCHED;
	s_add_i32 s51, 0, 0x18000
	s_add_i32 s52, 0, 0x1c000
	v_add_u32_e32 v160, s51, v144
	v_add_u32_e32 v176, s52, v144
	ds_read_b128 v[148:151], v160
	ds_read_b128 v[152:155], v160 offset:1024
	s_add_u32 s24, s24, 0x100000
	s_addc_u32 s25, s25, 0
	s_mov_b32 m0, s30
	s_nop 0
	global_load_lds_dwordx4 v132, s[24:25]
	ds_read_b128 v[156:159], v160 offset:2048
	ds_read_b128 v[160:163], v160 offset:3072
	ds_read_b128 v[164:167], v176
	ds_read_b128 v[168:171], v176 offset:1024
	ds_read_b128 v[172:175], v176 offset:2048
	ds_read_b128 v[176:179], v176 offset:3072
	ds_read_b128 v[180:183], v147 offset:32768
	s_mov_b32 m0, s31
	s_nop 0
	global_load_lds_dwordx4 v130, s[24:25]
	ds_read_b128 v[184:187], v147 offset:33792
	ds_read_b128 v[188:191], v147 offset:34816
	ds_read_b128 v[192:195], v147 offset:35840
	ds_read_b128 v[196:199], v147 offset:36864
	ds_read_b128 v[200:203], v147 offset:37888
	ds_read_b128 v[204:207], v147 offset:38912
	ds_read_b128 v[208:211], v147 offset:39936
	s_waitcnt vmcnt(8) lgkmcnt(0)
	s_barrier
	v_mfma_f32_16x16x32_bf16 v[126:129], v[148:151], v[180:183], v[126:129]
	v_mfma_f32_16x16x32_bf16 v[122:125], v[156:159], v[180:183], v[122:125]
	v_mfma_f32_16x16x32_bf16 v[118:121], v[148:151], v[188:191], v[118:121]
	v_mfma_f32_16x16x32_bf16 v[114:117], v[156:159], v[188:191], v[114:117]
	v_mfma_f32_16x16x32_bf16 v[106:109], v[148:151], v[196:199], v[106:109]
	v_mfma_f32_16x16x32_bf16 v[98:101], v[156:159], v[196:199], v[98:101]
	v_mfma_f32_16x16x32_bf16 v[90:93], v[148:151], v[204:207], v[90:93]
	v_mfma_f32_16x16x32_bf16 v[82:85], v[156:159], v[204:207], v[82:85]
	v_mfma_f32_16x16x32_bf16 v[126:129], v[152:155], v[184:187], v[126:129]
	v_mfma_f32_16x16x32_bf16 v[122:125], v[160:163], v[184:187], v[122:125]
	v_mfma_f32_16x16x32_bf16 v[118:121], v[152:155], v[192:195], v[118:121]
	v_mfma_f32_16x16x32_bf16 v[114:117], v[160:163], v[192:195], v[114:117]
	v_mfma_f32_16x16x32_bf16 v[106:109], v[152:155], v[200:203], v[106:109]
	v_mfma_f32_16x16x32_bf16 v[98:101], v[160:163], v[200:203], v[98:101]
	v_mfma_f32_16x16x32_bf16 v[90:93], v[152:155], v[208:211], v[90:93]
	v_mfma_f32_16x16x32_bf16 v[82:85], v[160:163], v[208:211], v[82:85]
	v_mfma_f32_16x16x32_bf16 v[110:113], v[164:167], v[180:183], v[110:113]
	v_mfma_f32_16x16x32_bf16 v[102:105], v[172:175], v[180:183], v[102:105]
	v_mfma_f32_16x16x32_bf16 v[94:97], v[164:167], v[188:191], v[94:97]
	v_mfma_f32_16x16x32_bf16 v[86:89], v[172:175], v[188:191], v[86:89]
	v_mfma_f32_16x16x32_bf16 v[78:81], v[164:167], v[196:199], v[78:81]
	v_mfma_f32_16x16x32_bf16 v[74:77], v[172:175], v[196:199], v[74:77]
	v_mfma_f32_16x16x32_bf16 v[70:73], v[164:167], v[204:207], v[70:73]
	v_mfma_f32_16x16x32_bf16 v[66:69], v[172:175], v[204:207], v[66:69]
	v_mfma_f32_16x16x32_bf16 v[110:113], v[168:171], v[184:187], v[110:113]
	v_mfma_f32_16x16x32_bf16 v[102:105], v[176:179], v[184:187], v[102:105]
	v_mfma_f32_16x16x32_bf16 v[94:97], v[168:171], v[192:195], v[94:97]
	v_mfma_f32_16x16x32_bf16 v[86:89], v[176:179], v[192:195], v[86:89]
	v_mfma_f32_16x16x32_bf16 v[78:81], v[168:171], v[200:203], v[78:81]
	v_mfma_f32_16x16x32_bf16 v[74:77], v[176:179], v[200:203], v[74:77]
	v_mfma_f32_16x16x32_bf16 v[70:73], v[168:171], v[208:211], v[70:73]
	v_mfma_f32_16x16x32_bf16 v[66:69], v[176:179], v[208:211], v[66:69]
	s_barrier
	s_add_i32 s24, s51, s29
	s_add_u32 s54, s22, s8
	s_addc_u32 s55, s23, s9
	s_mov_b32 m0, s24
	ds_read_b128 v[180:183], v147 offset:49152
	ds_read_b128 v[184:187], v147 offset:50176
	global_load_lds_dwordx4 v132, s[54:55]
	ds_read_b128 v[188:191], v147 offset:51200
	s_add_i32 m0, s24, 0x2000
	s_add_u32 s22, s22, 0x100080
	s_addc_u32 s23, s23, 0
	s_add_i32 s24, s52, s29
	global_load_lds_dwordx4 v130, s[54:55]
	ds_read_b128 v[192:195], v147 offset:52224
	s_mov_b32 m0, s24
	s_nop 0
	global_load_lds_dwordx4 v132, s[22:23]
	ds_read_b128 v[196:199], v147 offset:53248
	s_add_i32 m0, s24, 0x2000
	s_nop 0
	global_load_lds_dwordx4 v130, s[22:23]
	ds_read_b128 v[200:203], v147 offset:54272
	s_mov_b32 m0, s35
	s_nop 0
	global_load_lds_dwordx4 v132, s[56:57]
	ds_read_b128 v[204:207], v147 offset:55296
	s_mov_b32 m0, s36
	s_nop 0
	global_load_lds_dwordx4 v130, s[56:57]
	s_add_i32 s50, s50, 2
	s_add_u32 s20, s20, 0x100
	s_addc_u32 s21, s21, 0
	s_add_u32 s42, s42, 0x100
	s_addc_u32 s43, s43, 0
	s_cmp_gt_u32 s50, 5
	ds_read_b128 v[208:211], v147 offset:56320
	s_waitcnt vmcnt(8) lgkmcnt(0)
	s_barrier
; #define PG8_MMA(ai, bj, At, Bt) do { __builtin_amdgcn_s_setprio(1); _Pragma("unroll") for (int m = 0; m < 4; ++m) _Pragma("unroll") for (int n = 0; n < 2; ++n) _Pragma("unroll") for (int k = 0; k < 2; ++k) \
;         acc[ai][bj][m][n] = __builtin_amdgcn_mfma_f32_16x16x32_bf16(Bt[n][k], At[m][k], acc[ai][bj][m][n], 0, 0, 0); __builtin_amdgcn_s_setprio(0); } while (0)
; #define PG8_WAIT_V(n) asm volatile("s_waitcnt vmcnt(" #n ")" ::: "memory")
; #define PG8_WAIT_L(n) asm volatile("s_waitcnt lgkmcnt(" #n ")" ::: "memory")
; #define PG8_BAR __builtin_amdgcn_s_barrier()
; #define PG8_SCHED __builtin_amdgcn_sched_barrier(0)
;     __device__ __forceinline__ void operator()(const f32x4 (&acc)[2][2][4][2], const Unit& u, int wr, int wc, int fr, int fq) const {
;         float* base = C + (size_t)(u.ka / kslab) * slab_stride;
;         const int row0 = u.pm * BM + wr * 64 + fr, col0 = wc * 32 + 4 * fq;
; #pragma unroll
;         for (int ai = 0; ai < 2; ++ai)
; #pragma unroll
;             for (int m = 0; m < 4; ++m) { float* rowp = base + (size_t)(row0 + ai * HALF + m * 16) * 256 + col0;
; #pragma unroll
;                 for (int bj = 0; bj < 2; ++bj)
; #pragma unroll
;                     for (int n = 0; n < 2; ++n) *(f32x4*)(rowp + bj * HALF + n * 16) = acc[ai][bj][m][n]; }
;     }
; template <class Epi, class Sched, bool ALIGN_EPI, class Hook = NoHook>
; __device__ __forceinline__ void gemm_phase(LAS unsigned char* lds, const Gemm g, const Sched& S, const Epi& E, const Hook& H = Hook()) {
;     ...
;             PG8_WAIT_V(8); PG8_WAIT_L(0); PG8_BAR; PG8_MMA(1, 0, At, B0); PG8_MMA(1, 1, At, B1); PG8_BAR; PG8_SCHED;
;         }
;         if constexpr (Hook::ON) H.after(te, acc, cur, wr, wc, fr, fq);
;         }
;         if constexpr (ALIGN_EPI) { if (wr == 0) PG8_BAR; }
;         if constexpr (!Epi::AFTER_DRAIN) { E(acc, cur, wr, wc, fr, fq); S.done(cur); }
;         if (!has_next) break;
	v_mfma_f32_16x16x32_bf16 v[62:65], v[148:151], v[180:183], v[62:65]
	v_mfma_f32_16x16x32_bf16 v[58:61], v[156:159], v[180:183], v[58:61]
	v_mfma_f32_16x16x32_bf16 v[54:57], v[148:151], v[188:191], v[54:57]
	v_mfma_f32_16x16x32_bf16 v[50:53], v[156:159], v[188:191], v[50:53]
	v_mfma_f32_16x16x32_bf16 v[38:41], v[148:151], v[196:199], v[38:41]
	v_mfma_f32_16x16x32_bf16 v[34:37], v[156:159], v[196:199], v[34:37]
	v_mfma_f32_16x16x32_bf16 v[22:25], v[148:151], v[204:207], v[22:25]
	v_mfma_f32_16x16x32_bf16 v[18:21], v[156:159], v[204:207], v[18:21]
	v_mfma_f32_16x16x32_bf16 v[62:65], v[152:155], v[184:187], v[62:65]
	v_mfma_f32_16x16x32_bf16 v[58:61], v[160:163], v[184:187], v[58:61]
	v_mfma_f32_16x16x32_bf16 v[54:57], v[152:155], v[192:195], v[54:57]
	v_mfma_f32_16x16x32_bf16 v[50:53], v[160:163], v[192:195], v[50:53]
	v_mfma_f32_16x16x32_bf16 v[38:41], v[152:155], v[200:203], v[38:41]
	v_mfma_f32_16x16x32_bf16 v[34:37], v[160:163], v[200:203], v[34:37]
	v_mfma_f32_16x16x32_bf16 v[22:25], v[152:155], v[208:211], v[22:25]
	v_mfma_f32_16x16x32_bf16 v[18:21], v[160:163], v[208:211], v[18:21]
	v_mfma_f32_16x16x32_bf16 v[46:49], v[164:167], v[180:183], v[46:49]
	v_mfma_f32_16x16x32_bf16 v[42:45], v[172:175], v[180:183], v[42:45]
	v_mfma_f32_16x16x32_bf16 v[30:33], v[164:167], v[188:191], v[30:33]
	v_mfma_f32_16x16x32_bf16 v[26:29], v[172:175], v[188:191], v[26:29]
	v_mfma_f32_16x16x32_bf16 v[14:17], v[164:167], v[196:199], v[14:17]
	v_mfma_f32_16x16x32_bf16 v[10:13], v[172:175], v[196:199], v[10:13]
	v_mfma_f32_16x16x32_bf16 v[6:9], v[164:167], v[204:207], v[6:9]
	v_mfma_f32_16x16x32_bf16 v[2:5], v[172:175], v[204:207], v[2:5]
	v_mfma_f32_16x16x32_bf16 v[46:49], v[168:171], v[184:187], v[46:49]
	v_mfma_f32_16x16x32_bf16 v[42:45], v[176:179], v[184:187], v[42:45]
	v_mfma_f32_16x16x32_bf16 v[30:33], v[168:171], v[192:195], v[30:33]
	v_mfma_f32_16x16x32_bf16 v[26:29], v[176:179], v[192:195], v[26:29]
	v_mfma_f32_16x16x32_bf16 v[14:17], v[168:171], v[200:203], v[14:17]
	v_mfma_f32_16x16x32_bf16 v[10:13], v[176:179], v[200:203], v[10:13]
	v_mfma_f32_16x16x32_bf16 v[6:9], v[168:171], v[208:211], v[6:9]
	v_mfma_f32_16x16x32_bf16 v[2:5], v[176:179], v[208:211], v[2:5]
	s_barrier
	s_cbranch_scc0 .LBB0_262
	s_ashr_i32 s11, s6, 31
	s_lshr_b32 s11, s11, 23
	s_add_i32 s6, s6, s11
	s_ashr_i32 s20, s6, 9
	s_ashr_i32 s21, s20, 31
	v_lshl_add_u32 v148, s4, 8, v1
	s_lshl_b64 s[20:21], s[20:21], 23
	v_ashrrev_i32_e32 v149, 31, v148
	v_lshl_add_u64 v[150:151], v[134:135], 0, s[20:21]
	v_lshlrev_b64 v[152:153], 10, v[148:149]
	v_lshl_add_u64 v[152:153], v[150:151], 0, v[152:153]
	global_store_dwordx4 v[152:153], v[126:129], off
	global_store_dwordx4 v[152:153], v[122:125], off offset:64
	global_store_dwordx4 v[152:153], v[110:113], off offset:512
	global_store_dwordx4 v[152:153], v[102:105], off offset:576
	s_mov_b32 s4, 0x20000
	s_mov_b64 s[20:21], 0x20000
	v_or_b32_e32 v102, 16, v148
	v_ashrrev_i32_e32 v103, 31, v102
	v_lshlrev_b64 v[102:103], 10, v[102:103]
	v_lshl_add_u64 v[102:103], v[150:151], 0, v[102:103]
	global_store_dwordx4 v[102:103], v[118:121], off
	global_store_dwordx4 v[102:103], v[114:117], off offset:64
	global_store_dwordx4 v[102:103], v[94:97], off offset:512
	global_store_dwordx4 v[102:103], v[86:89], off offset:576
	s_mov_b32 s6, s12
	s_mov_b64 s[22:23], s[18:19]
	v_or_b32_e32 v86, 32, v148
	v_ashrrev_i32_e32 v87, 31, v86
	v_lshlrev_b64 v[86:87], 10, v[86:87]
	v_lshl_add_u64 v[86:87], v[150:151], 0, v[86:87]
	global_store_dwordx4 v[86:87], v[106:109], off
	global_store_dwordx4 v[86:87], v[98:101], off offset:64
	global_store_dwordx4 v[86:87], v[78:81], off offset:512
	global_store_dwordx4 v[86:87], v[74:77], off offset:576
	s_nop 1
	v_or_b32_e32 v74, 48, v148
	v_ashrrev_i32_e32 v75, 31, v74
	v_lshlrev_b64 v[74:75], 10, v[74:75]
	v_lshl_add_u64 v[74:75], v[150:151], 0, v[74:75]
	global_store_dwordx4 v[74:75], v[90:93], off
	global_store_dwordx4 v[74:75], v[82:85], off offset:64
	global_store_dwordx4 v[74:75], v[70:73], off offset:512
	global_store_dwordx4 v[74:75], v[66:69], off offset:576
	s_nop 1
	v_add_co_u32_e32 v68, vcc, s4, v152
	s_mov_b32 s4, 0x24000
	s_nop 0
	v_addc_co_u32_e32 v69, vcc, 0, v153, vcc
	v_lshl_add_u64 v[66:67], v[152:153], 0, s[20:21]
	global_store_dwordx4 v[68:69], v[62:65], off
	global_store_dwordx4 v[66:67], v[58:61], off offset:64
	global_store_dwordx4 v[66:67], v[46:49], off offset:512
	global_store_dwordx4 v[66:67], v[42:45], off offset:576
	s_mov_b64 s[20:21], 0x24000
	s_nop 0
	v_add_co_u32_e32 v44, vcc, s4, v152
	s_mov_b32 s4, 0x28000
	s_nop 0
	v_addc_co_u32_e32 v45, vcc, 0, v153, vcc
	v_lshl_add_u64 v[42:43], v[152:153], 0, s[20:21]
	global_store_dwordx4 v[44:45], v[54:57], off
	global_store_dwordx4 v[42:43], v[50:53], off offset:64
	global_store_dwordx4 v[42:43], v[30:33], off offset:512
	global_store_dwordx4 v[42:43], v[26:29], off offset:576
	s_mov_b64 s[20:21], 0x28000
	s_nop 0
	v_add_co_u32_e32 v28, vcc, s4, v152
	v_lshl_add_u64 v[26:27], v[152:153], 0, s[20:21]
	s_nop 0
	v_addc_co_u32_e32 v29, vcc, 0, v153, vcc
	global_store_dwordx4 v[28:29], v[38:41], off
	global_store_dwordx4 v[26:27], v[34:37], off offset:64
	global_store_dwordx4 v[26:27], v[14:17], off offset:512
	global_store_dwordx4 v[26:27], v[10:13], off offset:576
	s_mov_b64 s[20:21], 0x2c000
	s_mov_b32 s4, s10
	v_add_co_u32_e32 v12, vcc, 0x2c000, v152
	v_lshl_add_u64 v[10:11], v[152:153], 0, s[20:21]
	s_nop 0
	v_addc_co_u32_e32 v13, vcc, 0, v153, vcc
	s_and_b64 vcc, exec, s[2:3]
	s_mov_b64 s[20:21], s[14:15]
	global_store_dwordx4 v[12:13], v[22:25], off
	global_store_dwordx4 v[10:11], v[18:21], off offset:64
	global_store_dwordx4 v[10:11], v[6:9], off offset:512
	global_store_dwordx4 v[10:11], v[2:5], off offset:576
	s_cbranch_vccz .LBB0_259
	s_waitcnt vmcnt(0)
	s_cmpk_gt_u32 s26, 0xff
	s_cbranch_scc1 .LBB0_266
	s_barrier

; #define PG8_STAGE(bufoff, gbase, voff) do { _Pragma("unroll") for (int _i = 0; _i < 2; ++_i) \
;         __builtin_amdgcn_global_load_lds((const unsigned*)((const char*)(gbase) + (voff)[_i]), (LAS unsigned*)(lds + (bufoff) + ldsw + _i * 8192), 16, 0, 0); } while (0)
; #define PG8_LDA(dst, b, h) do { _Pragma("unroll") for (int m = 0; m < 4; ++m) _Pragma("unroll") for (int k = 0; k < 2; ++k) dst[m][k] = *(const LAS bf16x8*)(lds + PG8_SA(b, h) + aoff + m * 2048 + k * 1024); } while (0)
; #define PG8_LDB(dst, b, h) do { _Pragma("unroll") for (int n = 0; n < 2; ++n) _Pragma("unroll") for (int k = 0; k < 2; ++k) dst[n][k] = *(const LAS bf16x8*)(lds + PG8_SB(b, h) + boff + n * 2048 + k * 1024); } while (0)
; #define PG8_MMA(ai, bj, At, Bt) do { __builtin_amdgcn_s_setprio(1); _Pragma("unroll") for (int m = 0; m < 4; ++m) _Pragma("unroll") for (int n = 0; n < 2; ++n) _Pragma("unroll") for (int k = 0; k < 2; ++k) \
;         acc[ai][bj][m][n] = __builtin_amdgcn_mfma_f32_16x16x32_bf16(Bt[n][k], At[m][k], acc[ai][bj][m][n], 0, 0, 0); __builtin_amdgcn_s_setprio(0); } while (0)
; #define PG8_WAIT_V(n) asm volatile("s_waitcnt vmcnt(" #n ")" ::: "memory")
; #define PG8_WAIT_L(n) asm volatile("s_waitcnt lgkmcnt(" #n ")" ::: "memory")
; template <class Epi, class Sched, bool ALIGN_EPI, class Hook = NoHook>
; __device__ __forceinline__ void gemm_phase(LAS unsigned char* lds, const Gemm g, const Sched& S, const Epi& E, const Hook& H = Hook()) {
;     ...
;         for (int t = tb; t < te; t += 2) {
;             const bool last = (t == nt - 2);
;             const char* a1 = cA + (size_t)(t + 1) * kstep;
;             const char* a2 = last ? nA : cA + (size_t)(t + 2) * kstep; const char* b2 = last ? nB : cB + (size_t)(t + 2) * kstep;
;             const char* a3 = a2 + kstep; const char* b3 = b2 + kstep;
;             if (last && has_next) S.a_ready(nxt);
;             PG8_LDB(B0, 0, 0); PG8_LDB(B1, 0, 1); PG8_SCHED; PG8_LDA(At, 0, 0); PG8_STAGE(PG8_SA(1, 1), a1 + hA, voffA);
;             PG8_WAIT_V(8); PG8_WAIT_L(0); PG8_BAR; PG8_MMA(0, 0, At, B0); PG8_MMA(0, 1, At, B1); PG8_BAR; PG8_SCHED;
;             PG8_LDA(At, 0, 1); PG8_STAGE(PG8_SB(0, 0), b2, voffB); PG8_STAGE(PG8_SB(0, 1), b2 + hB, voffB); PG8_STAGE(PG8_SA(0, 0), a2, voffA);
;             PG8_WAIT_V(8); PG8_WAIT_L(0); PG8_BAR; PG8_MMA(1, 0, At, B0); PG8_MMA(1, 1, At, B1); PG8_BAR; PG8_SCHED;
.LBB0_783:
	v_add_u32_e32 v3, s56, v222
	s_add_i32 s67, s67, 2
	ds_read_b128 v[126:129], v3
	ds_read_b128 v[130:133], v3 offset:1024
	ds_read_b128 v[142:145], v3 offset:2048
	ds_read_b128 v[146:149], v3 offset:3072
	v_add_u32_e32 v3, s57, v222
	s_add_u32 s28, s22, s26
	s_addc_u32 s29, s23, s27
	s_add_u32 s28, s28, 0x100
	s_addc_u32 s29, s29, 0
	s_add_u32 s68, s63, s26
	s_addc_u32 s69, s64, s27
	s_cmpk_eq_i32 s26, 0x5f00
	s_cselect_b32 s31, s5, s29
	s_cselect_b32 s30, s4, s28
	s_cselect_b32 s29, s21, s69
	s_cselect_b32 s28, s20, s68
	ds_read_b128 v[150:153], v3
	ds_read_b128 v[154:157], v3 offset:1024
	ds_read_b128 v[158:161], v3 offset:2048
	ds_read_b128 v[162:165], v3 offset:3072
	v_lshl_add_u64 v[4:5], v[182:183], 0, s[26:27]
	s_add_i32 m0, s37, 0xc000
	s_nop 0
	global_load_lds_dwordx4 v[4:5], off
	ds_read_b128 v[186:189], v224
	ds_read_b128 v[190:193], v224 offset:1024
	ds_read_b128 v[194:197], v224 offset:2048
	ds_read_b128 v[198:201], v224 offset:3072
	ds_read_b128 v[202:205], v224 offset:4096
	ds_read_b128 v[206:209], v224 offset:5120
	ds_read_b128 v[210:213], v224 offset:6144
	ds_read_b128 v[214:217], v224 offset:7168
	v_lshl_add_u64 v[4:5], v[184:185], 0, s[26:27]
	s_add_i32 m0, s37, 0xe000
	s_nop 0
	global_load_lds_dwordx4 v[4:5], off
	s_waitcnt vmcnt(8) lgkmcnt(0)
	s_barrier
	v_mfma_f32_16x16x32_bf16 v[138:141], v[126:129], v[186:189], v[138:141]
	v_mfma_f32_16x16x32_bf16 v[134:137], v[142:145], v[186:189], v[134:137]
	v_mfma_f32_16x16x32_bf16 v[122:125], v[126:129], v[194:197], v[122:125]
	v_mfma_f32_16x16x32_bf16 v[118:121], v[142:145], v[194:197], v[118:121]
	v_mfma_f32_16x16x32_bf16 v[114:117], v[126:129], v[202:205], v[114:117]
	v_mfma_f32_16x16x32_bf16 v[110:113], v[142:145], v[202:205], v[110:113]
	v_mfma_f32_16x16x32_bf16 v[106:109], v[126:129], v[210:213], v[106:109]
	v_mfma_f32_16x16x32_bf16 v[102:105], v[142:145], v[210:213], v[102:105]
	v_mfma_f32_16x16x32_bf16 v[138:141], v[130:133], v[190:193], v[138:141]
	v_mfma_f32_16x16x32_bf16 v[134:137], v[146:149], v[190:193], v[134:137]
	v_mfma_f32_16x16x32_bf16 v[122:125], v[130:133], v[198:201], v[122:125]
	v_mfma_f32_16x16x32_bf16 v[118:121], v[146:149], v[198:201], v[118:121]
	v_mfma_f32_16x16x32_bf16 v[114:117], v[130:133], v[206:209], v[114:117]
	v_mfma_f32_16x16x32_bf16 v[110:113], v[146:149], v[206:209], v[110:113]
	v_mfma_f32_16x16x32_bf16 v[106:109], v[130:133], v[214:217], v[106:109]
	v_mfma_f32_16x16x32_bf16 v[102:105], v[146:149], v[214:217], v[102:105]
	v_mfma_f32_16x16x32_bf16 v[66:69], v[150:153], v[186:189], v[66:69]
	v_mfma_f32_16x16x32_bf16 v[62:65], v[158:161], v[186:189], v[62:65]
	v_mfma_f32_16x16x32_bf16 v[58:61], v[150:153], v[194:197], v[58:61]
	v_mfma_f32_16x16x32_bf16 v[54:57], v[158:161], v[194:197], v[54:57]
	v_mfma_f32_16x16x32_bf16 v[50:53], v[150:153], v[202:205], v[50:53]
	v_mfma_f32_16x16x32_bf16 v[46:49], v[158:161], v[202:205], v[46:49]
	v_mfma_f32_16x16x32_bf16 v[42:45], v[150:153], v[210:213], v[42:45]
	v_mfma_f32_16x16x32_bf16 v[38:41], v[158:161], v[210:213], v[38:41]
	v_mfma_f32_16x16x32_bf16 v[66:69], v[154:157], v[190:193], v[66:69]
	v_mfma_f32_16x16x32_bf16 v[62:65], v[162:165], v[190:193], v[62:65]
	v_mfma_f32_16x16x32_bf16 v[58:61], v[154:157], v[198:201], v[58:61]
	v_mfma_f32_16x16x32_bf16 v[54:57], v[162:165], v[198:201], v[54:57]
	v_mfma_f32_16x16x32_bf16 v[50:53], v[154:157], v[206:209], v[50:53]
	v_mfma_f32_16x16x32_bf16 v[46:49], v[162:165], v[206:209], v[46:49]
	v_mfma_f32_16x16x32_bf16 v[42:45], v[154:157], v[214:217], v[42:45]
	v_mfma_f32_16x16x32_bf16 v[38:41], v[162:165], v[214:217], v[38:41]
	s_barrier
	s_add_i32 s68, s56, s35
	s_mov_b32 m0, s68
	ds_read_b128 v[186:189], v224 offset:16384
	ds_read_b128 v[190:193], v224 offset:17408
	global_load_lds_dwordx4 v168, s[28:29]
	ds_read_b128 v[194:197], v224 offset:18432
	s_add_i32 m0, s68, 0x2000
	s_add_u32 s68, s28, 0x300000
	s_addc_u32 s69, s29, 0
	s_add_i32 s70, s57, s35
	global_load_lds_dwordx4 v172, s[28:29]
	ds_read_b128 v[198:201], v224 offset:19456
	s_mov_b32 m0, s70
	s_add_u32 s74, s30, s14
	s_addc_u32 s75, s31, s15
	global_load_lds_dwordx4 v168, s[68:69]
	ds_read_b128 v[202:205], v224 offset:20480
	s_add_i32 m0, s70, 0x2000
	s_nop 0
	global_load_lds_dwordx4 v172, s[68:69]
	ds_read_b128 v[206:209], v224 offset:21504
	s_mov_b32 m0, s37
	s_nop 0
	global_load_lds_dwordx4 v166, s[30:31]
	ds_read_b128 v[210:213], v224 offset:22528
	s_mov_b32 m0, s38
	s_nop 0
	global_load_lds_dwordx4 v170, s[30:31]
	ds_read_b128 v[214:217], v224 offset:23552
	s_waitcnt vmcnt(8) lgkmcnt(0)
	s_barrier
; #define PG8_STAGE(bufoff, gbase, voff) do { _Pragma("unroll") for (int _i = 0; _i < 2; ++_i) \
;         __builtin_amdgcn_global_load_lds((const unsigned*)((const char*)(gbase) + (voff)[_i]), (LAS unsigned*)(lds + (bufoff) + ldsw + _i * 8192), 16, 0, 0); } while (0)
; #define PG8_LDA(dst, b, h) do { _Pragma("unroll") for (int m = 0; m < 4; ++m) _Pragma("unroll") for (int k = 0; k < 2; ++k) dst[m][k] = *(const LAS bf16x8*)(lds + PG8_SA(b, h) + aoff + m * 2048 + k * 1024); } while (0)
; #define PG8_LDB(dst, b, h) do { _Pragma("unroll") for (int n = 0; n < 2; ++n) _Pragma("unroll") for (int k = 0; k < 2; ++k) dst[n][k] = *(const LAS bf16x8*)(lds + PG8_SB(b, h) + boff + n * 2048 + k * 1024); } while (0)
; #define PG8_MMA(ai, bj, At, Bt) do { __builtin_amdgcn_s_setprio(1); _Pragma("unroll") for (int m = 0; m < 4; ++m) _Pragma("unroll") for (int n = 0; n < 2; ++n) _Pragma("unroll") for (int k = 0; k < 2; ++k) \
;         acc[ai][bj][m][n] = __builtin_amdgcn_mfma_f32_16x16x32_bf16(Bt[n][k], At[m][k], acc[ai][bj][m][n], 0, 0, 0); __builtin_amdgcn_s_setprio(0); } while (0)
; #define PG8_WAIT_V(n) asm volatile("s_waitcnt vmcnt(" #n ")" ::: "memory")
; #define PG8_WAIT_L(n) asm volatile("s_waitcnt lgkmcnt(" #n ")" ::: "memory")
; #define PG8_BAR __builtin_amdgcn_s_barrier()
; #define PG8_SCHED __builtin_amdgcn_sched_barrier(0)
; template <class Epi, class Sched, bool ALIGN_EPI, class Hook = NoHook>
; __device__ __forceinline__ void gemm_phase(LAS unsigned char* lds, const Gemm g, const Sched& S, const Epi& E, const Hook& H = Hook()) {
;     ...
;             PG8_WAIT_V(8); PG8_WAIT_L(0); PG8_BAR; PG8_MMA(1, 0, At, B0); PG8_MMA(1, 1, At, B1); PG8_BAR; PG8_SCHED;
;             PG8_LDB(B0, 1, 0); PG8_LDB(B1, 1, 1); PG8_SCHED; PG8_LDA(At, 1, 0); PG8_STAGE(PG8_SA(0, 1), a2 + hA, voffA);
;             PG8_WAIT_V(8); PG8_WAIT_L(0); PG8_BAR; PG8_MMA(0, 0, At, B0); PG8_MMA(0, 1, At, B1); PG8_BAR; PG8_SCHED;
;             PG8_LDA(At, 1, 1); PG8_STAGE(PG8_SB(1, 0), b3, voffB); PG8_STAGE(PG8_SB(1, 1), b3 + hB, voffB); PG8_STAGE(PG8_SA(1, 0), a3, voffA);
	v_mfma_f32_16x16x32_bf16 v[98:101], v[126:129], v[186:189], v[98:101]
	v_mfma_f32_16x16x32_bf16 v[94:97], v[142:145], v[186:189], v[94:97]
	v_mfma_f32_16x16x32_bf16 v[90:93], v[126:129], v[194:197], v[90:93]
	v_mfma_f32_16x16x32_bf16 v[86:89], v[142:145], v[194:197], v[86:89]
	v_mfma_f32_16x16x32_bf16 v[82:85], v[126:129], v[202:205], v[82:85]
	v_mfma_f32_16x16x32_bf16 v[78:81], v[142:145], v[202:205], v[78:81]
	v_mfma_f32_16x16x32_bf16 v[74:77], v[126:129], v[210:213], v[74:77]
	v_mfma_f32_16x16x32_bf16 v[70:73], v[142:145], v[210:213], v[70:73]
	v_mfma_f32_16x16x32_bf16 v[98:101], v[130:133], v[190:193], v[98:101]
	v_mfma_f32_16x16x32_bf16 v[94:97], v[146:149], v[190:193], v[94:97]
	v_mfma_f32_16x16x32_bf16 v[90:93], v[130:133], v[198:201], v[90:93]
	v_mfma_f32_16x16x32_bf16 v[86:89], v[146:149], v[198:201], v[86:89]
	v_mfma_f32_16x16x32_bf16 v[82:85], v[130:133], v[206:209], v[82:85]
	v_mfma_f32_16x16x32_bf16 v[78:81], v[146:149], v[206:209], v[78:81]
	v_mfma_f32_16x16x32_bf16 v[74:77], v[130:133], v[214:217], v[74:77]
	v_mfma_f32_16x16x32_bf16 v[70:73], v[146:149], v[214:217], v[70:73]
	v_mfma_f32_16x16x32_bf16 v[34:37], v[150:153], v[186:189], v[34:37]
	v_mfma_f32_16x16x32_bf16 v[30:33], v[158:161], v[186:189], v[30:33]
	v_mfma_f32_16x16x32_bf16 v[26:29], v[150:153], v[194:197], v[26:29]
	v_mfma_f32_16x16x32_bf16 v[22:25], v[158:161], v[194:197], v[22:25]
	v_mfma_f32_16x16x32_bf16 v[18:21], v[150:153], v[202:205], v[18:21]
	v_mfma_f32_16x16x32_bf16 v[14:17], v[158:161], v[202:205], v[14:17]
	v_mfma_f32_16x16x32_bf16 v[10:13], v[150:153], v[210:213], v[10:13]
	v_mfma_f32_16x16x32_bf16 v[4:7], v[158:161], v[210:213], v[6:9]
	v_mfma_f32_16x16x32_bf16 v[34:37], v[154:157], v[190:193], v[34:37]
	v_mfma_f32_16x16x32_bf16 v[30:33], v[162:165], v[190:193], v[30:33]
	v_mfma_f32_16x16x32_bf16 v[26:29], v[154:157], v[198:201], v[26:29]
	v_mfma_f32_16x16x32_bf16 v[22:25], v[162:165], v[198:201], v[22:25]
	v_mfma_f32_16x16x32_bf16 v[18:21], v[154:157], v[206:209], v[18:21]
	v_mfma_f32_16x16x32_bf16 v[14:17], v[162:165], v[206:209], v[14:17]
	v_mfma_f32_16x16x32_bf16 v[10:13], v[154:157], v[214:217], v[10:13]
	v_mfma_f32_16x16x32_bf16 v[4:7], v[162:165], v[214:217], v[4:7]
	s_barrier
	s_add_i32 s68, 0, 0x18000
	v_add_u32_e32 v3, s68, v222
	s_add_i32 s69, 0, 0x1c000
	ds_read_b128 v[126:129], v3
	ds_read_b128 v[130:133], v3 offset:1024
	ds_read_b128 v[142:145], v3 offset:2048
	ds_read_b128 v[146:149], v3 offset:3072
	v_add_u32_e32 v3, s69, v222
	s_add_u32 s30, s30, 0x300000
	s_addc_u32 s31, s31, 0
	s_mov_b32 m0, s39
	s_nop 0
	global_load_lds_dwordx4 v166, s[30:31]
	ds_read_b128 v[150:153], v3
	ds_read_b128 v[154:157], v3 offset:1024
	ds_read_b128 v[158:161], v3 offset:2048
	ds_read_b128 v[162:165], v3 offset:3072
	ds_read_b128 v[186:189], v224 offset:32768
	ds_read_b128 v[190:193], v224 offset:33792
	ds_read_b128 v[194:197], v224 offset:34816
	s_mov_b32 m0, s40
	s_nop 0
	global_load_lds_dwordx4 v170, s[30:31]
	ds_read_b128 v[198:201], v224 offset:35840
	ds_read_b128 v[202:205], v224 offset:36864
	ds_read_b128 v[206:209], v224 offset:37888
	ds_read_b128 v[210:213], v224 offset:38912
	ds_read_b128 v[214:217], v224 offset:39936
	s_waitcnt vmcnt(8) lgkmcnt(0)
	s_barrier
	v_mfma_f32_16x16x32_bf16 v[138:141], v[126:129], v[186:189], v[138:141]
	v_mfma_f32_16x16x32_bf16 v[134:137], v[142:145], v[186:189], v[134:137]
	v_mfma_f32_16x16x32_bf16 v[122:125], v[126:129], v[194:197], v[122:125]
	v_mfma_f32_16x16x32_bf16 v[118:121], v[142:145], v[194:197], v[118:121]
	v_mfma_f32_16x16x32_bf16 v[114:117], v[126:129], v[202:205], v[114:117]
	v_mfma_f32_16x16x32_bf16 v[110:113], v[142:145], v[202:205], v[110:113]
	v_mfma_f32_16x16x32_bf16 v[106:109], v[126:129], v[210:213], v[106:109]
	v_mfma_f32_16x16x32_bf16 v[102:105], v[142:145], v[210:213], v[102:105]
	v_mfma_f32_16x16x32_bf16 v[138:141], v[130:133], v[190:193], v[138:141]
	v_mfma_f32_16x16x32_bf16 v[134:137], v[146:149], v[190:193], v[134:137]
	v_mfma_f32_16x16x32_bf16 v[122:125], v[130:133], v[198:201], v[122:125]
	v_mfma_f32_16x16x32_bf16 v[118:121], v[146:149], v[198:201], v[118:121]
	v_mfma_f32_16x16x32_bf16 v[114:117], v[130:133], v[206:209], v[114:117]
	v_mfma_f32_16x16x32_bf16 v[110:113], v[146:149], v[206:209], v[110:113]
	v_mfma_f32_16x16x32_bf16 v[106:109], v[130:133], v[214:217], v[106:109]
	v_mfma_f32_16x16x32_bf16 v[102:105], v[146:149], v[214:217], v[102:105]
	v_mfma_f32_16x16x32_bf16 v[66:69], v[150:153], v[186:189], v[66:69]
	v_mfma_f32_16x16x32_bf16 v[62:65], v[158:161], v[186:189], v[62:65]
	v_mfma_f32_16x16x32_bf16 v[58:61], v[150:153], v[194:197], v[58:61]
	v_mfma_f32_16x16x32_bf16 v[54:57], v[158:161], v[194:197], v[54:57]
	v_mfma_f32_16x16x32_bf16 v[50:53], v[150:153], v[202:205], v[50:53]
	v_mfma_f32_16x16x32_bf16 v[46:49], v[158:161], v[202:205], v[46:49]
	v_mfma_f32_16x16x32_bf16 v[42:45], v[150:153], v[210:213], v[42:45]
	v_mfma_f32_16x16x32_bf16 v[38:41], v[158:161], v[210:213], v[38:41]
	v_mfma_f32_16x16x32_bf16 v[66:69], v[154:157], v[190:193], v[66:69]
	v_mfma_f32_16x16x32_bf16 v[62:65], v[162:165], v[190:193], v[62:65]
	v_mfma_f32_16x16x32_bf16 v[58:61], v[154:157], v[198:201], v[58:61]
	v_mfma_f32_16x16x32_bf16 v[54:57], v[162:165], v[198:201], v[54:57]
	v_mfma_f32_16x16x32_bf16 v[50:53], v[154:157], v[206:209], v[50:53]
	v_mfma_f32_16x16x32_bf16 v[46:49], v[162:165], v[206:209], v[46:49]
	v_mfma_f32_16x16x32_bf16 v[42:45], v[154:157], v[214:217], v[42:45]
	v_mfma_f32_16x16x32_bf16 v[38:41], v[162:165], v[214:217], v[38:41]
	s_barrier
; #define PG8_MMA(ai, bj, At, Bt) do { __builtin_amdgcn_s_setprio(1); _Pragma("unroll") for (int m = 0; m < 4; ++m) _Pragma("unroll") for (int n = 0; n < 2; ++n) _Pragma("unroll") for (int k = 0; k < 2; ++k) \
;         acc[ai][bj][m][n] = __builtin_amdgcn_mfma_f32_16x16x32_bf16(Bt[n][k], At[m][k], acc[ai][bj][m][n], 0, 0, 0); __builtin_amdgcn_s_setprio(0); } while (0)
; #define PG8_WAIT_V(n) asm volatile("s_waitcnt vmcnt(" #n ")" ::: "memory")
; #define PG8_WAIT_L(n) asm volatile("s_waitcnt lgkmcnt(" #n ")" ::: "memory")
; #define PG8_BAR __builtin_amdgcn_s_barrier()
; #define PG8_SCHED __builtin_amdgcn_sched_barrier(0)
;     __device__ __forceinline__ void after(int te, f32x4 (&acc)[2][2][4][2], const Unit& u, int wr, int wc, int fr, int fq) const {
;         if (te > D_INNER / BK) return;
;         const int g = (te >> 4) - 1;
;         asm volatile("" : "+v"(fr), "+v"(fq));
; #pragma unroll
;         for (int ai = 0; ai < 2; ++ai)
; #pragma unroll
;             for (int m = 0; m < 4; ++m) { const float f = tab[(ai * HALF + wr * 64 + m * 16 + fr) * 8 + g];
; #pragma unroll
;                 for (int bj = 0; bj < 2; ++bj)
; #pragma unroll
;                     for (int n = 0; n < 2; ++n) acc[ai][bj][m][n] *= f; }
; template <class Epi, class Sched, bool ALIGN_EPI, class Hook = NoHook>
; __device__ __forceinline__ void gemm_phase(LAS unsigned char* lds, const Gemm g, const Sched& S, const Epi& E, const Hook& H = Hook()) {
;     ...
;             PG8_WAIT_V(8); PG8_WAIT_L(0); PG8_BAR; PG8_MMA(1, 0, At, B0); PG8_MMA(1, 1, At, B1); PG8_BAR; PG8_SCHED;
;         }
;         if constexpr (Hook::ON) H.after(te, acc, cur, wr, wc, fr, fq);
	s_add_i32 s30, s68, s35
	s_add_u32 s72, s28, s14
	s_addc_u32 s73, s29, s15
	s_mov_b32 m0, s30
	ds_read_b128 v[186:189], v224 offset:49152
	ds_read_b128 v[190:193], v224 offset:50176
	global_load_lds_dwordx4 v168, s[72:73]
	ds_read_b128 v[194:197], v224 offset:51200
	s_add_i32 m0, s30, 0x2000
	s_add_u32 s28, s28, 0x300080
	s_addc_u32 s29, s29, 0
	s_add_i32 s30, s69, s35
	global_load_lds_dwordx4 v172, s[72:73]
	ds_read_b128 v[198:201], v224 offset:52224
	s_mov_b32 m0, s30
	s_nop 0
	global_load_lds_dwordx4 v168, s[28:29]
	ds_read_b128 v[202:205], v224 offset:53248
	s_add_i32 m0, s30, 0x2000
	s_nop 0
	global_load_lds_dwordx4 v172, s[28:29]
	ds_read_b128 v[206:209], v224 offset:54272
	s_mov_b32 m0, s45
	s_nop 0
	global_load_lds_dwordx4 v166, s[74:75]
	ds_read_b128 v[210:213], v224 offset:55296
	s_mov_b32 m0, s46
	s_nop 0
	global_load_lds_dwordx4 v170, s[74:75]
	s_add_u32 s26, s26, 0x100
	s_addc_u32 s27, s27, 0
	s_cmp_ge_u32 s67, s66
	ds_read_b128 v[214:217], v224 offset:56320
	s_waitcnt vmcnt(8) lgkmcnt(0)
	s_barrier
	v_mfma_f32_16x16x32_bf16 v[98:101], v[126:129], v[186:189], v[98:101]
	v_mfma_f32_16x16x32_bf16 v[94:97], v[142:145], v[186:189], v[94:97]
	v_mfma_f32_16x16x32_bf16 v[90:93], v[126:129], v[194:197], v[90:93]
	v_mfma_f32_16x16x32_bf16 v[86:89], v[142:145], v[194:197], v[86:89]
	v_mfma_f32_16x16x32_bf16 v[82:85], v[126:129], v[202:205], v[82:85]
	v_mfma_f32_16x16x32_bf16 v[78:81], v[142:145], v[202:205], v[78:81]
	v_mfma_f32_16x16x32_bf16 v[74:77], v[126:129], v[210:213], v[74:77]
	v_mfma_f32_16x16x32_bf16 v[70:73], v[142:145], v[210:213], v[70:73]
	v_mfma_f32_16x16x32_bf16 v[98:101], v[130:133], v[190:193], v[98:101]
	v_mfma_f32_16x16x32_bf16 v[94:97], v[146:149], v[190:193], v[94:97]
	v_mfma_f32_16x16x32_bf16 v[90:93], v[130:133], v[198:201], v[90:93]
	v_mfma_f32_16x16x32_bf16 v[86:89], v[146:149], v[198:201], v[86:89]
	v_mfma_f32_16x16x32_bf16 v[82:85], v[130:133], v[206:209], v[82:85]
	v_mfma_f32_16x16x32_bf16 v[78:81], v[146:149], v[206:209], v[78:81]
	v_mfma_f32_16x16x32_bf16 v[74:77], v[130:133], v[214:217], v[74:77]
	v_mfma_f32_16x16x32_bf16 v[70:73], v[146:149], v[214:217], v[70:73]
	v_mfma_f32_16x16x32_bf16 v[34:37], v[150:153], v[186:189], v[34:37]
	v_mfma_f32_16x16x32_bf16 v[30:33], v[158:161], v[186:189], v[30:33]
	v_mfma_f32_16x16x32_bf16 v[26:29], v[150:153], v[194:197], v[26:29]
	v_mfma_f32_16x16x32_bf16 v[22:25], v[158:161], v[194:197], v[22:25]
	v_mfma_f32_16x16x32_bf16 v[18:21], v[150:153], v[202:205], v[18:21]
	v_mfma_f32_16x16x32_bf16 v[14:17], v[158:161], v[202:205], v[14:17]
	v_mfma_f32_16x16x32_bf16 v[8:11], v[150:153], v[210:213], v[10:13]
	v_mfma_f32_16x16x32_bf16 v[4:7], v[158:161], v[210:213], v[4:7]
	v_mfma_f32_16x16x32_bf16 v[34:37], v[154:157], v[190:193], v[34:37]
	v_mfma_f32_16x16x32_bf16 v[30:33], v[162:165], v[190:193], v[30:33]
	v_mfma_f32_16x16x32_bf16 v[26:29], v[154:157], v[198:201], v[26:29]
	v_mfma_f32_16x16x32_bf16 v[22:25], v[162:165], v[198:201], v[22:25]
	v_mfma_f32_16x16x32_bf16 v[18:21], v[154:157], v[206:209], v[18:21]
	v_mfma_f32_16x16x32_bf16 v[14:17], v[162:165], v[206:209], v[14:17]
	v_mfma_f32_16x16x32_bf16 v[10:13], v[154:157], v[214:217], v[8:11]
	v_mfma_f32_16x16x32_bf16 v[6:9], v[162:165], v[214:217], v[4:7]
	s_barrier
	s_cbranch_scc0 .LBB0_783
	s_cmpk_gt_u32 s65, 0x7f
	s_cbranch_scc1 .LBB0_787
	s_lshr_b32 s26, s66, 4
	s_add_i32 s26, s26, -1
	v_mov_b32_e32 v3, v1
	v_mov_b32_e32 v4, v220
	s_lshl_b32 s27, s26, 2
	s_add_i32 s28, s27, s48
	v_lshlrev_b32_e32 v5, 5, v3
	v_add_u32_e32 v126, s28, v5
	ds_read_b32 v126, v126
	s_add_i32 s28, s27, s49
	s_waitcnt lgkmcnt(0)
	v_pk_mul_f32 v[140:141], v[140:141], v[126:127] op_sel_hi:[1,0]
	v_pk_mul_f32 v[138:139], v[138:139], v[126:127] op_sel_hi:[1,0]
	v_pk_mul_f32 v[136:137], v[136:137], v[126:127] op_sel_hi:[1,0]
	v_pk_mul_f32 v[134:135], v[134:135], v[126:127] op_sel_hi:[1,0]
	v_pk_mul_f32 v[68:69], v[68:69], v[126:127] op_sel_hi:[1,0]
	v_pk_mul_f32 v[66:67], v[66:67], v[126:127] op_sel_hi:[1,0]
	v_pk_mul_f32 v[64:65], v[64:65], v[126:127] op_sel_hi:[1,0]
	v_pk_mul_f32 v[62:63], v[62:63], v[126:127] op_sel_hi:[1,0]
	v_add_u32_e32 v126, s28, v5
	ds_read_b32 v126, v126
	s_add_i32 s28, s27, s50
	s_waitcnt lgkmcnt(0)
	v_pk_mul_f32 v[124:125], v[124:125], v[126:127] op_sel_hi:[1,0]
	v_pk_mul_f32 v[122:123], v[122:123], v[126:127] op_sel_hi:[1,0]
	v_pk_mul_f32 v[120:121], v[120:121], v[126:127] op_sel_hi:[1,0]
	v_pk_mul_f32 v[118:119], v[118:119], v[126:127] op_sel_hi:[1,0]
	v_pk_mul_f32 v[60:61], v[60:61], v[126:127] op_sel_hi:[1,0]
	v_pk_mul_f32 v[58:59], v[58:59], v[126:127] op_sel_hi:[1,0]
	v_pk_mul_f32 v[56:57], v[56:57], v[126:127] op_sel_hi:[1,0]
	v_pk_mul_f32 v[54:55], v[54:55], v[126:127] op_sel_hi:[1,0]
	v_add_u32_e32 v126, s28, v5
	ds_read_b32 v126, v126
	s_add_i32 s28, s27, s51
	s_waitcnt lgkmcnt(0)
	v_pk_mul_f32 v[116:117], v[116:117], v[126:127] op_sel_hi:[1,0]
	v_pk_mul_f32 v[114:115], v[114:115], v[126:127] op_sel_hi:[1,0]
	v_pk_mul_f32 v[112:113], v[112:113], v[126:127] op_sel_hi:[1,0]
	v_pk_mul_f32 v[110:111], v[110:111], v[126:127] op_sel_hi:[1,0]
	v_pk_mul_f32 v[52:53], v[52:53], v[126:127] op_sel_hi:[1,0]
	v_pk_mul_f32 v[50:51], v[50:51], v[126:127] op_sel_hi:[1,0]
	v_pk_mul_f32 v[48:49], v[48:49], v[126:127] op_sel_hi:[1,0]
	v_pk_mul_f32 v[46:47], v[46:47], v[126:127] op_sel_hi:[1,0]
	v_add_u32_e32 v126, s28, v5
	ds_read_b32 v126, v126
	s_add_i32 s28, s27, s52
	s_waitcnt lgkmcnt(0)
;     __device__ __forceinline__ void after(int te, f32x4 (&acc)[2][2][4][2], const Unit& u, int wr, int wc, int fr, int fq) const {
;     ...
; #pragma unroll
;         for (int ai = 0; ai < 2; ++ai)
; #pragma unroll
;             for (int m = 0; m < 4; ++m) { const float f = tab[(ai * HALF + wr * 64 + m * 16 + fr) * 8 + g];
; #pragma unroll
;                 for (int bj = 0; bj < 2; ++bj)
; #pragma unroll
;                     for (int n = 0; n < 2; ++n) acc[ai][bj][m][n] *= f; }
;         if (g == 7) {
;             const int row0 = u.pm * BM + wr * 64 + fr, col0 = u.pn * BM + wc * 32 + 8 * fq;
; #pragma unroll
;             for (int bj = 0; bj < 2; ++bj) { const int c = col0 + bj * HALF;
;                 const f32x4 s0 = *(const f32x4*)(gb + c), s1 = *(const f32x4*)(gb + c + 4), a0 = *(const f32x4*)(gb + D_MODEL + c), a1 = *(const f32x4*)(gb + D_MODEL + c + 4);
; #pragma unroll
;                 for (int ai = 0; ai < 2; ++ai) {
;                     u32x4 gs[4], ga[4];
; #pragma unroll
;                     for (int m = 0; m < 4; ++m) { const size_t r = (size_t)(row0 + ai * HALF + m * 16); gs[m] = *(const u32x4*)(proj + r * LDP + PGS + c); ga[m] = *(const u32x4*)(proj + r * LDP + PGA + c); }
	v_pk_mul_f32 v[108:109], v[108:109], v[126:127] op_sel_hi:[1,0]
	v_pk_mul_f32 v[106:107], v[106:107], v[126:127] op_sel_hi:[1,0]
	v_pk_mul_f32 v[104:105], v[104:105], v[126:127] op_sel_hi:[1,0]
	v_pk_mul_f32 v[102:103], v[102:103], v[126:127] op_sel_hi:[1,0]
	v_pk_mul_f32 v[44:45], v[44:45], v[126:127] op_sel_hi:[1,0]
	v_pk_mul_f32 v[42:43], v[42:43], v[126:127] op_sel_hi:[1,0]
	v_pk_mul_f32 v[40:41], v[40:41], v[126:127] op_sel_hi:[1,0]
	v_pk_mul_f32 v[38:39], v[38:39], v[126:127] op_sel_hi:[1,0]
	v_add_u32_e32 v126, s28, v5
	ds_read_b32 v126, v126
	s_add_i32 s28, s27, s53
	s_waitcnt lgkmcnt(0)
	v_pk_mul_f32 v[100:101], v[100:101], v[126:127] op_sel_hi:[1,0]
	v_pk_mul_f32 v[98:99], v[98:99], v[126:127] op_sel_hi:[1,0]
	v_pk_mul_f32 v[96:97], v[96:97], v[126:127] op_sel_hi:[1,0]
	v_pk_mul_f32 v[94:95], v[94:95], v[126:127] op_sel_hi:[1,0]
	v_pk_mul_f32 v[36:37], v[36:37], v[126:127] op_sel_hi:[1,0]
	v_pk_mul_f32 v[34:35], v[34:35], v[126:127] op_sel_hi:[1,0]
	v_pk_mul_f32 v[32:33], v[32:33], v[126:127] op_sel_hi:[1,0]
	v_pk_mul_f32 v[30:31], v[30:31], v[126:127] op_sel_hi:[1,0]
	v_add_u32_e32 v126, s28, v5
	ds_read_b32 v126, v126
	s_add_i32 s28, s27, s54
	s_add_i32 s27, s27, s55
	s_cmp_lg_u32 s26, 7
	s_waitcnt lgkmcnt(0)
	v_pk_mul_f32 v[92:93], v[92:93], v[126:127] op_sel_hi:[1,0]
	v_pk_mul_f32 v[90:91], v[90:91], v[126:127] op_sel_hi:[1,0]
	v_pk_mul_f32 v[88:89], v[88:89], v[126:127] op_sel_hi:[1,0]
	v_pk_mul_f32 v[86:87], v[86:87], v[126:127] op_sel_hi:[1,0]
	v_pk_mul_f32 v[28:29], v[28:29], v[126:127] op_sel_hi:[1,0]
	v_pk_mul_f32 v[26:27], v[26:27], v[126:127] op_sel_hi:[1,0]
	v_pk_mul_f32 v[24:25], v[24:25], v[126:127] op_sel_hi:[1,0]
	v_pk_mul_f32 v[22:23], v[22:23], v[126:127] op_sel_hi:[1,0]
	v_add_u32_e32 v126, s28, v5
	ds_read_b32 v126, v126
	v_add_u32_e32 v5, s27, v5
	s_waitcnt lgkmcnt(0)
	v_pk_mul_f32 v[84:85], v[84:85], v[126:127] op_sel_hi:[1,0]
	v_pk_mul_f32 v[82:83], v[82:83], v[126:127] op_sel_hi:[1,0]
	v_pk_mul_f32 v[80:81], v[80:81], v[126:127] op_sel_hi:[1,0]
	v_pk_mul_f32 v[78:79], v[78:79], v[126:127] op_sel_hi:[1,0]
	v_pk_mul_f32 v[20:21], v[20:21], v[126:127] op_sel_hi:[1,0]
	v_pk_mul_f32 v[18:19], v[18:19], v[126:127] op_sel_hi:[1,0]
	v_pk_mul_f32 v[16:17], v[16:17], v[126:127] op_sel_hi:[1,0]
	v_pk_mul_f32 v[14:15], v[14:15], v[126:127] op_sel_hi:[1,0]
	ds_read_b32 v126, v5
	s_waitcnt lgkmcnt(0)
	v_pk_mul_f32 v[76:77], v[76:77], v[126:127] op_sel_hi:[1,0]
	v_pk_mul_f32 v[74:75], v[74:75], v[126:127] op_sel_hi:[1,0]
	v_pk_mul_f32 v[72:73], v[72:73], v[126:127] op_sel_hi:[1,0]
	v_pk_mul_f32 v[70:71], v[70:71], v[126:127] op_sel_hi:[1,0]
	v_pk_mul_f32 v[12:13], v[12:13], v[126:127] op_sel_hi:[1,0]
	v_pk_mul_f32 v[10:11], v[10:11], v[126:127] op_sel_hi:[1,0]
	v_pk_mul_f32 v[8:9], v[8:9], v[126:127] op_sel_hi:[1,0]
	v_pk_mul_f32 v[6:7], v[6:7], v[126:127] op_sel_hi:[1,0]
	s_cbranch_scc1 .LBB0_787
	v_add_u32_e32 v126, s62, v3
	v_ashrrev_i32_e32 v127, 31, v126
	v_lshl_add_u32 v4, v4, 3, s61
	v_lshlrev_b64 v[126:127], 14, v[126:127]
	v_ashrrev_i32_e32 v5, 31, v4
	v_lshl_add_u64 v[126:127], s[76:77], 0, v[126:127]
	v_lshl_add_u64 v[192:193], v[4:5], 1, v[126:127]
	v_readlane_b32 s68, v254, 20
	global_load_dwordx4 v[204:207], v[192:193], off
	v_add_co_u32_e32 v126, vcc, s41, v192
	v_lshlrev_b64 v[4:5], 2, v[4:5]
	v_readlane_b32 s70, v254, 22
	v_readlane_b32 s71, v254, 23
	v_addc_co_u32_e32 v127, vcc, 0, v193, vcc
	s_nop 0
	v_lshl_add_u64 v[196:197], s[70:71], 0, v[4:5]
	global_load_dwordx4 v[208:211], v[126:127], off
	global_load_dwordx4 v[142:145], v[196:197], off
	s_nop 0
	global_load_dwordx4 v[126:129], v[196:197], off offset:16
	v_lshl_add_u64 v[198:199], s[12:13], 0, v[4:5]
	global_load_dwordx4 v[146:149], v[198:199], off
	global_load_dwordx4 v[130:133], v[198:199], off offset:16
	s_mov_b64 s[26:27], 0x40000
	v_lshl_add_u64 v[4:5], v[192:193], 0, s[26:27]
	s_mov_b32 s26, 0x40000
	v_add_co_u32_e32 v150, vcc, s26, v192
	s_mov_b64 s[26:27], 0x42000
	s_nop 0
	v_addc_co_u32_e32 v151, vcc, 0, v193, vcc
	v_lshl_add_u64 v[186:187], v[192:193], 0, s[26:27]
	s_mov_b32 s26, 0x42000
	v_add_co_u32_e32 v152, vcc, s26, v192
	s_mov_b64 s[26:27], 0x80000
	s_nop 0
	v_addc_co_u32_e32 v153, vcc, 0, v193, vcc
	v_lshl_add_u64 v[188:189], v[192:193], 0, s[26:27]
	s_mov_b32 s26, 0x80000
	v_add_co_u32_e32 v154, vcc, s26, v192
	s_mov_b64 s[26:27], 0x82000
	s_nop 0
	v_addc_co_u32_e32 v155, vcc, 0, v193, vcc
	v_lshl_add_u64 v[190:191], v[192:193], 0, s[26:27]
	s_mov_b32 s26, 0x82000
	v_add_co_u32_e32 v156, vcc, s26, v192
	s_mov_b64 s[26:27], 0xc0000
	s_nop 0
	v_addc_co_u32_e32 v157, vcc, 0, v193, vcc
	v_lshl_add_u64 v[194:195], v[192:193], 0, s[26:27]
	s_mov_b32 s26, 0xc0000
	v_add_co_u32_e32 v228, vcc, s26, v192
	s_mov_b64 s[26:27], 0xc2000
	s_nop 0
	v_addc_co_u32_e32 v229, vcc, 0, v193, vcc
	v_lshl_add_u64 v[200:201], v[192:193], 0, s[26:27]
	s_mov_b32 s26, 0xc2000
	v_add_co_u32_e32 v230, vcc, s26, v192
	s_mov_b32 s26, 0x200000
	s_nop 0
	v_addc_co_u32_e32 v231, vcc, 0, v193, vcc
	global_load_dwordx4 v[212:215], v[150:151], off
	global_load_dwordx4 v[216:219], v[152:153], off
	global_load_dwordx4 v[162:165], v[154:155], off
	global_load_dwordx4 v[158:161], v[156:157], off
	s_nop 0
	global_load_dwordx4 v[154:157], v[228:229], off
	global_load_dwordx4 v[150:153], v[230:231], off
	v_lshl_add_u64 v[202:203], v[192:193], 0, s[18:19]
	v_readlane_b32 s76, v254, 28
	v_readlane_b32 s77, v254, 29
	v_readlane_b32 s76, v255, 8
	v_readlane_b32 s77, v255, 9
	v_readlane_b32 s69, v254, 21
	v_readlane_b32 s72, v254, 24
	v_readlane_b32 s73, v254, 25
	v_readlane_b32 s74, v254, 26
	v_readlane_b32 s75, v254, 27
	v_readlane_b32 s78, v254, 30
	v_readlane_b32 s79, v254, 31
	v_readlane_b32 s80, v254, 32
	v_readlane_b32 s81, v254, 33
	v_readlane_b32 s82, v254, 34
	v_readlane_b32 s83, v254, 35
	s_waitcnt vmcnt(0)
; __device__ __forceinline__ void unpack8(const u32x4 w, float (&v)[8]) { v[0] = bf_lo(w.x); v[1] = bf_hi(w.x); v[2] = bf_lo(w.y); v[3] = bf_hi(w.y); v[4] = bf_lo(w.z); v[5] = bf_hi(w.z); v[6] = bf_lo(w.w); v[7] = bf_hi(w.w); }
;     __device__ __forceinline__ void after(int te, f32x4 (&acc)[2][2][4][2], const Unit& u, int wr, int wc, int fr, int fq) const {
;     ...
;                     for (int m = 0; m < 4; ++m) { float vs[8], va[8]; unpack8(gs[m], vs); unpack8(ga[m], va);
; #pragma unroll
;                         for (int e = 0; e < 4; ++e) {
;                             acc[ai][bj][m][0][e] *= (1.f + __expf(-(va[e] + a0[e]))) * __builtin_amdgcn_rcpf(1.f + __expf(-(vs[e] + s0[e])));
;                             acc[ai][bj][m][1][e] *= (1.f + __expf(-(va[4 + e] + a1[e]))) * __builtin_amdgcn_rcpf(1.f + __expf(-(vs[4 + e] + s1[e]))); } }
	v_lshlrev_b32_e32 v3, 16, v204
	v_and_b32_e32 v204, 0xffff0000, v204
	v_lshlrev_b32_e32 v225, 16, v205
	v_and_b32_e32 v227, 0xffff0000, v205
	v_lshlrev_b32_e32 v205, 16, v206
	v_and_b32_e32 v228, 0xffff0000, v206
	v_lshlrev_b32_e32 v229, 16, v207
	v_and_b32_e32 v233, 0xffff0000, v207
	v_add_f32_e32 v3, v142, v3
	v_add_f32_e32 v204, v143, v204
	v_mul_f32_e32 v3, 0xbfb8aa3b, v3
	v_mul_f32_e32 v204, 0xbfb8aa3b, v204
	v_exp_f32_e32 v3, v3
	v_lshlrev_b32_e32 v230, 16, v209
	v_and_b32_e32 v231, 0xffff0000, v209
	v_exp_f32_e32 v209, v204
	v_lshlrev_b32_e32 v206, 16, v208
	v_and_b32_e32 v207, 0xffff0000, v208
	v_lshlrev_b32_e32 v208, 16, v210
	v_add_f32_e32 v206, v146, v206
	v_add_f32_e32 v208, v130, v208
	v_mul_f32_e32 v206, 0xbfb8aa3b, v206
	v_mul_f32_e32 v208, 0xbfb8aa3b, v208
	v_add_f32_e32 v3, 1.0, v3
	v_exp_f32_e32 v204, v206
	v_exp_f32_e32 v206, v208
	v_rcp_f32_e32 v208, v3
	v_add_f32_e32 v3, 1.0, v209
	v_rcp_f32_e32 v209, v3
	v_add_f32_e32 v3, v127, v228
	v_mul_f32_e32 v3, 0xbfb8aa3b, v3
	v_exp_f32_e32 v3, v3
	v_lshlrev_b32_e32 v234, 16, v211
	v_and_b32_e32 v235, 0xffff0000, v211
	v_add_f32_e32 v205, v126, v205
	v_add_f32_e32 v3, 1.0, v3
	v_rcp_f32_e32 v211, v3
	v_add_f32_e32 v3, v144, v225
	v_mul_f32_e32 v3, 0xbfb8aa3b, v3
	v_exp_f32_e32 v3, v3
	v_mul_f32_e32 v205, 0xbfb8aa3b, v205
	v_exp_f32_e32 v205, v205
	v_add_f32_e32 v225, v148, v230
	v_add_f32_e32 v3, 1.0, v3
	v_rcp_f32_e32 v230, v3
	v_add_f32_e32 v3, v128, v229
	v_mul_f32_e32 v3, 0xbfb8aa3b, v3
	v_add_f32_e32 v227, v145, v227
	v_mul_f32_e32 v225, 0xbfb8aa3b, v225
	v_exp_f32_e32 v3, v3
	v_mul_f32_e32 v227, 0xbfb8aa3b, v227
	v_add_f32_e32 v207, v147, v207
	v_exp_f32_e32 v228, v225
	v_add_f32_e32 v225, v132, v234
	v_exp_f32_e32 v227, v227
	v_and_b32_e32 v232, 0xffff0000, v210
	v_mul_f32_e32 v207, 0xbfb8aa3b, v207
	v_add_f32_e32 v205, 1.0, v205
	v_mul_f32_e32 v225, 0xbfb8aa3b, v225
	v_rcp_f32_e32 v210, v205
	v_exp_f32_e32 v205, v207
	v_add_f32_e32 v207, v131, v232
	v_exp_f32_e32 v232, v225
	v_add_f32_e32 v225, v149, v231
	v_add_f32_e32 v3, 1.0, v3
	v_mul_f32_e32 v225, 0xbfb8aa3b, v225
	v_exp_f32_e32 v229, v225
	v_rcp_f32_e32 v234, v3
	v_add_f32_e32 v3, 1.0, v227
	v_rcp_f32_e32 v231, v3
	v_pk_add_f32 v[228:229], v[228:229], 1.0 op_sel_hi:[1,0]
	v_pk_add_f32 v[204:205], v[204:205], 1.0 op_sel_hi:[1,0]
	v_add_f32_e32 v3, v133, v235
	v_pk_mul_f32 v[204:205], v[204:205], v[208:209]
	v_pk_mul_f32 v[208:209], v[228:229], v[230:231]
	v_mul_f32_e32 v3, 0xbfb8aa3b, v3
	v_pk_mul_f32 v[140:141], v[140:141], v[208:209]
	v_add_f32_e32 v208, v129, v233
	v_mul_f32_e32 v208, 0xbfb8aa3b, v208
	v_exp_f32_e32 v208, v208
	v_exp_f32_e32 v233, v3
	v_mul_f32_e32 v207, 0xbfb8aa3b, v207
	v_exp_f32_e32 v207, v207
	v_add_f32_e32 v3, 1.0, v208
	v_rcp_f32_e32 v235, v3
	v_lshlrev_b32_e32 v3, 16, v212
	v_add_f32_e32 v3, v142, v3
	v_mul_f32_e32 v3, 0xbfb8aa3b, v3
	v_exp_f32_e32 v3, v3
	v_pk_add_f32 v[206:207], v[206:207], 1.0 op_sel_hi:[1,0]
	v_pk_mul_f32 v[138:139], v[138:139], v[204:205]
	v_pk_mul_f32 v[206:207], v[206:207], v[210:211]
	v_add_f32_e32 v3, 1.0, v3
	v_pk_mul_f32 v[134:135], v[134:135], v[206:207]
	v_lshlrev_b32_e32 v207, 16, v214
	v_rcp_f32_e32 v206, v3
	v_add_f32_e32 v3, v126, v207
	v_mul_f32_e32 v3, 0xbfb8aa3b, v3
	v_exp_f32_e32 v3, v3
	v_pk_add_f32 v[204:205], v[232:233], 1.0 op_sel_hi:[1,0]
	v_lshlrev_b32_e32 v208, 16, v218
	v_pk_mul_f32 v[204:205], v[204:205], v[234:235]
	v_add_f32_e32 v3, 1.0, v3
	v_pk_mul_f32 v[136:137], v[136:137], v[204:205]
	v_and_b32_e32 v205, 0xffff0000, v212
	v_rcp_f32_e32 v210, v3
	v_add_f32_e32 v3, v143, v205
	v_mul_f32_e32 v3, 0xbfb8aa3b, v3
	v_exp_f32_e32 v3, v3
	v_add_f32_e32 v207, v130, v208
	v_and_b32_e32 v209, 0xffff0000, v214
	v_mul_f32_e32 v207, 0xbfb8aa3b, v207
	v_add_f32_e32 v3, 1.0, v3
	v_exp_f32_e32 v208, v207
	v_rcp_f32_e32 v207, v3
	v_add_f32_e32 v3, v127, v209
	v_mul_f32_e32 v3, 0xbfb8aa3b, v3
	v_exp_f32_e32 v3, v3
	v_lshlrev_b32_e32 v212, 16, v213
	v_and_b32_e32 v211, 0xffff0000, v216
	v_add_f32_e32 v205, v147, v211
	v_add_f32_e32 v3, 1.0, v3
	v_rcp_f32_e32 v211, v3
	v_add_f32_e32 v3, v144, v212
	v_mul_f32_e32 v3, 0xbfb8aa3b, v3
	v_exp_f32_e32 v3, v3
	v_lshlrev_b32_e32 v225, 16, v215
	v_lshlrev_b32_e32 v214, 16, v217
	v_and_b32_e32 v213, 0xffff0000, v213
	v_add_f32_e32 v3, 1.0, v3
	v_add_f32_e32 v212, v148, v214
	v_rcp_f32_e32 v214, v3
	v_add_f32_e32 v3, v128, v225
	v_mul_f32_e32 v3, 0xbfb8aa3b, v3
	v_add_f32_e32 v213, v145, v213
	v_and_b32_e32 v227, 0xffff0000, v215
	v_lshlrev_b32_e32 v204, 16, v216
	v_and_b32_e32 v215, 0xffff0000, v217
	v_and_b32_e32 v216, 0xffff0000, v218
	v_lshlrev_b32_e32 v217, 16, v219
	v_exp_f32_e32 v3, v3
	v_mul_f32_e32 v213, 0xbfb8aa3b, v213
	v_add_f32_e32 v209, v131, v216
	v_add_f32_e32 v216, v132, v217
	v_exp_f32_e32 v217, v213
	v_add_f32_e32 v204, v146, v204
	v_add_f32_e32 v215, v149, v215
	v_mul_f32_e32 v204, 0xbfb8aa3b, v204
	v_mul_f32_e32 v205, 0xbfb8aa3b, v205
	v_mul_f32_e32 v212, 0xbfb8aa3b, v212
	v_add_f32_e32 v3, 1.0, v3
	v_mul_f32_e32 v213, 0xbfb8aa3b, v215
	v_exp_f32_e32 v204, v204
	v_exp_f32_e32 v205, v205
	v_exp_f32_e32 v212, v212
	v_exp_f32_e32 v213, v213
	v_rcp_f32_e32 v218, v3
	v_add_f32_e32 v3, 1.0, v217
	v_rcp_f32_e32 v215, v3
	v_pk_add_f32 v[212:213], v[212:213], 1.0 op_sel_hi:[1,0]
	v_pk_add_f32 v[204:205], v[204:205], 1.0 op_sel_hi:[1,0]
	v_and_b32_e32 v219, 0xffff0000, v219
	v_pk_mul_f32 v[204:205], v[204:205], v[206:207]
	v_pk_mul_f32 v[206:207], v[212:213], v[214:215]
	v_add_f32_e32 v3, v133, v219
	v_pk_mul_f32 v[124:125], v[124:125], v[206:207]
	v_add_f32_e32 v206, v129, v227
	v_mul_f32_e32 v206, 0xbfb8aa3b, v206
	v_exp_f32_e32 v206, v206
	v_mul_f32_e32 v3, 0xbfb8aa3b, v3
	v_exp_f32_e32 v217, v3
; __device__ __forceinline__ void unpack8(const u32x4 w, float (&v)[8]) { v[0] = bf_lo(w.x); v[1] = bf_hi(w.x); v[2] = bf_lo(w.y); v[3] = bf_hi(w.y); v[4] = bf_lo(w.z); v[5] = bf_hi(w.z); v[6] = bf_lo(w.w); v[7] = bf_hi(w.w); }
;     __device__ __forceinline__ void after(int te, f32x4 (&acc)[2][2][4][2], const Unit& u, int wr, int wc, int fr, int fq) const {
;     ...
;                     for (int m = 0; m < 4; ++m) { float vs[8], va[8]; unpack8(gs[m], vs); unpack8(ga[m], va);
; #pragma unroll
;                         for (int e = 0; e < 4; ++e) {
;                             acc[ai][bj][m][0][e] *= (1.f + __expf(-(va[e] + a0[e]))) * __builtin_amdgcn_rcpf(1.f + __expf(-(vs[e] + s0[e])));
;                             acc[ai][bj][m][1][e] *= (1.f + __expf(-(va[4 + e] + a1[e]))) * __builtin_amdgcn_rcpf(1.f + __expf(-(vs[4 + e] + s1[e]))); } }
	v_mul_f32_e32 v216, 0xbfb8aa3b, v216
	v_add_f32_e32 v3, 1.0, v206
	v_rcp_f32_e32 v219, v3
	v_lshlrev_b32_e32 v3, 16, v162
	v_mul_f32_e32 v209, 0xbfb8aa3b, v209
	v_exp_f32_e32 v216, v216
	v_add_f32_e32 v3, v142, v3
	v_exp_f32_e32 v209, v209
	v_mul_f32_e32 v3, 0xbfb8aa3b, v3
	v_exp_f32_e32 v3, v3
	v_pk_mul_f32 v[122:123], v[122:123], v[204:205]
	v_pk_add_f32 v[204:205], v[216:217], 1.0 op_sel_hi:[1,0]
	v_pk_add_f32 v[206:207], v[208:209], 1.0 op_sel_hi:[1,0]
	v_pk_mul_f32 v[204:205], v[204:205], v[218:219]
	v_pk_mul_f32 v[206:207], v[206:207], v[210:211]
	v_pk_mul_f32 v[120:121], v[120:121], v[204:205]
	v_and_b32_e32 v204, 0xffff0000, v162
	v_lshlrev_b32_e32 v162, 16, v164
	v_add_f32_e32 v3, 1.0, v3
	v_pk_mul_f32 v[118:119], v[118:119], v[206:207]
	v_lshlrev_b32_e32 v206, 16, v159
	v_and_b32_e32 v210, 0xffff0000, v159
	v_lshlrev_b32_e32 v159, 16, v160
	v_and_b32_e32 v211, 0xffff0000, v160
	v_rcp_f32_e32 v160, v3
	v_add_f32_e32 v3, v126, v162
	v_mul_f32_e32 v3, 0xbfb8aa3b, v3
	v_exp_f32_e32 v3, v3
	v_lshlrev_b32_e32 v205, 16, v163
	v_and_b32_e32 v207, 0xffff0000, v163
	v_and_b32_e32 v163, 0xffff0000, v164
	v_lshlrev_b32_e32 v164, 16, v158
	v_add_f32_e32 v3, 1.0, v3
	v_lshlrev_b32_e32 v208, 16, v165
	v_and_b32_e32 v209, 0xffff0000, v165
	v_and_b32_e32 v165, 0xffff0000, v158
	v_add_f32_e32 v158, v146, v164
	v_rcp_f32_e32 v164, v3
	v_add_f32_e32 v3, v143, v204
	v_mul_f32_e32 v3, 0xbfb8aa3b, v3
	v_exp_f32_e32 v3, v3
	v_lshlrev_b32_e32 v212, 16, v161
	v_and_b32_e32 v213, 0xffff0000, v161
	v_add_f32_e32 v159, v130, v159
	v_add_f32_e32 v3, 1.0, v3
	v_rcp_f32_e32 v161, v3
	v_add_f32_e32 v3, v127, v163
	v_mul_f32_e32 v3, 0xbfb8aa3b, v3
	v_exp_f32_e32 v3, v3
	v_mul_f32_e32 v159, 0xbfb8aa3b, v159
	v_exp_f32_e32 v162, v159
	v_add_f32_e32 v159, v147, v165
	v_add_f32_e32 v3, 1.0, v3
	v_rcp_f32_e32 v165, v3
	v_add_f32_e32 v3, v144, v205
	v_mul_f32_e32 v3, 0xbfb8aa3b, v3
	v_exp_f32_e32 v3, v3
	v_add_f32_e32 v204, v148, v206
	v_add_f32_e32 v207, v145, v207
	v_mul_f32_e32 v207, 0xbfb8aa3b, v207
	v_add_f32_e32 v3, 1.0, v3
	v_rcp_f32_e32 v206, v3
	v_add_f32_e32 v3, v128, v208
	v_mul_f32_e32 v3, 0xbfb8aa3b, v3
	v_exp_f32_e32 v3, v3
	v_add_f32_e32 v205, v132, v212
	v_exp_f32_e32 v207, v207
	v_mul_f32_e32 v205, 0xbfb8aa3b, v205
	v_exp_f32_e32 v208, v205
	v_add_f32_e32 v205, v149, v210
	v_mul_f32_e32 v158, 0xbfb8aa3b, v158
	v_mul_f32_e32 v159, 0xbfb8aa3b, v159
	v_mul_f32_e32 v204, 0xbfb8aa3b, v204
	v_add_f32_e32 v3, 1.0, v3
	v_mul_f32_e32 v205, 0xbfb8aa3b, v205
	v_exp_f32_e32 v158, v158
	v_exp_f32_e32 v159, v159
	v_exp_f32_e32 v204, v204
	v_exp_f32_e32 v205, v205
	v_rcp_f32_e32 v210, v3
	v_add_f32_e32 v3, 1.0, v207
	v_rcp_f32_e32 v207, v3
	v_pk_add_f32 v[204:205], v[204:205], 1.0 op_sel_hi:[1,0]
	v_pk_add_f32 v[158:159], v[158:159], 1.0 op_sel_hi:[1,0]
	v_add_f32_e32 v3, v133, v213
	v_pk_mul_f32 v[158:159], v[158:159], v[160:161]
	v_pk_mul_f32 v[160:161], v[204:205], v[206:207]
	v_mul_f32_e32 v3, 0xbfb8aa3b, v3
	v_pk_mul_f32 v[116:117], v[116:117], v[160:161]
	v_add_f32_e32 v160, v129, v209
	v_mul_f32_e32 v160, 0xbfb8aa3b, v160
	v_exp_f32_e32 v160, v160
	v_exp_f32_e32 v209, v3
	v_add_f32_e32 v163, v131, v211
	v_mul_f32_e32 v163, 0xbfb8aa3b, v163
	v_add_f32_e32 v3, 1.0, v160
	v_rcp_f32_e32 v211, v3
	v_lshlrev_b32_e32 v3, 16, v154
	v_add_f32_e32 v3, v142, v3
	v_exp_f32_e32 v163, v163
	v_mul_f32_e32 v3, 0xbfb8aa3b, v3
	v_exp_f32_e32 v3, v3
	v_pk_mul_f32 v[114:115], v[114:115], v[158:159]
	v_pk_add_f32 v[158:159], v[208:209], 1.0 op_sel_hi:[1,0]
	v_pk_add_f32 v[160:161], v[162:163], 1.0 op_sel_hi:[1,0]
	v_pk_mul_f32 v[158:159], v[158:159], v[210:211]
	v_pk_mul_f32 v[160:161], v[160:161], v[164:165]
	v_pk_mul_f32 v[112:113], v[112:113], v[158:159]
	v_and_b32_e32 v158, 0xffff0000, v154
	v_lshlrev_b32_e32 v154, 16, v156
	v_add_f32_e32 v3, 1.0, v3
	v_pk_mul_f32 v[110:111], v[110:111], v[160:161]
	v_lshlrev_b32_e32 v160, 16, v151
	v_and_b32_e32 v204, 0xffff0000, v151
	v_lshlrev_b32_e32 v151, 16, v152
	v_and_b32_e32 v162, 0xffff0000, v152
	v_rcp_f32_e32 v152, v3
	v_add_f32_e32 v3, v126, v154
	v_mul_f32_e32 v3, 0xbfb8aa3b, v3
	v_exp_f32_e32 v3, v3
	v_lshlrev_b32_e32 v159, 16, v155
	v_and_b32_e32 v161, 0xffff0000, v155
	v_and_b32_e32 v155, 0xffff0000, v156
	v_lshlrev_b32_e32 v156, 16, v150
	v_add_f32_e32 v3, 1.0, v3
	v_lshlrev_b32_e32 v164, 16, v157
	v_and_b32_e32 v165, 0xffff0000, v157
	v_and_b32_e32 v157, 0xffff0000, v150
	v_add_f32_e32 v150, v146, v156
	v_rcp_f32_e32 v156, v3
	v_add_f32_e32 v3, v143, v158
	v_mul_f32_e32 v3, 0xbfb8aa3b, v3
	v_exp_f32_e32 v3, v3
	v_lshlrev_b32_e32 v205, 16, v153
	v_and_b32_e32 v206, 0xffff0000, v153
	v_add_f32_e32 v151, v130, v151
	v_add_f32_e32 v3, 1.0, v3
	v_rcp_f32_e32 v153, v3
	v_add_f32_e32 v3, v127, v155
	v_add_f32_e32 v155, v131, v162
	v_add_co_u32_e32 v162, vcc, s26, v192
	v_mul_f32_e32 v3, 0xbfb8aa3b, v3
	s_nop 0
	v_addc_co_u32_e32 v163, vcc, 0, v193, vcc
	global_load_dwordx4 v[228:231], v[162:163], off
	v_exp_f32_e32 v3, v3
	v_mul_f32_e32 v151, 0xbfb8aa3b, v151
	s_mov_b32 s26, 0x202000
	v_exp_f32_e32 v154, v151
	v_add_f32_e32 v3, 1.0, v3
	v_add_f32_e32 v151, v147, v157
	v_rcp_f32_e32 v157, v3
	v_add_f32_e32 v3, v144, v159
	v_add_co_u32_e32 v162, vcc, s26, v192
	v_mul_f32_e32 v3, 0xbfb8aa3b, v3
	s_nop 0
	v_addc_co_u32_e32 v163, vcc, 0, v193, vcc
	v_exp_f32_e32 v3, v3
	global_load_dwordx4 v[232:235], v[162:163], off
	v_add_f32_e32 v158, v148, v160
	v_add_f32_e32 v161, v145, v161
	v_add_f32_e32 v3, 1.0, v3
	v_rcp_f32_e32 v160, v3
	v_add_f32_e32 v3, v128, v164
	v_mul_f32_e32 v3, 0xbfb8aa3b, v3
	v_exp_f32_e32 v3, v3
	v_mul_f32_e32 v161, 0xbfb8aa3b, v161
	v_add_f32_e32 v159, v132, v205
	v_exp_f32_e32 v161, v161
	v_mul_f32_e32 v159, 0xbfb8aa3b, v159
; __device__ __forceinline__ void unpack8(const u32x4 w, float (&v)[8]) { v[0] = bf_lo(w.x); v[1] = bf_hi(w.x); v[2] = bf_lo(w.y); v[3] = bf_hi(w.y); v[4] = bf_lo(w.z); v[5] = bf_hi(w.z); v[6] = bf_lo(w.w); v[7] = bf_hi(w.w); }
;     __device__ __forceinline__ void after(int te, f32x4 (&acc)[2][2][4][2], const Unit& u, int wr, int wc, int fr, int fq) const {
;     ...
;             for (int bj = 0; bj < 2; ++bj) { const int c = col0 + bj * HALF;
;                 const f32x4 s0 = *(const f32x4*)(gb + c), s1 = *(const f32x4*)(gb + c + 4), a0 = *(const f32x4*)(gb + D_MODEL + c), a1 = *(const f32x4*)(gb + D_MODEL + c + 4);
; #pragma unroll
;                 for (int ai = 0; ai < 2; ++ai) {
;                     u32x4 gs[4], ga[4];
; #pragma unroll
;                     for (int m = 0; m < 4; ++m) { const size_t r = (size_t)(row0 + ai * HALF + m * 16); gs[m] = *(const u32x4*)(proj + r * LDP + PGS + c); ga[m] = *(const u32x4*)(proj + r * LDP + PGA + c); }
; #pragma unroll
;                     for (int m = 0; m < 4; ++m) { float vs[8], va[8]; unpack8(gs[m], vs); unpack8(ga[m], va);
; #pragma unroll
;                         for (int e = 0; e < 4; ++e) {
;                             acc[ai][bj][m][0][e] *= (1.f + __expf(-(va[e] + a0[e]))) * __builtin_amdgcn_rcpf(1.f + __expf(-(vs[e] + s0[e])));
;                             acc[ai][bj][m][1][e] *= (1.f + __expf(-(va[4 + e] + a1[e]))) * __builtin_amdgcn_rcpf(1.f + __expf(-(vs[4 + e] + s1[e]))); } }
	v_exp_f32_e32 v162, v159
	v_add_f32_e32 v159, v149, v204
	v_mul_f32_e32 v150, 0xbfb8aa3b, v150
	v_mul_f32_e32 v151, 0xbfb8aa3b, v151
	v_mul_f32_e32 v158, 0xbfb8aa3b, v158
	v_add_f32_e32 v3, 1.0, v3
	v_mul_f32_e32 v159, 0xbfb8aa3b, v159
	v_exp_f32_e32 v150, v150
	v_exp_f32_e32 v151, v151
	v_exp_f32_e32 v158, v158
	v_exp_f32_e32 v159, v159
	v_rcp_f32_e32 v164, v3
	v_add_f32_e32 v3, 1.0, v161
	v_rcp_f32_e32 v161, v3
	v_pk_add_f32 v[158:159], v[158:159], 1.0 op_sel_hi:[1,0]
	v_pk_add_f32 v[150:151], v[150:151], 1.0 op_sel_hi:[1,0]
	v_add_f32_e32 v3, v133, v206
	v_pk_mul_f32 v[150:151], v[150:151], v[152:153]
	v_pk_mul_f32 v[152:153], v[158:159], v[160:161]
	v_mul_f32_e32 v3, 0xbfb8aa3b, v3
	v_pk_mul_f32 v[108:109], v[108:109], v[152:153]
	v_add_f32_e32 v152, v129, v165
	v_mul_f32_e32 v152, 0xbfb8aa3b, v152
	v_exp_f32_e32 v152, v152
	v_exp_f32_e32 v163, v3
	v_mul_f32_e32 v155, 0xbfb8aa3b, v155
	v_exp_f32_e32 v155, v155
	v_add_f32_e32 v3, 1.0, v152
	v_rcp_f32_e32 v165, v3
	s_mov_b64 s[26:27], 0x200000
	v_lshl_add_u64 v[218:219], v[192:193], 0, s[26:27]
	s_mov_b64 s[26:27], 0x202000
	v_pk_mul_f32 v[106:107], v[106:107], v[150:151]
	v_pk_add_f32 v[150:151], v[162:163], 1.0 op_sel_hi:[1,0]
	v_lshl_add_u64 v[216:217], v[192:193], 0, s[26:27]
	s_mov_b64 s[26:27], 0x240000
	v_pk_mul_f32 v[150:151], v[150:151], v[164:165]
	v_lshl_add_u64 v[204:205], v[192:193], 0, s[26:27]
	s_mov_b32 s26, 0x240000
	v_pk_add_f32 v[152:153], v[154:155], 1.0 op_sel_hi:[1,0]
	v_pk_mul_f32 v[104:105], v[104:105], v[150:151]
	v_add_co_u32_e32 v150, vcc, s26, v192
	s_mov_b64 s[26:27], 0x242000
	v_pk_mul_f32 v[152:153], v[152:153], v[156:157]
	v_addc_co_u32_e32 v151, vcc, 0, v193, vcc
	v_lshl_add_u64 v[206:207], v[192:193], 0, s[26:27]
	s_mov_b32 s26, 0x242000
	v_pk_mul_f32 v[102:103], v[102:103], v[152:153]
	v_add_co_u32_e32 v152, vcc, s26, v192
	s_mov_b64 s[26:27], 0x280000
	s_nop 0
	v_addc_co_u32_e32 v153, vcc, 0, v193, vcc
	global_load_dwordx4 v[236:239], v[150:151], off
	global_load_dwordx4 v[240:243], v[152:153], off
	s_waitcnt vmcnt(3)
	v_lshlrev_b32_e32 v3, 16, v228
	v_add_f32_e32 v3, v142, v3
	v_mul_f32_e32 v3, 0xbfb8aa3b, v3
	v_exp_f32_e32 v3, v3
	v_lshlrev_b32_e32 v227, 16, v229
	v_and_b32_e32 v245, 0xffff0000, v229
	v_lshlrev_b32_e32 v229, 16, v230
	v_add_f32_e32 v3, 1.0, v3
	v_and_b32_e32 v246, 0xffff0000, v230
	v_rcp_f32_e32 v230, v3
	v_add_f32_e32 v3, v126, v229
	v_mul_f32_e32 v3, 0xbfb8aa3b, v3
	v_exp_f32_e32 v3, v3
	v_lshl_add_u64 v[208:209], v[192:193], 0, s[26:27]
	s_mov_b32 s26, 0x280000
	v_add_co_u32_e32 v150, vcc, s26, v192
	s_mov_b64 s[26:27], 0x282000
	s_nop 0
	v_addc_co_u32_e32 v151, vcc, 0, v193, vcc
	v_lshl_add_u64 v[210:211], v[192:193], 0, s[26:27]
	s_mov_b32 s26, 0x282000
	v_add_co_u32_e32 v152, vcc, s26, v192
	v_and_b32_e32 v225, 0xffff0000, v228
	v_add_f32_e32 v3, 1.0, v3
	v_addc_co_u32_e32 v153, vcc, 0, v193, vcc
	global_load_dwordx4 v[162:165], v[150:151], off
	global_load_dwordx4 v[158:161], v[152:153], off
	v_lshlrev_b32_e32 v247, 16, v231
	v_and_b32_e32 v251, 0xffff0000, v231
	s_waitcnt vmcnt(4)
	v_lshlrev_b32_e32 v228, 16, v232
	v_and_b32_e32 v231, 0xffff0000, v232
	v_lshlrev_b32_e32 v248, 16, v233
	v_and_b32_e32 v249, 0xffff0000, v233
	v_lshlrev_b32_e32 v232, 16, v234
	v_and_b32_e32 v233, 0xffff0000, v234
	v_rcp_f32_e32 v234, v3
	v_add_f32_e32 v3, v143, v225
	v_mul_f32_e32 v3, 0xbfb8aa3b, v3
	v_exp_f32_e32 v3, v3
	v_add_f32_e32 v225, v147, v231
	v_lshlrev_b32_e32 v250, 16, v235
	v_and_b32_e32 v253, 0xffff0000, v235
	v_add_f32_e32 v3, 1.0, v3
	v_rcp_f32_e32 v231, v3
	v_add_f32_e32 v3, v127, v246
	v_mul_f32_e32 v3, 0xbfb8aa3b, v3
	v_exp_f32_e32 v3, v3
	v_add_f32_e32 v229, v130, v232
	v_mul_f32_e32 v229, 0xbfb8aa3b, v229
	v_mul_f32_e32 v225, 0xbfb8aa3b, v225
	v_add_f32_e32 v3, 1.0, v3
	v_rcp_f32_e32 v235, v3
	v_add_f32_e32 v3, v144, v227
	v_mul_f32_e32 v3, 0xbfb8aa3b, v3
	v_exp_f32_e32 v3, v3
	v_exp_f32_e32 v232, v229
	v_exp_f32_e32 v229, v225
	v_add_f32_e32 v225, v131, v233
	v_mul_f32_e32 v225, 0xbfb8aa3b, v225
	v_exp_f32_e32 v233, v225
	v_add_f32_e32 v225, v148, v248
	v_mul_f32_e32 v225, 0xbfb8aa3b, v225
	v_add_f32_e32 v3, 1.0, v3
	v_exp_f32_e32 v246, v225
	v_rcp_f32_e32 v248, v3
	v_add_f32_e32 v3, v128, v247
	v_add_f32_e32 v225, v132, v250
	v_mul_f32_e32 v3, 0xbfb8aa3b, v3
	v_mul_f32_e32 v225, 0xbfb8aa3b, v225
	v_add_f32_e32 v227, v145, v245
	v_exp_f32_e32 v3, v3
	v_exp_f32_e32 v250, v225
	v_add_f32_e32 v225, v149, v249
	v_mul_f32_e32 v227, 0xbfb8aa3b, v227
	v_exp_f32_e32 v227, v227
	v_mul_f32_e32 v225, 0xbfb8aa3b, v225
	v_exp_f32_e32 v247, v225
	v_add_f32_e32 v225, v129, v251
	v_mul_f32_e32 v225, 0xbfb8aa3b, v225
	v_add_f32_e32 v3, 1.0, v3
	v_exp_f32_e32 v225, v225
	v_rcp_f32_e32 v252, v3
	v_add_f32_e32 v3, 1.0, v227
	v_add_f32_e32 v228, v146, v228
	v_rcp_f32_e32 v249, v3
	v_add_f32_e32 v3, v133, v253
	v_mul_f32_e32 v228, 0xbfb8aa3b, v228
	v_mul_f32_e32 v3, 0xbfb8aa3b, v3
	v_exp_f32_e32 v228, v228
	v_exp_f32_e32 v251, v3
	v_add_f32_e32 v3, 1.0, v225
	v_rcp_f32_e32 v253, v3
	s_waitcnt vmcnt(3)
; __device__ __forceinline__ void unpack8(const u32x4 w, float (&v)[8]) { v[0] = bf_lo(w.x); v[1] = bf_hi(w.x); v[2] = bf_lo(w.y); v[3] = bf_hi(w.y); v[4] = bf_lo(w.z); v[5] = bf_hi(w.z); v[6] = bf_lo(w.w); v[7] = bf_hi(w.w); }
;     __device__ __forceinline__ void after(int te, f32x4 (&acc)[2][2][4][2], const Unit& u, int wr, int wc, int fr, int fq) const {
;     ...
;                     for (int m = 0; m < 4; ++m) { const size_t r = (size_t)(row0 + ai * HALF + m * 16); gs[m] = *(const u32x4*)(proj + r * LDP + PGS + c); ga[m] = *(const u32x4*)(proj + r * LDP + PGA + c); }
; #pragma unroll
;                     for (int m = 0; m < 4; ++m) { float vs[8], va[8]; unpack8(gs[m], vs); unpack8(ga[m], va);
; #pragma unroll
;                         for (int e = 0; e < 4; ++e) {
;                             acc[ai][bj][m][0][e] *= (1.f + __expf(-(va[e] + a0[e]))) * __builtin_amdgcn_rcpf(1.f + __expf(-(vs[e] + s0[e])));
;                             acc[ai][bj][m][1][e] *= (1.f + __expf(-(va[4 + e] + a1[e]))) * __builtin_amdgcn_rcpf(1.f + __expf(-(vs[4 + e] + s1[e]))); } }
	v_lshlrev_b32_e32 v3, 16, v236
	v_add_f32_e32 v3, v142, v3
	v_mul_f32_e32 v3, 0xbfb8aa3b, v3
	v_pk_add_f32 v[228:229], v[228:229], 1.0 op_sel_hi:[1,0]
	v_exp_f32_e32 v3, v3
	v_pk_add_f32 v[246:247], v[246:247], 1.0 op_sel_hi:[1,0]
	v_pk_mul_f32 v[228:229], v[228:229], v[230:231]
	v_pk_mul_f32 v[230:231], v[246:247], v[248:249]
	v_pk_mul_f32 v[98:99], v[98:99], v[228:229]
	v_pk_add_f32 v[228:229], v[250:251], 1.0 op_sel_hi:[1,0]
	v_pk_mul_f32 v[100:101], v[100:101], v[230:231]
	v_pk_add_f32 v[230:231], v[232:233], 1.0 op_sel_hi:[1,0]
	v_pk_mul_f32 v[228:229], v[228:229], v[252:253]
	v_pk_mul_f32 v[230:231], v[230:231], v[234:235]
	v_pk_mul_f32 v[96:97], v[96:97], v[228:229]
	v_lshlrev_b32_e32 v229, 16, v238
	v_add_f32_e32 v3, 1.0, v3
	v_pk_mul_f32 v[94:95], v[94:95], v[230:231]
	v_rcp_f32_e32 v230, v3
	v_add_f32_e32 v3, v126, v229
	v_mul_f32_e32 v3, 0xbfb8aa3b, v3
	v_exp_f32_e32 v3, v3
	v_and_b32_e32 v225, 0xffff0000, v236
	s_mov_b64 s[26:27], 0x2c0000
	v_lshl_add_u64 v[212:213], v[192:193], 0, s[26:27]
	v_add_f32_e32 v3, 1.0, v3
	v_rcp_f32_e32 v234, v3
	v_add_f32_e32 v3, v143, v225
	v_mul_f32_e32 v3, 0xbfb8aa3b, v3
	v_exp_f32_e32 v3, v3
	s_mov_b32 s26, 0x2c0000
	v_add_co_u32_e32 v150, vcc, s26, v192
	s_mov_b64 s[26:27], 0x2c2000
	s_nop 0
	v_addc_co_u32_e32 v151, vcc, 0, v193, vcc
	v_lshl_add_u64 v[214:215], v[192:193], 0, s[26:27]
	s_mov_b32 s26, 0x2c2000
	v_and_b32_e32 v233, 0xffff0000, v238
	s_waitcnt vmcnt(2)
	v_and_b32_e32 v231, 0xffff0000, v240
	v_add_f32_e32 v3, 1.0, v3
	v_add_co_u32_e32 v152, vcc, s26, v192
	v_add_f32_e32 v225, v147, v231
	v_rcp_f32_e32 v231, v3
	v_add_f32_e32 v3, v127, v233
	v_addc_co_u32_e32 v153, vcc, 0, v193, vcc
	v_mul_f32_e32 v3, 0xbfb8aa3b, v3
	global_load_dwordx4 v[154:157], v[150:151], off
	s_nop 0
	global_load_dwordx4 v[150:153], v[152:153], off
	v_exp_f32_e32 v3, v3
	v_lshlrev_b32_e32 v232, 16, v242
	v_add_f32_e32 v229, v130, v232
	v_lshlrev_b32_e32 v227, 16, v237
	v_and_b32_e32 v235, 0xffff0000, v242
	v_mul_f32_e32 v229, 0xbfb8aa3b, v229
	v_mul_f32_e32 v225, 0xbfb8aa3b, v225
	v_add_f32_e32 v3, 1.0, v3
	v_exp_f32_e32 v232, v229
	v_exp_f32_e32 v229, v225
	v_add_f32_e32 v225, v131, v235
	v_rcp_f32_e32 v235, v3
	v_add_f32_e32 v3, v144, v227
	v_mul_f32_e32 v3, 0xbfb8aa3b, v3
	v_exp_f32_e32 v3, v3
	v_lshlrev_b32_e32 v236, 16, v241
	v_mul_f32_e32 v225, 0xbfb8aa3b, v225
	v_exp_f32_e32 v233, v225
	v_add_f32_e32 v225, v148, v236
	v_lshlrev_b32_e32 v245, 16, v239
	v_lshlrev_b32_e32 v228, 16, v240
	v_lshlrev_b32_e32 v240, 16, v243
	v_mul_f32_e32 v225, 0xbfb8aa3b, v225
	v_add_f32_e32 v3, 1.0, v3
	v_and_b32_e32 v237, 0xffff0000, v237
	v_exp_f32_e32 v236, v225
	v_rcp_f32_e32 v238, v3
	v_add_f32_e32 v3, v128, v245
	v_add_f32_e32 v225, v132, v240
	v_and_b32_e32 v246, 0xffff0000, v239
	v_and_b32_e32 v239, 0xffff0000, v241
	v_mul_f32_e32 v3, 0xbfb8aa3b, v3
	v_mul_f32_e32 v225, 0xbfb8aa3b, v225
	v_add_f32_e32 v227, v145, v237
	v_exp_f32_e32 v3, v3
	v_exp_f32_e32 v240, v225
	v_add_f32_e32 v225, v149, v239
	v_mul_f32_e32 v227, 0xbfb8aa3b, v227
	v_exp_f32_e32 v227, v227
	v_mul_f32_e32 v225, 0xbfb8aa3b, v225
	v_exp_f32_e32 v237, v225
	v_add_f32_e32 v225, v129, v246
	v_mul_f32_e32 v225, 0xbfb8aa3b, v225
	v_add_f32_e32 v3, 1.0, v3
	v_exp_f32_e32 v225, v225
	v_and_b32_e32 v241, 0xffff0000, v243
	v_rcp_f32_e32 v242, v3
	v_add_f32_e32 v3, 1.0, v227
	v_rcp_f32_e32 v239, v3
	v_add_f32_e32 v3, v133, v241
	v_add_f32_e32 v228, v146, v228
	v_mul_f32_e32 v3, 0xbfb8aa3b, v3
	v_mul_f32_e32 v228, 0xbfb8aa3b, v228
	v_exp_f32_e32 v241, v3
	v_add_f32_e32 v3, 1.0, v225
	v_exp_f32_e32 v228, v228
	v_rcp_f32_e32 v243, v3
	s_waitcnt vmcnt(3)
	v_lshlrev_b32_e32 v3, 16, v162
	v_add_f32_e32 v3, v142, v3
	v_mul_f32_e32 v3, 0xbfb8aa3b, v3
	v_exp_f32_e32 v3, v3
	v_pk_add_f32 v[236:237], v[236:237], 1.0 op_sel_hi:[1,0]
	v_pk_add_f32 v[228:229], v[228:229], 1.0 op_sel_hi:[1,0]
	v_and_b32_e32 v225, 0xffff0000, v162
	v_pk_mul_f32 v[228:229], v[228:229], v[230:231]
	v_pk_mul_f32 v[230:231], v[236:237], v[238:239]
	v_pk_mul_f32 v[90:91], v[90:91], v[228:229]
	v_pk_mul_f32 v[92:93], v[92:93], v[230:231]
	v_pk_add_f32 v[228:229], v[240:241], 1.0 op_sel_hi:[1,0]
	v_pk_add_f32 v[230:231], v[232:233], 1.0 op_sel_hi:[1,0]
	v_pk_mul_f32 v[228:229], v[228:229], v[242:243]
	v_pk_mul_f32 v[230:231], v[230:231], v[234:235]
	v_lshlrev_b32_e32 v162, 16, v164
	v_add_f32_e32 v3, 1.0, v3
	v_pk_mul_f32 v[88:89], v[88:89], v[228:229]
	v_pk_mul_f32 v[86:87], v[86:87], v[230:231]
	s_waitcnt vmcnt(2)
; __device__ __forceinline__ void unpack8(const u32x4 w, float (&v)[8]) { v[0] = bf_lo(w.x); v[1] = bf_hi(w.x); v[2] = bf_lo(w.y); v[3] = bf_hi(w.y); v[4] = bf_lo(w.z); v[5] = bf_hi(w.z); v[6] = bf_lo(w.w); v[7] = bf_hi(w.w); }
;     __device__ __forceinline__ void after(int te, f32x4 (&acc)[2][2][4][2], const Unit& u, int wr, int wc, int fr, int fq) const {
;     ...
;             for (int bj = 0; bj < 2; ++bj) { const int c = col0 + bj * HALF;
;                 const f32x4 s0 = *(const f32x4*)(gb + c), s1 = *(const f32x4*)(gb + c + 4), a0 = *(const f32x4*)(gb + D_MODEL + c), a1 = *(const f32x4*)(gb + D_MODEL + c + 4);
; #pragma unroll
;                 for (int ai = 0; ai < 2; ++ai) {
;                     u32x4 gs[4], ga[4];
; #pragma unroll
;                     for (int m = 0; m < 4; ++m) { const size_t r = (size_t)(row0 + ai * HALF + m * 16); gs[m] = *(const u32x4*)(proj + r * LDP + PGS + c); ga[m] = *(const u32x4*)(proj + r * LDP + PGA + c); }
; #pragma unroll
;                     for (int m = 0; m < 4; ++m) { float vs[8], va[8]; unpack8(gs[m], vs); unpack8(ga[m], va);
; #pragma unroll
;                         for (int e = 0; e < 4; ++e) {
;                             acc[ai][bj][m][0][e] *= (1.f + __expf(-(va[e] + a0[e]))) * __builtin_amdgcn_rcpf(1.f + __expf(-(vs[e] + s0[e])));
;                             acc[ai][bj][m][1][e] *= (1.f + __expf(-(va[4 + e] + a1[e]))) * __builtin_amdgcn_rcpf(1.f + __expf(-(vs[4 + e] + s1[e]))); } }
	v_lshlrev_b32_e32 v228, 16, v159
	v_and_b32_e32 v234, 0xffff0000, v159
	v_lshlrev_b32_e32 v159, 16, v160
	v_and_b32_e32 v230, 0xffff0000, v160
	v_rcp_f32_e32 v160, v3
	v_add_f32_e32 v3, v126, v162
	v_mul_f32_e32 v3, 0xbfb8aa3b, v3
	v_exp_f32_e32 v3, v3
	v_lshlrev_b32_e32 v227, 16, v163
	v_and_b32_e32 v229, 0xffff0000, v163
	v_and_b32_e32 v163, 0xffff0000, v164
	v_lshlrev_b32_e32 v164, 16, v158
	v_add_f32_e32 v3, 1.0, v3
	v_lshlrev_b32_e32 v231, 16, v165
	v_and_b32_e32 v233, 0xffff0000, v165
	v_and_b32_e32 v165, 0xffff0000, v158
	v_add_f32_e32 v158, v146, v164
	v_rcp_f32_e32 v164, v3
	v_add_f32_e32 v3, v143, v225
	v_mul_f32_e32 v3, 0xbfb8aa3b, v3
	v_exp_f32_e32 v3, v3
	v_lshlrev_b32_e32 v232, 16, v161
	v_and_b32_e32 v235, 0xffff0000, v161
	v_add_f32_e32 v159, v130, v159
	v_add_f32_e32 v3, 1.0, v3
	v_rcp_f32_e32 v161, v3
	v_add_f32_e32 v3, v127, v163
	v_mul_f32_e32 v3, 0xbfb8aa3b, v3
	v_exp_f32_e32 v3, v3
	v_mul_f32_e32 v159, 0xbfb8aa3b, v159
	v_exp_f32_e32 v162, v159
	v_add_f32_e32 v159, v147, v165
	v_add_f32_e32 v3, 1.0, v3
	v_rcp_f32_e32 v165, v3
	v_add_f32_e32 v3, v144, v227
	v_mul_f32_e32 v3, 0xbfb8aa3b, v3
	v_exp_f32_e32 v3, v3
	v_add_f32_e32 v163, v131, v230
	v_add_f32_e32 v225, v148, v228
	v_add_f32_e32 v227, v145, v229
	v_add_f32_e32 v3, 1.0, v3
	v_rcp_f32_e32 v230, v3
	v_add_f32_e32 v3, v128, v231
	v_mul_f32_e32 v3, 0xbfb8aa3b, v3
	v_mul_f32_e32 v225, 0xbfb8aa3b, v225
	v_exp_f32_e32 v3, v3
	v_mul_f32_e32 v227, 0xbfb8aa3b, v227
	v_exp_f32_e32 v228, v225
	v_add_f32_e32 v225, v132, v232
	v_exp_f32_e32 v227, v227
	v_mul_f32_e32 v225, 0xbfb8aa3b, v225
	v_exp_f32_e32 v232, v225
	v_add_f32_e32 v225, v149, v234
	v_mul_f32_e32 v158, 0xbfb8aa3b, v158
	v_mul_f32_e32 v159, 0xbfb8aa3b, v159
	v_add_f32_e32 v3, 1.0, v3
	v_mul_f32_e32 v225, 0xbfb8aa3b, v225
	v_exp_f32_e32 v158, v158
	v_exp_f32_e32 v159, v159
	v_exp_f32_e32 v229, v225
	v_rcp_f32_e32 v234, v3
	v_add_f32_e32 v3, 1.0, v227
	v_rcp_f32_e32 v231, v3
	v_pk_add_f32 v[228:229], v[228:229], 1.0 op_sel_hi:[1,0]
	v_pk_add_f32 v[158:159], v[158:159], 1.0 op_sel_hi:[1,0]
	v_add_f32_e32 v3, v133, v235
	v_pk_mul_f32 v[158:159], v[158:159], v[160:161]
	v_pk_mul_f32 v[160:161], v[228:229], v[230:231]
	v_mul_f32_e32 v3, 0xbfb8aa3b, v3
	v_pk_mul_f32 v[84:85], v[84:85], v[160:161]
	v_add_f32_e32 v160, v129, v233
	v_mul_f32_e32 v160, 0xbfb8aa3b, v160
	v_exp_f32_e32 v160, v160
	v_exp_f32_e32 v233, v3
	s_waitcnt vmcnt(1)
	v_lshlrev_b32_e32 v225, 16, v155
	v_and_b32_e32 v227, 0xffff0000, v155
	v_add_f32_e32 v3, 1.0, v160
	v_rcp_f32_e32 v235, v3
	v_lshlrev_b32_e32 v3, 16, v154
	v_add_f32_e32 v3, v142, v3
	v_mul_f32_e32 v3, 0xbfb8aa3b, v3
	v_exp_f32_e32 v3, v3
	v_lshlrev_b32_e32 v155, 16, v156
	v_and_b32_e32 v236, 0xffff0000, v156
	s_waitcnt vmcnt(0)
	v_lshlrev_b32_e32 v156, 16, v150
	v_add_f32_e32 v3, 1.0, v3
	v_mul_f32_e32 v163, 0xbfb8aa3b, v163
	v_add_f32_e32 v142, v146, v156
	v_rcp_f32_e32 v146, v3
	v_add_f32_e32 v3, v126, v155
	v_exp_f32_e32 v163, v163
	v_mul_f32_e32 v3, 0xbfb8aa3b, v3
	v_exp_f32_e32 v3, v3
	v_pk_mul_f32 v[82:83], v[82:83], v[158:159]
	v_pk_add_f32 v[158:159], v[232:233], 1.0 op_sel_hi:[1,0]
	v_pk_add_f32 v[160:161], v[162:163], 1.0 op_sel_hi:[1,0]
	v_pk_mul_f32 v[158:159], v[158:159], v[234:235]
	v_pk_mul_f32 v[160:161], v[160:161], v[164:165]
	v_and_b32_e32 v150, 0xffff0000, v150
	v_lshlrev_b32_e32 v239, 16, v151
	v_and_b32_e32 v240, 0xffff0000, v151
	v_lshlrev_b32_e32 v151, 16, v152
	global_load_dwordx4 v[228:231], v[192:193], off offset:256
	global_load_dwordx4 v[232:235], v[202:203], off offset:256
	v_add_f32_e32 v3, 1.0, v3
	v_pk_mul_f32 v[80:81], v[80:81], v[158:159]
	v_pk_mul_f32 v[78:79], v[78:79], v[160:161]
	v_and_b32_e32 v241, 0xffff0000, v152
	v_lshlrev_b32_e32 v242, 16, v153
	v_and_b32_e32 v243, 0xffff0000, v153
	v_add_f32_e32 v126, v130, v151
	v_rcp_f32_e32 v130, v3
	v_add_f32_e32 v3, v147, v150
	global_load_dwordx4 v[150:153], v[196:197], off offset:528
	global_load_dwordx4 v[158:161], v[196:197], off offset:512
	v_and_b32_e32 v154, 0xffff0000, v154
	v_lshlrev_b32_e32 v237, 16, v157
	v_and_b32_e32 v238, 0xffff0000, v157
	v_add_f32_e32 v143, v143, v154
	global_load_dwordx4 v[154:157], v[198:199], off offset:528
	global_load_dwordx4 v[162:165], v[198:199], off offset:512
	v_mul_f32_e32 v143, 0xbfb8aa3b, v143
	v_exp_f32_e32 v147, v143
	v_mul_f32_e32 v3, 0xbfb8aa3b, v3
	v_exp_f32_e32 v143, v3
	v_add_f32_e32 v145, v145, v227
	v_add_f32_e32 v3, 1.0, v147
	v_rcp_f32_e32 v147, v3
	v_add_f32_e32 v3, v127, v236
	v_mul_f32_e32 v3, 0xbfb8aa3b, v3
	v_exp_f32_e32 v3, v3
	v_add_f32_e32 v127, v131, v241
	v_mul_f32_e32 v145, 0xbfb8aa3b, v145
	v_add_f32_e32 v129, v129, v238
	v_add_f32_e32 v3, 1.0, v3
	v_rcp_f32_e32 v131, v3
	v_add_f32_e32 v3, v144, v225
	v_mul_f32_e32 v3, 0xbfb8aa3b, v3
	v_exp_f32_e32 v3, v3
	v_add_f32_e32 v144, v148, v239
	v_mul_f32_e32 v129, 0xbfb8aa3b, v129
	v_mul_f32_e32 v142, 0xbfb8aa3b, v142
	v_add_f32_e32 v3, 1.0, v3
	v_rcp_f32_e32 v148, v3
	v_add_f32_e32 v3, v128, v237
	v_mul_f32_e32 v3, 0xbfb8aa3b, v3
	v_exp_f32_e32 v3, v3
	v_add_f32_e32 v128, v132, v242
	v_add_f32_e32 v132, v149, v240
	v_exp_f32_e32 v149, v145
	v_add_f32_e32 v3, 1.0, v3
	v_mul_f32_e32 v132, 0xbfb8aa3b, v132
	v_exp_f32_e32 v145, v132
	v_rcp_f32_e32 v132, v3
	v_add_f32_e32 v3, 1.0, v149
	v_rcp_f32_e32 v149, v3
	v_add_f32_e32 v3, v133, v243
	v_exp_f32_e32 v133, v129
	v_mul_f32_e32 v126, 0xbfb8aa3b, v126
	v_mul_f32_e32 v127, 0xbfb8aa3b, v127
	v_mul_f32_e32 v144, 0xbfb8aa3b, v144
	v_mul_f32_e32 v128, 0xbfb8aa3b, v128
	v_mul_f32_e32 v3, 0xbfb8aa3b, v3
	v_exp_f32_e32 v142, v142
	v_exp_f32_e32 v126, v126
	v_exp_f32_e32 v127, v127
	v_exp_f32_e32 v144, v144
	v_exp_f32_e32 v128, v128
	v_exp_f32_e32 v129, v3
	v_add_f32_e32 v3, 1.0, v133
	v_rcp_f32_e32 v133, v3
	v_pk_add_f32 v[144:145], v[144:145], 1.0 op_sel_hi:[1,0]
	v_pk_add_f32 v[142:143], v[142:143], 1.0 op_sel_hi:[1,0]
	v_pk_add_f32 v[128:129], v[128:129], 1.0 op_sel_hi:[1,0]
	v_pk_add_f32 v[126:127], v[126:127], 1.0 op_sel_hi:[1,0]
	v_pk_mul_f32 v[142:143], v[142:143], v[146:147]
	v_pk_mul_f32 v[144:145], v[144:145], v[148:149]
	v_pk_mul_f32 v[126:127], v[126:127], v[130:131]
	v_pk_mul_f32 v[128:129], v[128:129], v[132:133]
	v_pk_mul_f32 v[76:77], v[76:77], v[144:145]
	v_pk_mul_f32 v[74:75], v[74:75], v[142:143]
	v_pk_mul_f32 v[72:73], v[72:73], v[128:129]
	v_pk_mul_f32 v[70:71], v[70:71], v[126:127]
	global_load_dwordx4 v[196:199], v[4:5], off offset:256
	global_load_dwordx4 v[236:239], v[186:187], off offset:256
	global_load_dwordx4 v[146:149], v[188:189], off offset:256
	global_load_dwordx4 v[142:145], v[190:191], off offset:256
	global_load_dwordx4 v[130:133], v[194:195], off offset:256
	global_load_dwordx4 v[126:129], v[200:201], off offset:256
	s_waitcnt vmcnt(11)
; __device__ __forceinline__ void unpack8(const u32x4 w, float (&v)[8]) { v[0] = bf_lo(w.x); v[1] = bf_hi(w.x); v[2] = bf_lo(w.y); v[3] = bf_hi(w.y); v[4] = bf_lo(w.z); v[5] = bf_hi(w.z); v[6] = bf_lo(w.w); v[7] = bf_hi(w.w); }
;     __device__ __forceinline__ void after(int te, f32x4 (&acc)[2][2][4][2], const Unit& u, int wr, int wc, int fr, int fq) const {
;     ...
;                     for (int m = 0; m < 4; ++m) { const size_t r = (size_t)(row0 + ai * HALF + m * 16); gs[m] = *(const u32x4*)(proj + r * LDP + PGS + c); ga[m] = *(const u32x4*)(proj + r * LDP + PGA + c); }
; #pragma unroll
;                     for (int m = 0; m < 4; ++m) { float vs[8], va[8]; unpack8(gs[m], vs); unpack8(ga[m], va);
; #pragma unroll
;                         for (int e = 0; e < 4; ++e) {
;                             acc[ai][bj][m][0][e] *= (1.f + __expf(-(va[e] + a0[e]))) * __builtin_amdgcn_rcpf(1.f + __expf(-(vs[e] + s0[e])));
;                             acc[ai][bj][m][1][e] *= (1.f + __expf(-(va[4 + e] + a1[e]))) * __builtin_amdgcn_rcpf(1.f + __expf(-(vs[4 + e] + s1[e]))); } }
	v_lshlrev_b32_e32 v3, 16, v228
	v_lshlrev_b32_e32 v187, 16, v230
	v_and_b32_e32 v5, 0xffff0000, v228
	s_waitcnt vmcnt(10)
	v_lshlrev_b32_e32 v188, 16, v234
	v_and_b32_e32 v189, 0xffff0000, v230
	v_lshlrev_b32_e32 v192, 16, v229
	v_and_b32_e32 v191, 0xffff0000, v232
	v_lshlrev_b32_e32 v195, 16, v231
	v_lshlrev_b32_e32 v194, 16, v233
	v_and_b32_e32 v193, 0xffff0000, v229
	v_lshlrev_b32_e32 v203, 16, v235
	s_waitcnt vmcnt(8)
	v_add_f32_e32 v3, v158, v3
	v_mul_f32_e32 v3, 0xbfb8aa3b, v3
	v_exp_f32_e32 v3, v3
	v_add_f32_e32 v193, v161, v193
	v_mul_f32_e32 v193, 0xbfb8aa3b, v193
	v_lshlrev_b32_e32 v4, 16, v232
	v_add_f32_e32 v3, 1.0, v3
	v_rcp_f32_e32 v186, v3
	v_add_f32_e32 v3, v150, v187
	v_mul_f32_e32 v3, 0xbfb8aa3b, v3
	v_exp_f32_e32 v3, v3
	s_waitcnt vmcnt(7)
	v_add_f32_e32 v187, v154, v188
	v_mul_f32_e32 v187, 0xbfb8aa3b, v187
	v_exp_f32_e32 v188, v187
	v_add_f32_e32 v3, 1.0, v3
	v_rcp_f32_e32 v190, v3
	v_add_f32_e32 v3, v159, v5
	v_mul_f32_e32 v3, 0xbfb8aa3b, v3
	v_exp_f32_e32 v3, v3
	s_waitcnt vmcnt(6)
	v_add_f32_e32 v5, v163, v191
	v_and_b32_e32 v202, 0xffff0000, v233
	v_and_b32_e32 v200, 0xffff0000, v234
	v_add_f32_e32 v3, 1.0, v3
	v_rcp_f32_e32 v187, v3
	v_add_f32_e32 v3, v151, v189
	v_mul_f32_e32 v3, 0xbfb8aa3b, v3
	v_exp_f32_e32 v3, v3
	v_add_f32_e32 v4, v162, v4
	v_add_f32_e32 v189, v155, v200
	v_mul_f32_e32 v4, 0xbfb8aa3b, v4
	v_add_f32_e32 v3, 1.0, v3
	v_rcp_f32_e32 v191, v3
	v_add_f32_e32 v3, v160, v192
	v_mul_f32_e32 v3, 0xbfb8aa3b, v3
	v_exp_f32_e32 v3, v3
	v_add_f32_e32 v192, v164, v194
	v_mul_f32_e32 v5, 0xbfb8aa3b, v5
	v_mul_f32_e32 v192, 0xbfb8aa3b, v192
	v_add_f32_e32 v3, 1.0, v3
	v_rcp_f32_e32 v194, v3
	v_add_f32_e32 v3, v152, v195
	v_mul_f32_e32 v3, 0xbfb8aa3b, v3
	v_exp_f32_e32 v3, v3
	v_add_f32_e32 v195, v156, v203
	v_exp_f32_e32 v203, v193
	v_mul_f32_e32 v195, 0xbfb8aa3b, v195
	v_exp_f32_e32 v200, v195
	v_add_f32_e32 v195, v165, v202
	v_add_f32_e32 v3, 1.0, v3
	v_mul_f32_e32 v193, 0xbfb8aa3b, v195
	v_exp_f32_e32 v4, v4
	v_exp_f32_e32 v5, v5
	v_exp_f32_e32 v192, v192
	v_exp_f32_e32 v193, v193
	v_rcp_f32_e32 v202, v3
	v_add_f32_e32 v3, 1.0, v203
	v_rcp_f32_e32 v195, v3
	v_pk_add_f32 v[192:193], v[192:193], 1.0 op_sel_hi:[1,0]
	v_pk_add_f32 v[4:5], v[4:5], 1.0 op_sel_hi:[1,0]
	v_and_b32_e32 v201, 0xffff0000, v231
	v_pk_mul_f32 v[4:5], v[4:5], v[186:187]
	v_pk_mul_f32 v[186:187], v[192:193], v[194:195]
	v_and_b32_e32 v225, 0xffff0000, v235
	v_pk_mul_f32 v[68:69], v[68:69], v[186:187]
	v_add_f32_e32 v186, v153, v201
	v_mul_f32_e32 v186, 0xbfb8aa3b, v186
	v_exp_f32_e32 v186, v186
	v_add_f32_e32 v3, v157, v225
	v_mul_f32_e32 v3, 0xbfb8aa3b, v3
	v_exp_f32_e32 v201, v3
	v_add_f32_e32 v3, 1.0, v186
	v_mul_f32_e32 v189, 0xbfb8aa3b, v189
	v_rcp_f32_e32 v203, v3
	s_waitcnt vmcnt(5)
	v_lshlrev_b32_e32 v3, 16, v196
	v_exp_f32_e32 v189, v189
	v_add_f32_e32 v3, v158, v3
	v_mul_f32_e32 v3, 0xbfb8aa3b, v3
	v_exp_f32_e32 v3, v3
	v_pk_add_f32 v[186:187], v[188:189], 1.0 op_sel_hi:[1,0]
	v_pk_mul_f32 v[66:67], v[66:67], v[4:5]
	v_pk_mul_f32 v[186:187], v[186:187], v[190:191]
	v_add_f32_e32 v3, 1.0, v3
	v_pk_mul_f32 v[62:63], v[62:63], v[186:187]
	v_lshlrev_b32_e32 v187, 16, v198
	v_rcp_f32_e32 v186, v3
	v_add_f32_e32 v3, v150, v187
	v_mul_f32_e32 v3, 0xbfb8aa3b, v3
	v_exp_f32_e32 v3, v3
	v_pk_add_f32 v[4:5], v[200:201], 1.0 op_sel_hi:[1,0]
	s_waitcnt vmcnt(4)
	v_lshlrev_b32_e32 v188, 16, v238
	v_pk_mul_f32 v[4:5], v[4:5], v[202:203]
	v_add_f32_e32 v3, 1.0, v3
	v_pk_mul_f32 v[64:65], v[64:65], v[4:5]
	v_and_b32_e32 v5, 0xffff0000, v196
	v_rcp_f32_e32 v190, v3
	v_add_f32_e32 v3, v159, v5
	v_mul_f32_e32 v3, 0xbfb8aa3b, v3
	v_exp_f32_e32 v3, v3
	v_add_f32_e32 v187, v154, v188
	v_and_b32_e32 v189, 0xffff0000, v198
	v_mul_f32_e32 v187, 0xbfb8aa3b, v187
	v_add_f32_e32 v3, 1.0, v3
	v_exp_f32_e32 v188, v187
	v_rcp_f32_e32 v187, v3
	v_add_f32_e32 v3, v151, v189
	v_mul_f32_e32 v3, 0xbfb8aa3b, v3
	v_exp_f32_e32 v3, v3
	v_lshlrev_b32_e32 v192, 16, v197
	v_and_b32_e32 v191, 0xffff0000, v236
	v_add_f32_e32 v5, v163, v191
	v_add_f32_e32 v3, 1.0, v3
	v_rcp_f32_e32 v191, v3
	v_add_f32_e32 v3, v160, v192
	v_mul_f32_e32 v3, 0xbfb8aa3b, v3
	v_exp_f32_e32 v3, v3
	v_lshlrev_b32_e32 v195, 16, v199
	v_lshlrev_b32_e32 v194, 16, v237
	v_and_b32_e32 v193, 0xffff0000, v197
	v_add_f32_e32 v3, 1.0, v3
	v_add_f32_e32 v192, v164, v194
	v_rcp_f32_e32 v194, v3
	v_add_f32_e32 v3, v152, v195
	v_mul_f32_e32 v3, 0xbfb8aa3b, v3
	v_add_f32_e32 v193, v161, v193
	v_and_b32_e32 v197, 0xffff0000, v199
	v_lshlrev_b32_e32 v199, 16, v239
	v_exp_f32_e32 v3, v3
	v_mul_f32_e32 v193, 0xbfb8aa3b, v193
	v_add_f32_e32 v195, v156, v199
	v_exp_f32_e32 v199, v193
	v_lshlrev_b32_e32 v4, 16, v236
	v_and_b32_e32 v198, 0xffff0000, v237
	v_and_b32_e32 v196, 0xffff0000, v238
	v_mul_f32_e32 v195, 0xbfb8aa3b, v195
	v_add_f32_e32 v4, v162, v4
	v_add_f32_e32 v189, v155, v196
	v_exp_f32_e32 v196, v195
	v_add_f32_e32 v195, v165, v198
	v_mul_f32_e32 v4, 0xbfb8aa3b, v4
	v_mul_f32_e32 v5, 0xbfb8aa3b, v5
	v_mul_f32_e32 v192, 0xbfb8aa3b, v192
	v_add_f32_e32 v3, 1.0, v3
	v_mul_f32_e32 v193, 0xbfb8aa3b, v195
	v_exp_f32_e32 v4, v4
	v_exp_f32_e32 v5, v5
	v_exp_f32_e32 v192, v192
	v_exp_f32_e32 v193, v193
	v_rcp_f32_e32 v198, v3
	v_add_f32_e32 v3, 1.0, v199
	v_rcp_f32_e32 v195, v3
	v_pk_add_f32 v[192:193], v[192:193], 1.0 op_sel_hi:[1,0]
	v_pk_add_f32 v[4:5], v[4:5], 1.0 op_sel_hi:[1,0]
	v_and_b32_e32 v200, 0xffff0000, v239
	v_pk_mul_f32 v[4:5], v[4:5], v[186:187]
	v_pk_mul_f32 v[186:187], v[192:193], v[194:195]
	v_add_f32_e32 v3, v157, v200
	v_pk_mul_f32 v[60:61], v[60:61], v[186:187]
	v_add_f32_e32 v186, v153, v197
	v_mul_f32_e32 v186, 0xbfb8aa3b, v186
	v_exp_f32_e32 v186, v186
	v_mul_f32_e32 v3, 0xbfb8aa3b, v3
	v_exp_f32_e32 v197, v3
	v_mul_f32_e32 v189, 0xbfb8aa3b, v189
	v_add_f32_e32 v3, 1.0, v186
	v_rcp_f32_e32 v199, v3
	s_waitcnt vmcnt(3)
; __device__ __forceinline__ void unpack8(const u32x4 w, float (&v)[8]) { v[0] = bf_lo(w.x); v[1] = bf_hi(w.x); v[2] = bf_lo(w.y); v[3] = bf_hi(w.y); v[4] = bf_lo(w.z); v[5] = bf_hi(w.z); v[6] = bf_lo(w.w); v[7] = bf_hi(w.w); }
;     __device__ __forceinline__ void after(int te, f32x4 (&acc)[2][2][4][2], const Unit& u, int wr, int wc, int fr, int fq) const {
;     ...
;                     for (int m = 0; m < 4; ++m) { const size_t r = (size_t)(row0 + ai * HALF + m * 16); gs[m] = *(const u32x4*)(proj + r * LDP + PGS + c); ga[m] = *(const u32x4*)(proj + r * LDP + PGA + c); }
; #pragma unroll
;                     for (int m = 0; m < 4; ++m) { float vs[8], va[8]; unpack8(gs[m], vs); unpack8(ga[m], va);
; #pragma unroll
;                         for (int e = 0; e < 4; ++e) {
;                             acc[ai][bj][m][0][e] *= (1.f + __expf(-(va[e] + a0[e]))) * __builtin_amdgcn_rcpf(1.f + __expf(-(vs[e] + s0[e])));
;                             acc[ai][bj][m][1][e] *= (1.f + __expf(-(va[4 + e] + a1[e]))) * __builtin_amdgcn_rcpf(1.f + __expf(-(vs[4 + e] + s1[e]))); } }
	v_lshlrev_b32_e32 v3, 16, v146
	v_add_f32_e32 v3, v158, v3
	v_exp_f32_e32 v189, v189
	v_mul_f32_e32 v3, 0xbfb8aa3b, v3
	v_exp_f32_e32 v3, v3
	v_pk_mul_f32 v[58:59], v[58:59], v[4:5]
	v_pk_add_f32 v[4:5], v[196:197], 1.0 op_sel_hi:[1,0]
	v_pk_add_f32 v[186:187], v[188:189], 1.0 op_sel_hi:[1,0]
	v_pk_mul_f32 v[4:5], v[4:5], v[198:199]
	v_pk_mul_f32 v[186:187], v[186:187], v[190:191]
	v_pk_mul_f32 v[56:57], v[56:57], v[4:5]
	v_and_b32_e32 v5, 0xffff0000, v146
	v_lshlrev_b32_e32 v146, 16, v148
	v_add_f32_e32 v3, 1.0, v3
	v_pk_mul_f32 v[54:55], v[54:55], v[186:187]
	v_lshlrev_b32_e32 v186, 16, v147
	v_and_b32_e32 v187, 0xffff0000, v147
	v_and_b32_e32 v147, 0xffff0000, v148
	s_waitcnt vmcnt(2)
	v_lshlrev_b32_e32 v4, 16, v142
	v_and_b32_e32 v148, 0xffff0000, v142
	v_rcp_f32_e32 v142, v3
	v_add_f32_e32 v3, v150, v146
	v_mul_f32_e32 v3, 0xbfb8aa3b, v3
	v_exp_f32_e32 v3, v3
	v_lshlrev_b32_e32 v188, 16, v149
	v_and_b32_e32 v189, 0xffff0000, v149
	v_lshlrev_b32_e32 v149, 16, v143
	v_add_f32_e32 v3, 1.0, v3
	v_rcp_f32_e32 v146, v3
	v_add_f32_e32 v3, v159, v5
	v_mul_f32_e32 v3, 0xbfb8aa3b, v3
	v_exp_f32_e32 v3, v3
	v_and_b32_e32 v190, 0xffff0000, v143
	v_lshlrev_b32_e32 v143, 16, v144
	v_add_f32_e32 v143, v154, v143
	v_mul_f32_e32 v143, 0xbfb8aa3b, v143
	v_add_f32_e32 v3, 1.0, v3
	v_and_b32_e32 v191, 0xffff0000, v144
	v_exp_f32_e32 v144, v143
	v_rcp_f32_e32 v143, v3
	v_add_f32_e32 v3, v151, v147
	v_mul_f32_e32 v3, 0xbfb8aa3b, v3
	v_exp_f32_e32 v3, v3
	v_add_f32_e32 v187, v161, v187
	v_lshlrev_b32_e32 v192, 16, v145
	v_mul_f32_e32 v187, 0xbfb8aa3b, v187
	v_add_f32_e32 v3, 1.0, v3
	v_rcp_f32_e32 v147, v3
	v_add_f32_e32 v3, v160, v186
	v_mul_f32_e32 v3, 0xbfb8aa3b, v3
	v_exp_f32_e32 v3, v3
	v_add_f32_e32 v5, v163, v148
	v_add_f32_e32 v148, v164, v149
	v_add_f32_e32 v149, v156, v192
	v_add_f32_e32 v3, 1.0, v3
	v_rcp_f32_e32 v186, v3
	v_add_f32_e32 v3, v152, v188
	v_mul_f32_e32 v3, 0xbfb8aa3b, v3
	v_exp_f32_e32 v3, v3
	v_exp_f32_e32 v187, v187
	v_mul_f32_e32 v149, 0xbfb8aa3b, v149
	v_add_f32_e32 v4, v162, v4
	v_exp_f32_e32 v188, v149
	v_add_f32_e32 v149, v165, v190
	v_mul_f32_e32 v4, 0xbfb8aa3b, v4
	v_mul_f32_e32 v5, 0xbfb8aa3b, v5
	v_mul_f32_e32 v148, 0xbfb8aa3b, v148
	v_add_f32_e32 v3, 1.0, v3
	v_mul_f32_e32 v149, 0xbfb8aa3b, v149
	v_exp_f32_e32 v4, v4
	v_exp_f32_e32 v5, v5
	v_exp_f32_e32 v148, v148
	v_exp_f32_e32 v149, v149
	v_rcp_f32_e32 v190, v3
	v_add_f32_e32 v3, 1.0, v187
	v_rcp_f32_e32 v187, v3
	v_pk_add_f32 v[148:149], v[148:149], 1.0 op_sel_hi:[1,0]
	v_pk_add_f32 v[4:5], v[4:5], 1.0 op_sel_hi:[1,0]
	v_and_b32_e32 v193, 0xffff0000, v145
	v_pk_mul_f32 v[4:5], v[4:5], v[142:143]
	v_pk_mul_f32 v[142:143], v[148:149], v[186:187]
	v_add_f32_e32 v3, v157, v193
	v_pk_mul_f32 v[52:53], v[52:53], v[142:143]
	v_add_f32_e32 v142, v153, v189
	v_mul_f32_e32 v142, 0xbfb8aa3b, v142
	v_mul_f32_e32 v3, 0xbfb8aa3b, v3
	v_exp_f32_e32 v142, v142
	v_exp_f32_e32 v189, v3
	v_pk_mul_f32 v[50:51], v[50:51], v[4:5]
	v_add_f32_e32 v3, 1.0, v142
	v_pk_add_f32 v[4:5], v[188:189], 1.0 op_sel_hi:[1,0]
	global_load_dwordx4 v[186:189], v[218:219], off offset:256
	v_add_f32_e32 v145, v155, v191
	v_rcp_f32_e32 v191, v3
	s_waitcnt vmcnt(2)
	v_lshlrev_b32_e32 v3, 16, v130
	v_mul_f32_e32 v145, 0xbfb8aa3b, v145
	v_add_f32_e32 v3, v158, v3
	v_exp_f32_e32 v145, v145
	v_mul_f32_e32 v3, 0xbfb8aa3b, v3
	v_exp_f32_e32 v3, v3
	v_pk_mul_f32 v[4:5], v[4:5], v[190:191]
	v_pk_add_f32 v[142:143], v[144:145], 1.0 op_sel_hi:[1,0]
	v_pk_mul_f32 v[48:49], v[48:49], v[4:5]
	v_pk_mul_f32 v[142:143], v[142:143], v[146:147]
	v_and_b32_e32 v5, 0xffff0000, v130
	v_lshlrev_b32_e32 v130, 16, v132
	v_add_f32_e32 v3, 1.0, v3
	v_pk_mul_f32 v[46:47], v[46:47], v[142:143]
	v_lshlrev_b32_e32 v142, 16, v131
	v_and_b32_e32 v143, 0xffff0000, v131
	v_and_b32_e32 v131, 0xffff0000, v132
	s_waitcnt vmcnt(1)
	v_lshlrev_b32_e32 v4, 16, v126
	v_and_b32_e32 v132, 0xffff0000, v126
	v_rcp_f32_e32 v126, v3
	v_add_f32_e32 v3, v150, v130
	v_mul_f32_e32 v3, 0xbfb8aa3b, v3
	v_exp_f32_e32 v3, v3
	global_load_dwordx4 v[190:193], v[216:217], off offset:256
	v_lshlrev_b32_e32 v144, 16, v133
	v_and_b32_e32 v145, 0xffff0000, v133
	v_add_f32_e32 v3, 1.0, v3
	v_rcp_f32_e32 v130, v3
	v_add_f32_e32 v3, v159, v5
	v_mul_f32_e32 v3, 0xbfb8aa3b, v3
	v_exp_f32_e32 v3, v3
	v_lshlrev_b32_e32 v133, 16, v127
	v_and_b32_e32 v146, 0xffff0000, v127
	v_lshlrev_b32_e32 v127, 16, v128
	v_add_f32_e32 v127, v154, v127
	v_mul_f32_e32 v127, 0xbfb8aa3b, v127
	v_add_f32_e32 v3, 1.0, v3
	v_and_b32_e32 v147, 0xffff0000, v128
	v_exp_f32_e32 v128, v127
	v_rcp_f32_e32 v127, v3
	v_add_f32_e32 v3, v151, v131
	v_mul_f32_e32 v3, 0xbfb8aa3b, v3
	v_exp_f32_e32 v3, v3
	v_add_f32_e32 v143, v161, v143
	v_lshlrev_b32_e32 v148, 16, v129
	v_mul_f32_e32 v143, 0xbfb8aa3b, v143
	v_add_f32_e32 v3, 1.0, v3
	v_rcp_f32_e32 v131, v3
	v_add_f32_e32 v3, v160, v142
	v_mul_f32_e32 v3, 0xbfb8aa3b, v3
	v_exp_f32_e32 v3, v3
	v_add_f32_e32 v5, v163, v132
	v_add_f32_e32 v132, v164, v133
	v_add_f32_e32 v133, v156, v148
	v_add_f32_e32 v3, 1.0, v3
	v_rcp_f32_e32 v142, v3
	v_add_f32_e32 v3, v152, v144
	v_mul_f32_e32 v3, 0xbfb8aa3b, v3
	v_exp_f32_e32 v3, v3
	v_exp_f32_e32 v143, v143
	v_mul_f32_e32 v133, 0xbfb8aa3b, v133
	v_add_f32_e32 v4, v162, v4
	v_exp_f32_e32 v144, v133
	v_add_f32_e32 v133, v165, v146
	v_mul_f32_e32 v4, 0xbfb8aa3b, v4
	v_mul_f32_e32 v5, 0xbfb8aa3b, v5
	v_mul_f32_e32 v132, 0xbfb8aa3b, v132
	v_add_f32_e32 v3, 1.0, v3
	v_mul_f32_e32 v133, 0xbfb8aa3b, v133
	v_exp_f32_e32 v4, v4
	v_exp_f32_e32 v5, v5
	v_exp_f32_e32 v132, v132
	v_exp_f32_e32 v133, v133
	v_rcp_f32_e32 v146, v3
	v_add_f32_e32 v3, 1.0, v143
	v_rcp_f32_e32 v143, v3
	v_pk_add_f32 v[132:133], v[132:133], 1.0 op_sel_hi:[1,0]
	v_pk_add_f32 v[4:5], v[4:5], 1.0 op_sel_hi:[1,0]
	v_and_b32_e32 v149, 0xffff0000, v129
	v_pk_mul_f32 v[4:5], v[4:5], v[126:127]
	v_pk_mul_f32 v[126:127], v[132:133], v[142:143]
	v_add_f32_e32 v129, v155, v147
	v_pk_mul_f32 v[44:45], v[44:45], v[126:127]
	v_add_f32_e32 v126, v153, v145
	v_mul_f32_e32 v126, 0xbfb8aa3b, v126
	v_exp_f32_e32 v126, v126
	v_mul_f32_e32 v129, 0xbfb8aa3b, v129
	v_add_f32_e32 v3, v157, v149
	v_exp_f32_e32 v129, v129
	v_mul_f32_e32 v3, 0xbfb8aa3b, v3
	v_exp_f32_e32 v145, v3
	v_add_f32_e32 v3, 1.0, v126
	v_rcp_f32_e32 v147, v3
	v_pk_add_f32 v[126:127], v[128:129], 1.0 op_sel_hi:[1,0]
	v_pk_mul_f32 v[42:43], v[42:43], v[4:5]
	v_pk_add_f32 v[4:5], v[144:145], 1.0 op_sel_hi:[1,0]
	v_pk_mul_f32 v[126:127], v[126:127], v[130:131]
	v_pk_mul_f32 v[4:5], v[4:5], v[146:147]
	v_pk_mul_f32 v[38:39], v[38:39], v[126:127]
	global_load_dwordx4 v[194:197], v[204:205], off offset:256
	global_load_dwordx4 v[198:201], v[206:207], off offset:256
	global_load_dwordx4 v[146:149], v[208:209], off offset:256
	global_load_dwordx4 v[142:145], v[210:211], off offset:256
	global_load_dwordx4 v[130:133], v[212:213], off offset:256
	global_load_dwordx4 v[126:129], v[214:215], off offset:256
	s_waitcnt vmcnt(7)
; __device__ __forceinline__ void unpack8(const u32x4 w, float (&v)[8]) { v[0] = bf_lo(w.x); v[1] = bf_hi(w.x); v[2] = bf_lo(w.y); v[3] = bf_hi(w.y); v[4] = bf_lo(w.z); v[5] = bf_hi(w.z); v[6] = bf_lo(w.w); v[7] = bf_hi(w.w); }
;     __device__ __forceinline__ void after(int te, f32x4 (&acc)[2][2][4][2], const Unit& u, int wr, int wc, int fr, int fq) const {
;     ...
;                     for (int m = 0; m < 4; ++m) { const size_t r = (size_t)(row0 + ai * HALF + m * 16); gs[m] = *(const u32x4*)(proj + r * LDP + PGS + c); ga[m] = *(const u32x4*)(proj + r * LDP + PGA + c); }
; #pragma unroll
;                     for (int m = 0; m < 4; ++m) { float vs[8], va[8]; unpack8(gs[m], vs); unpack8(ga[m], va);
; #pragma unroll
;                         for (int e = 0; e < 4; ++e) {
;                             acc[ai][bj][m][0][e] *= (1.f + __expf(-(va[e] + a0[e]))) * __builtin_amdgcn_rcpf(1.f + __expf(-(vs[e] + s0[e])));
;                             acc[ai][bj][m][1][e] *= (1.f + __expf(-(va[4 + e] + a1[e]))) * __builtin_amdgcn_rcpf(1.f + __expf(-(vs[4 + e] + s1[e]))); } }
	v_lshlrev_b32_e32 v3, 16, v186
	v_add_f32_e32 v3, v158, v3
	v_mul_f32_e32 v3, 0xbfb8aa3b, v3
	v_exp_f32_e32 v3, v3
	v_lshlrev_b32_e32 v202, 16, v187
	v_and_b32_e32 v203, 0xffff0000, v187
	v_lshlrev_b32_e32 v187, 16, v188
	v_add_f32_e32 v3, 1.0, v3
	v_pk_mul_f32 v[40:41], v[40:41], v[4:5]
	v_and_b32_e32 v5, 0xffff0000, v186
	v_rcp_f32_e32 v186, v3
	v_add_f32_e32 v3, v150, v187
	v_mul_f32_e32 v3, 0xbfb8aa3b, v3
	v_exp_f32_e32 v3, v3
	v_lshlrev_b32_e32 v205, 16, v189
	v_and_b32_e32 v207, 0xffff0000, v189
	s_waitcnt vmcnt(6)
	v_lshlrev_b32_e32 v4, 16, v190
	v_add_f32_e32 v3, 1.0, v3
	v_and_b32_e32 v189, 0xffff0000, v190
	v_rcp_f32_e32 v190, v3
	v_add_f32_e32 v3, v159, v5
	v_mul_f32_e32 v3, 0xbfb8aa3b, v3
	v_exp_f32_e32 v3, v3
	v_and_b32_e32 v204, 0xffff0000, v188
	v_lshlrev_b32_e32 v188, 16, v192
	v_add_f32_e32 v187, v154, v188
	v_mul_f32_e32 v187, 0xbfb8aa3b, v187
	v_add_f32_e32 v3, 1.0, v3
	v_exp_f32_e32 v188, v187
	v_rcp_f32_e32 v187, v3
	v_add_f32_e32 v3, v151, v204
	v_mul_f32_e32 v3, 0xbfb8aa3b, v3
	v_exp_f32_e32 v3, v3
	v_lshlrev_b32_e32 v206, 16, v191
	v_and_b32_e32 v208, 0xffff0000, v191
	v_and_b32_e32 v191, 0xffff0000, v192
	v_add_f32_e32 v3, 1.0, v3
	v_add_f32_e32 v5, v163, v189
	v_add_f32_e32 v189, v155, v191
	v_rcp_f32_e32 v191, v3
	v_add_f32_e32 v3, v160, v202
	v_mul_f32_e32 v3, 0xbfb8aa3b, v3
	v_exp_f32_e32 v3, v3
	v_add_f32_e32 v203, v161, v203
	v_lshlrev_b32_e32 v209, 16, v193
	v_mul_f32_e32 v203, 0xbfb8aa3b, v203
	v_add_f32_e32 v3, 1.0, v3
	v_rcp_f32_e32 v202, v3
	v_add_f32_e32 v3, v152, v205
	v_mul_f32_e32 v3, 0xbfb8aa3b, v3
	v_exp_f32_e32 v3, v3
	v_and_b32_e32 v210, 0xffff0000, v193
	v_add_f32_e32 v193, v156, v209
	v_exp_f32_e32 v203, v203
	v_mul_f32_e32 v193, 0xbfb8aa3b, v193
	v_add_f32_e32 v4, v162, v4
	v_add_f32_e32 v192, v164, v206
	v_exp_f32_e32 v204, v193
	v_add_f32_e32 v193, v165, v208
	v_mul_f32_e32 v4, 0xbfb8aa3b, v4
	v_mul_f32_e32 v5, 0xbfb8aa3b, v5
	v_mul_f32_e32 v192, 0xbfb8aa3b, v192
	v_add_f32_e32 v3, 1.0, v3
	v_mul_f32_e32 v193, 0xbfb8aa3b, v193
	v_exp_f32_e32 v4, v4
	v_exp_f32_e32 v5, v5
	v_exp_f32_e32 v192, v192
	v_exp_f32_e32 v193, v193
	v_rcp_f32_e32 v206, v3
	v_add_f32_e32 v3, 1.0, v203
	v_rcp_f32_e32 v203, v3
	v_pk_add_f32 v[192:193], v[192:193], 1.0 op_sel_hi:[1,0]
	v_pk_add_f32 v[4:5], v[4:5], 1.0 op_sel_hi:[1,0]
	v_add_f32_e32 v3, v157, v210
	v_pk_mul_f32 v[4:5], v[4:5], v[186:187]
	v_pk_mul_f32 v[186:187], v[192:193], v[202:203]
	v_mul_f32_e32 v3, 0xbfb8aa3b, v3
	v_pk_mul_f32 v[36:37], v[36:37], v[186:187]
	v_add_f32_e32 v186, v153, v207
	v_mul_f32_e32 v186, 0xbfb8aa3b, v186
	v_exp_f32_e32 v186, v186
	v_exp_f32_e32 v205, v3
	v_mul_f32_e32 v189, 0xbfb8aa3b, v189
	v_exp_f32_e32 v189, v189
	v_add_f32_e32 v3, 1.0, v186
	v_rcp_f32_e32 v207, v3
	s_waitcnt vmcnt(5)
	v_lshlrev_b32_e32 v3, 16, v194
	v_add_f32_e32 v3, v158, v3
	v_mul_f32_e32 v3, 0xbfb8aa3b, v3
	v_exp_f32_e32 v3, v3
	v_pk_add_f32 v[186:187], v[188:189], 1.0 op_sel_hi:[1,0]
	v_pk_mul_f32 v[34:35], v[34:35], v[4:5]
	v_pk_mul_f32 v[186:187], v[186:187], v[190:191]
	v_add_f32_e32 v3, 1.0, v3
	v_pk_mul_f32 v[30:31], v[30:31], v[186:187]
	v_lshlrev_b32_e32 v187, 16, v196
	v_rcp_f32_e32 v186, v3
	v_add_f32_e32 v3, v150, v187
	v_mul_f32_e32 v3, 0xbfb8aa3b, v3
	v_exp_f32_e32 v3, v3
	v_pk_add_f32 v[4:5], v[204:205], 1.0 op_sel_hi:[1,0]
	s_waitcnt vmcnt(4)
	v_lshlrev_b32_e32 v188, 16, v200
	v_pk_mul_f32 v[4:5], v[4:5], v[206:207]
	v_add_f32_e32 v3, 1.0, v3
	v_pk_mul_f32 v[32:33], v[32:33], v[4:5]
	v_and_b32_e32 v5, 0xffff0000, v194
	v_rcp_f32_e32 v190, v3
	v_add_f32_e32 v3, v159, v5
	v_mul_f32_e32 v3, 0xbfb8aa3b, v3
	v_exp_f32_e32 v3, v3
	v_add_f32_e32 v187, v154, v188
	v_and_b32_e32 v189, 0xffff0000, v196
	v_mul_f32_e32 v187, 0xbfb8aa3b, v187
	v_add_f32_e32 v3, 1.0, v3
	v_exp_f32_e32 v188, v187
	v_rcp_f32_e32 v187, v3
	v_add_f32_e32 v3, v151, v189
	v_mul_f32_e32 v3, 0xbfb8aa3b, v3
	v_exp_f32_e32 v3, v3
	v_lshlrev_b32_e32 v192, 16, v195
	v_and_b32_e32 v191, 0xffff0000, v198
	v_add_f32_e32 v5, v163, v191
	v_add_f32_e32 v3, 1.0, v3
	v_rcp_f32_e32 v191, v3
	v_add_f32_e32 v3, v160, v192
	v_mul_f32_e32 v3, 0xbfb8aa3b, v3
	v_exp_f32_e32 v3, v3
	v_and_b32_e32 v193, 0xffff0000, v195
	v_lshlrev_b32_e32 v195, 16, v197
	v_lshlrev_b32_e32 v194, 16, v199
	v_add_f32_e32 v3, 1.0, v3
	v_add_f32_e32 v192, v164, v194
	v_rcp_f32_e32 v194, v3
	v_add_f32_e32 v3, v152, v195
	v_mul_f32_e32 v3, 0xbfb8aa3b, v3
	v_add_f32_e32 v193, v161, v193
	v_lshlrev_b32_e32 v4, 16, v198
	v_and_b32_e32 v198, 0xffff0000, v199
	v_lshlrev_b32_e32 v199, 16, v201
	v_exp_f32_e32 v3, v3
	v_mul_f32_e32 v193, 0xbfb8aa3b, v193
	v_add_f32_e32 v195, v156, v199
	v_exp_f32_e32 v199, v193
	v_and_b32_e32 v196, 0xffff0000, v200
	v_mul_f32_e32 v195, 0xbfb8aa3b, v195
	v_add_f32_e32 v4, v162, v4
	v_add_f32_e32 v189, v155, v196
	v_exp_f32_e32 v196, v195
	v_add_f32_e32 v195, v165, v198
	v_mul_f32_e32 v4, 0xbfb8aa3b, v4
	v_mul_f32_e32 v5, 0xbfb8aa3b, v5
	v_mul_f32_e32 v192, 0xbfb8aa3b, v192
	v_add_f32_e32 v3, 1.0, v3
	v_mul_f32_e32 v193, 0xbfb8aa3b, v195
	v_exp_f32_e32 v4, v4
	v_exp_f32_e32 v5, v5
	v_exp_f32_e32 v192, v192
	v_exp_f32_e32 v193, v193
	v_rcp_f32_e32 v198, v3
	v_add_f32_e32 v3, 1.0, v199
	v_rcp_f32_e32 v195, v3
	v_pk_add_f32 v[192:193], v[192:193], 1.0 op_sel_hi:[1,0]
	v_pk_add_f32 v[4:5], v[4:5], 1.0 op_sel_hi:[1,0]
	v_and_b32_e32 v197, 0xffff0000, v197
	v_pk_mul_f32 v[4:5], v[4:5], v[186:187]
	v_pk_mul_f32 v[186:187], v[192:193], v[194:195]
	v_and_b32_e32 v200, 0xffff0000, v201
	v_pk_mul_f32 v[28:29], v[28:29], v[186:187]
	v_add_f32_e32 v186, v153, v197
	v_mul_f32_e32 v186, 0xbfb8aa3b, v186
	v_exp_f32_e32 v186, v186
	v_add_f32_e32 v3, v157, v200
	v_mul_f32_e32 v3, 0xbfb8aa3b, v3
	v_exp_f32_e32 v197, v3
	v_add_f32_e32 v3, 1.0, v186
	v_rcp_f32_e32 v199, v3
	s_waitcnt vmcnt(3)
; __device__ __forceinline__ void unpack8(const u32x4 w, float (&v)[8]) { v[0] = bf_lo(w.x); v[1] = bf_hi(w.x); v[2] = bf_lo(w.y); v[3] = bf_hi(w.y); v[4] = bf_lo(w.z); v[5] = bf_hi(w.z); v[6] = bf_lo(w.w); v[7] = bf_hi(w.w); }
;     __device__ __forceinline__ void after(int te, f32x4 (&acc)[2][2][4][2], const Unit& u, int wr, int wc, int fr, int fq) const {
;     ...
;                     for (int m = 0; m < 4; ++m) { const size_t r = (size_t)(row0 + ai * HALF + m * 16); gs[m] = *(const u32x4*)(proj + r * LDP + PGS + c); ga[m] = *(const u32x4*)(proj + r * LDP + PGA + c); }
; #pragma unroll
;                     for (int m = 0; m < 4; ++m) { float vs[8], va[8]; unpack8(gs[m], vs); unpack8(ga[m], va);
; #pragma unroll
;                         for (int e = 0; e < 4; ++e) {
;                             acc[ai][bj][m][0][e] *= (1.f + __expf(-(va[e] + a0[e]))) * __builtin_amdgcn_rcpf(1.f + __expf(-(vs[e] + s0[e])));
;                             acc[ai][bj][m][1][e] *= (1.f + __expf(-(va[4 + e] + a1[e]))) * __builtin_amdgcn_rcpf(1.f + __expf(-(vs[4 + e] + s1[e]))); } }
	v_lshlrev_b32_e32 v3, 16, v146
	v_mul_f32_e32 v189, 0xbfb8aa3b, v189
	v_add_f32_e32 v3, v158, v3
	v_exp_f32_e32 v189, v189
	v_mul_f32_e32 v3, 0xbfb8aa3b, v3
	v_exp_f32_e32 v3, v3
	v_pk_mul_f32 v[26:27], v[26:27], v[4:5]
	v_pk_add_f32 v[4:5], v[196:197], 1.0 op_sel_hi:[1,0]
	v_pk_add_f32 v[186:187], v[188:189], 1.0 op_sel_hi:[1,0]
	v_pk_mul_f32 v[4:5], v[4:5], v[198:199]
	v_pk_mul_f32 v[186:187], v[186:187], v[190:191]
	v_pk_mul_f32 v[24:25], v[24:25], v[4:5]
	v_and_b32_e32 v5, 0xffff0000, v146
	v_lshlrev_b32_e32 v146, 16, v148
	v_add_f32_e32 v3, 1.0, v3
	v_pk_mul_f32 v[22:23], v[22:23], v[186:187]
	v_lshlrev_b32_e32 v186, 16, v147
	v_and_b32_e32 v187, 0xffff0000, v147
	v_and_b32_e32 v147, 0xffff0000, v148
	s_waitcnt vmcnt(2)
	v_lshlrev_b32_e32 v4, 16, v142
	v_and_b32_e32 v148, 0xffff0000, v142
	v_rcp_f32_e32 v142, v3
	v_add_f32_e32 v3, v150, v146
	v_mul_f32_e32 v3, 0xbfb8aa3b, v3
	v_exp_f32_e32 v3, v3
	v_lshlrev_b32_e32 v188, 16, v149
	v_and_b32_e32 v189, 0xffff0000, v149
	v_lshlrev_b32_e32 v149, 16, v143
	v_add_f32_e32 v3, 1.0, v3
	v_rcp_f32_e32 v146, v3
	v_add_f32_e32 v3, v159, v5
	v_mul_f32_e32 v3, 0xbfb8aa3b, v3
	v_exp_f32_e32 v3, v3
	v_and_b32_e32 v190, 0xffff0000, v143
	v_lshlrev_b32_e32 v143, 16, v144
	v_add_f32_e32 v143, v154, v143
	v_mul_f32_e32 v143, 0xbfb8aa3b, v143
	v_add_f32_e32 v3, 1.0, v3
	v_and_b32_e32 v191, 0xffff0000, v144
	v_exp_f32_e32 v144, v143
	v_rcp_f32_e32 v143, v3
	v_add_f32_e32 v3, v151, v147
	v_mul_f32_e32 v3, 0xbfb8aa3b, v3
	v_exp_f32_e32 v3, v3
	v_add_f32_e32 v187, v161, v187
	v_lshlrev_b32_e32 v192, 16, v145
	v_mul_f32_e32 v187, 0xbfb8aa3b, v187
	v_add_f32_e32 v3, 1.0, v3
	v_rcp_f32_e32 v147, v3
	v_add_f32_e32 v3, v160, v186
	v_mul_f32_e32 v3, 0xbfb8aa3b, v3
	v_exp_f32_e32 v3, v3
	v_add_f32_e32 v5, v163, v148
	v_add_f32_e32 v148, v164, v149
	v_add_f32_e32 v149, v156, v192
	v_add_f32_e32 v3, 1.0, v3
	v_rcp_f32_e32 v186, v3
	v_add_f32_e32 v3, v152, v188
	v_mul_f32_e32 v3, 0xbfb8aa3b, v3
	v_exp_f32_e32 v3, v3
	v_exp_f32_e32 v187, v187
	v_mul_f32_e32 v149, 0xbfb8aa3b, v149
	v_add_f32_e32 v4, v162, v4
	v_exp_f32_e32 v188, v149
	v_add_f32_e32 v149, v165, v190
	v_mul_f32_e32 v4, 0xbfb8aa3b, v4
	v_mul_f32_e32 v5, 0xbfb8aa3b, v5
	v_mul_f32_e32 v148, 0xbfb8aa3b, v148
	v_add_f32_e32 v3, 1.0, v3
	v_mul_f32_e32 v149, 0xbfb8aa3b, v149
	v_exp_f32_e32 v4, v4
	v_exp_f32_e32 v5, v5
	v_exp_f32_e32 v148, v148
	v_exp_f32_e32 v149, v149
	v_rcp_f32_e32 v190, v3
	v_add_f32_e32 v3, 1.0, v187
	v_rcp_f32_e32 v187, v3
	v_pk_add_f32 v[148:149], v[148:149], 1.0 op_sel_hi:[1,0]
	v_pk_add_f32 v[4:5], v[4:5], 1.0 op_sel_hi:[1,0]
	v_and_b32_e32 v193, 0xffff0000, v145
	v_pk_mul_f32 v[4:5], v[4:5], v[142:143]
	v_pk_mul_f32 v[142:143], v[148:149], v[186:187]
	v_add_f32_e32 v3, v157, v193
	v_pk_mul_f32 v[20:21], v[20:21], v[142:143]
	v_add_f32_e32 v142, v153, v189
	v_mul_f32_e32 v142, 0xbfb8aa3b, v142
	v_exp_f32_e32 v142, v142
	v_mul_f32_e32 v3, 0xbfb8aa3b, v3
	v_exp_f32_e32 v189, v3
	v_add_f32_e32 v145, v155, v191
	v_add_f32_e32 v3, 1.0, v142
	v_rcp_f32_e32 v191, v3
	s_waitcnt vmcnt(1)
	v_lshlrev_b32_e32 v3, 16, v130
	v_mul_f32_e32 v145, 0xbfb8aa3b, v145
	v_add_f32_e32 v3, v158, v3
	v_exp_f32_e32 v145, v145
	v_mul_f32_e32 v3, 0xbfb8aa3b, v3
	v_exp_f32_e32 v3, v3
	v_pk_mul_f32 v[18:19], v[18:19], v[4:5]
	v_pk_add_f32 v[4:5], v[188:189], 1.0 op_sel_hi:[1,0]
	v_pk_add_f32 v[142:143], v[144:145], 1.0 op_sel_hi:[1,0]
	v_pk_mul_f32 v[4:5], v[4:5], v[190:191]
	v_pk_mul_f32 v[142:143], v[142:143], v[146:147]
	v_pk_mul_f32 v[16:17], v[16:17], v[4:5]
	v_and_b32_e32 v5, 0xffff0000, v130
	v_lshlrev_b32_e32 v130, 16, v132
	v_add_f32_e32 v3, 1.0, v3
	v_pk_mul_f32 v[14:15], v[14:15], v[142:143]
	v_lshlrev_b32_e32 v142, 16, v131
	v_and_b32_e32 v143, 0xffff0000, v131
	v_and_b32_e32 v131, 0xffff0000, v132
	s_waitcnt vmcnt(0)
	v_lshlrev_b32_e32 v4, 16, v126
	v_and_b32_e32 v132, 0xffff0000, v126
	v_rcp_f32_e32 v126, v3
	v_add_f32_e32 v3, v150, v130
	v_mul_f32_e32 v3, 0xbfb8aa3b, v3
	v_exp_f32_e32 v3, v3
	v_lshlrev_b32_e32 v144, 16, v133
	v_and_b32_e32 v145, 0xffff0000, v133
	v_lshlrev_b32_e32 v133, 16, v127
	v_add_f32_e32 v3, 1.0, v3
	v_rcp_f32_e32 v130, v3
	v_add_f32_e32 v3, v159, v5
	v_mul_f32_e32 v3, 0xbfb8aa3b, v3
	v_exp_f32_e32 v3, v3
	v_and_b32_e32 v146, 0xffff0000, v127
	v_lshlrev_b32_e32 v127, 16, v128
	v_add_f32_e32 v127, v154, v127
	v_mul_f32_e32 v127, 0xbfb8aa3b, v127
	v_add_f32_e32 v3, 1.0, v3
	v_and_b32_e32 v147, 0xffff0000, v128
	v_exp_f32_e32 v128, v127
	v_rcp_f32_e32 v127, v3
	v_add_f32_e32 v3, v151, v131
	v_mul_f32_e32 v3, 0xbfb8aa3b, v3
	v_exp_f32_e32 v3, v3
	v_add_f32_e32 v143, v161, v143
	v_lshlrev_b32_e32 v148, 16, v129
	v_mul_f32_e32 v143, 0xbfb8aa3b, v143
	v_add_f32_e32 v3, 1.0, v3
	v_rcp_f32_e32 v131, v3
	v_add_f32_e32 v3, v160, v142
	v_mul_f32_e32 v3, 0xbfb8aa3b, v3
	v_exp_f32_e32 v3, v3
	v_add_f32_e32 v5, v163, v132
	v_add_f32_e32 v132, v164, v133
	v_add_f32_e32 v133, v156, v148
	v_add_f32_e32 v3, 1.0, v3
	v_rcp_f32_e32 v142, v3
	v_add_f32_e32 v3, v152, v144
	v_mul_f32_e32 v3, 0xbfb8aa3b, v3
	v_exp_f32_e32 v3, v3
	v_exp_f32_e32 v143, v143
	v_mul_f32_e32 v133, 0xbfb8aa3b, v133
	v_add_f32_e32 v4, v162, v4
	v_exp_f32_e32 v144, v133
	v_add_f32_e32 v133, v165, v146
	v_mul_f32_e32 v4, 0xbfb8aa3b, v4
	v_mul_f32_e32 v5, 0xbfb8aa3b, v5
	v_mul_f32_e32 v132, 0xbfb8aa3b, v132
	v_add_f32_e32 v3, 1.0, v3
	v_mul_f32_e32 v133, 0xbfb8aa3b, v133
	v_exp_f32_e32 v4, v4
	v_exp_f32_e32 v5, v5
	v_exp_f32_e32 v132, v132
	v_exp_f32_e32 v133, v133
	v_rcp_f32_e32 v146, v3
	v_add_f32_e32 v3, 1.0, v143
	v_rcp_f32_e32 v143, v3
	v_pk_add_f32 v[132:133], v[132:133], 1.0 op_sel_hi:[1,0]
	v_pk_add_f32 v[4:5], v[4:5], 1.0 op_sel_hi:[1,0]
	v_and_b32_e32 v149, 0xffff0000, v129
	v_pk_mul_f32 v[4:5], v[4:5], v[126:127]
	v_pk_mul_f32 v[126:127], v[132:133], v[142:143]
	v_add_f32_e32 v129, v155, v147
	v_pk_mul_f32 v[12:13], v[12:13], v[126:127]
	v_add_f32_e32 v126, v153, v145
	v_mul_f32_e32 v126, 0xbfb8aa3b, v126
	v_exp_f32_e32 v126, v126
	v_add_f32_e32 v3, v157, v149
	v_mul_f32_e32 v129, 0xbfb8aa3b, v129
	v_mul_f32_e32 v3, 0xbfb8aa3b, v3
	v_exp_f32_e32 v129, v129
	v_exp_f32_e32 v145, v3
	v_add_f32_e32 v3, 1.0, v126
	v_rcp_f32_e32 v147, v3
	v_pk_mul_f32 v[10:11], v[10:11], v[4:5]
	v_pk_add_f32 v[4:5], v[144:145], 1.0 op_sel_hi:[1,0]
	v_pk_add_f32 v[126:127], v[128:129], 1.0 op_sel_hi:[1,0]
	v_pk_mul_f32 v[4:5], v[4:5], v[146:147]
	v_pk_mul_f32 v[126:127], v[126:127], v[130:131]
	v_pk_mul_f32 v[8:9], v[8:9], v[4:5]
	v_pk_mul_f32 v[6:7], v[6:7], v[126:127]

; #define PG8_STAGE(bufoff, gbase, voff) do { _Pragma("unroll") for (int _i = 0; _i < 2; ++_i) \
;         __builtin_amdgcn_global_load_lds((const unsigned*)((const char*)(gbase) + (voff)[_i]), (LAS unsigned*)(lds + (bufoff) + ldsw + _i * 8192), 16, 0, 0); } while (0)
; #define PG8_LDA(dst, b, h) do { _Pragma("unroll") for (int m = 0; m < 4; ++m) _Pragma("unroll") for (int k = 0; k < 2; ++k) dst[m][k] = *(const LAS bf16x8*)(lds + PG8_SA(b, h) + aoff + m * 2048 + k * 1024); } while (0)
; #define PG8_LDB(dst, b, h) do { _Pragma("unroll") for (int n = 0; n < 2; ++n) _Pragma("unroll") for (int k = 0; k < 2; ++k) dst[n][k] = *(const LAS bf16x8*)(lds + PG8_SB(b, h) + boff + n * 2048 + k * 1024); } while (0)
; #define PG8_MMA(ai, bj, At, Bt) do { __builtin_amdgcn_s_setprio(1); _Pragma("unroll") for (int m = 0; m < 4; ++m) _Pragma("unroll") for (int n = 0; n < 2; ++n) _Pragma("unroll") for (int k = 0; k < 2; ++k) \
;         acc[ai][bj][m][n] = __builtin_amdgcn_mfma_f32_16x16x32_bf16(Bt[n][k], At[m][k], acc[ai][bj][m][n], 0, 0, 0); __builtin_amdgcn_s_setprio(0); } while (0)
; #define PG8_WAIT_V(n) asm volatile("s_waitcnt vmcnt(" #n ")" ::: "memory")
; #define PG8_WAIT_L(n) asm volatile("s_waitcnt lgkmcnt(" #n ")" ::: "memory")
; #define PG8_BAR __builtin_amdgcn_s_barrier()
; #define PG8_SCHED __builtin_amdgcn_sched_barrier(0)
; template <class Epi, class Sched, bool ALIGN_EPI, class Hook = NoHook>
; __device__ __forceinline__ void gemm_phase(LAS unsigned char* lds, const Gemm g, const Sched& S, const Epi& E, const Hook& H = Hook()) {
;     ...
;             PG8_LDB(B0, 0, 0); PG8_LDB(B1, 0, 1); PG8_SCHED; PG8_LDA(At, 0, 0); PG8_STAGE(PG8_SA(1, 1), a1 + hA, voffA);
;             PG8_WAIT_V(8); PG8_WAIT_L(0); PG8_BAR; PG8_MMA(0, 0, At, B0); PG8_MMA(0, 1, At, B1); PG8_BAR; PG8_SCHED;
;             PG8_LDA(At, 0, 1); PG8_STAGE(PG8_SB(0, 0), b2, voffB); PG8_STAGE(PG8_SB(0, 1), b2 + hB, voffB); PG8_STAGE(PG8_SA(0, 0), a2, voffA);
;             PG8_WAIT_V(8); PG8_WAIT_L(0); PG8_BAR; PG8_MMA(1, 0, At, B0); PG8_MMA(1, 1, At, B1); PG8_BAR; PG8_SCHED;
.LBB0_850:
	ds_read_b128 v[146:149], v1
	ds_read_b128 v[150:153], v1 offset:1024
	s_add_u32 s20, s6, 0x87c00080
	s_addc_u32 s21, s7, -1
	s_cmp_lg_u32 s42, 60
	s_cselect_b32 s20, s20, 0
	s_cselect_b32 s21, s21, 0
	s_add_u32 s22, s2, s20
	s_addc_u32 s23, s3, s21
	s_add_u32 s20, s14, s20
	s_addc_u32 s21, s15, s21
	s_mov_b32 m0, s43
	ds_read_b128 v[154:157], v1 offset:2048
	ds_read_b128 v[158:161], v1 offset:3072
	ds_read_b128 v[162:165], v142
	ds_read_b128 v[166:169], v142 offset:1024
	ds_read_b128 v[170:173], v142 offset:2048
	ds_read_b128 v[174:177], v142 offset:3072
	v_lshl_add_u64 v[178:179], v[138:139], 0, s[6:7]
	global_load_lds_dwordx4 v[178:179], off
	ds_read_b128 v[186:189], v143
	ds_read_b128 v[190:193], v143 offset:1024
	ds_read_b128 v[194:197], v143 offset:2048
	ds_read_b128 v[198:201], v143 offset:3072
	ds_read_b128 v[202:205], v143 offset:4096
	ds_read_b128 v[206:209], v143 offset:5120
	ds_read_b128 v[210:213], v143 offset:6144
	ds_read_b128 v[214:217], v143 offset:7168
	v_lshl_add_u64 v[178:179], v[140:141], 0, s[6:7]
	s_mov_b32 m0, s44
	s_nop 0
	global_load_lds_dwordx4 v[178:179], off
	s_waitcnt vmcnt(8) lgkmcnt(0)
	s_barrier
	v_mfma_f32_16x16x32_bf16 v[54:57], v[146:149], v[186:189], v[54:57]
	v_mfma_f32_16x16x32_bf16 v[34:37], v[154:157], v[186:189], v[34:37]
	v_mfma_f32_16x16x32_bf16 v[42:45], v[146:149], v[194:197], v[42:45]
	v_mfma_f32_16x16x32_bf16 v[30:33], v[154:157], v[194:197], v[30:33]
	v_mfma_f32_16x16x32_bf16 v[62:65], v[146:149], v[202:205], v[62:65]
	v_mfma_f32_16x16x32_bf16 v[50:53], v[154:157], v[202:205], v[50:53]
	v_mfma_f32_16x16x32_bf16 v[78:81], v[146:149], v[210:213], v[78:81]
	v_mfma_f32_16x16x32_bf16 v[70:73], v[154:157], v[210:213], v[70:73]
	v_mfma_f32_16x16x32_bf16 v[54:57], v[150:153], v[190:193], v[54:57]
	v_mfma_f32_16x16x32_bf16 v[34:37], v[158:161], v[190:193], v[34:37]
	v_mfma_f32_16x16x32_bf16 v[42:45], v[150:153], v[198:201], v[42:45]
	v_mfma_f32_16x16x32_bf16 v[30:33], v[158:161], v[198:201], v[30:33]
	v_mfma_f32_16x16x32_bf16 v[62:65], v[150:153], v[206:209], v[62:65]
	v_mfma_f32_16x16x32_bf16 v[50:53], v[158:161], v[206:209], v[50:53]
	v_mfma_f32_16x16x32_bf16 v[78:81], v[150:153], v[214:217], v[78:81]
	v_mfma_f32_16x16x32_bf16 v[70:73], v[158:161], v[214:217], v[70:73]
	v_mfma_f32_16x16x32_bf16 v[10:13], v[162:165], v[186:189], v[10:13]
	v_mfma_f32_16x16x32_bf16 v[2:5], v[170:173], v[186:189], v[2:5]
	v_mfma_f32_16x16x32_bf16 v[14:17], v[162:165], v[194:197], v[14:17]
	v_mfma_f32_16x16x32_bf16 v[6:9], v[170:173], v[194:197], v[6:9]
	v_mfma_f32_16x16x32_bf16 v[22:25], v[162:165], v[202:205], v[22:25]
	v_mfma_f32_16x16x32_bf16 v[18:21], v[170:173], v[202:205], v[18:21]
	v_mfma_f32_16x16x32_bf16 v[38:41], v[162:165], v[210:213], v[38:41]
	v_mfma_f32_16x16x32_bf16 v[26:29], v[170:173], v[210:213], v[26:29]
	v_mfma_f32_16x16x32_bf16 v[10:13], v[166:169], v[190:193], v[10:13]
	v_mfma_f32_16x16x32_bf16 v[2:5], v[174:177], v[190:193], v[2:5]
	v_mfma_f32_16x16x32_bf16 v[14:17], v[166:169], v[198:201], v[14:17]
	v_mfma_f32_16x16x32_bf16 v[6:9], v[174:177], v[198:201], v[6:9]
	v_mfma_f32_16x16x32_bf16 v[22:25], v[166:169], v[206:209], v[22:25]
	v_mfma_f32_16x16x32_bf16 v[18:21], v[174:177], v[206:209], v[18:21]
	v_mfma_f32_16x16x32_bf16 v[38:41], v[166:169], v[214:217], v[38:41]
	v_mfma_f32_16x16x32_bf16 v[26:29], v[174:177], v[214:217], v[26:29]
	s_barrier
	s_mov_b32 m0, s45
	s_add_u32 s54, s20, 0x100000
	ds_read_b128 v[186:189], v143 offset:16384
	ds_read_b128 v[190:193], v143 offset:17408
	global_load_lds_dwordx4 v132, s[20:21]
	ds_read_b128 v[194:197], v143 offset:18432
	s_mov_b32 m0, s46
	s_addc_u32 s55, s21, 0
	global_load_lds_dwordx4 v136, s[20:21]
	ds_read_b128 v[198:201], v143 offset:19456
	s_mov_b32 m0, s47
	s_nop 0
	global_load_lds_dwordx4 v132, s[54:55]
	ds_read_b128 v[202:205], v143 offset:20480
	s_mov_b32 m0, s48
	s_nop 0
	global_load_lds_dwordx4 v136, s[54:55]
	ds_read_b128 v[206:209], v143 offset:21504
	s_add_u32 s58, s22, s4
	s_addc_u32 s59, s23, s5
	s_mov_b32 m0, s28
	s_nop 0
	global_load_lds_dwordx4 v130, s[22:23]
	ds_read_b128 v[210:213], v143 offset:22528
	s_mov_b32 m0, s29
	s_nop 0
	global_load_lds_dwordx4 v134, s[22:23]
	ds_read_b128 v[214:217], v143 offset:23552
	s_waitcnt vmcnt(8) lgkmcnt(0)
	s_barrier
	v_mfma_f32_16x16x32_bf16 v[94:97], v[146:149], v[186:189], v[94:97]
	v_mfma_f32_16x16x32_bf16 v[86:89], v[154:157], v[186:189], v[86:89]
	v_mfma_f32_16x16x32_bf16 v[102:105], v[146:149], v[194:197], v[102:105]
	v_mfma_f32_16x16x32_bf16 v[98:101], v[154:157], v[194:197], v[98:101]
	v_mfma_f32_16x16x32_bf16 v[110:113], v[146:149], v[202:205], v[110:113]
	v_mfma_f32_16x16x32_bf16 v[106:109], v[154:157], v[202:205], v[106:109]
	v_mfma_f32_16x16x32_bf16 v[126:129], v[146:149], v[210:213], v[126:129]
	v_mfma_f32_16x16x32_bf16 v[122:125], v[154:157], v[210:213], v[122:125]
	v_mfma_f32_16x16x32_bf16 v[94:97], v[150:153], v[190:193], v[94:97]
	v_mfma_f32_16x16x32_bf16 v[86:89], v[158:161], v[190:193], v[86:89]
	v_mfma_f32_16x16x32_bf16 v[102:105], v[150:153], v[198:201], v[102:105]
	v_mfma_f32_16x16x32_bf16 v[98:101], v[158:161], v[198:201], v[98:101]
	v_mfma_f32_16x16x32_bf16 v[110:113], v[150:153], v[206:209], v[110:113]
	v_mfma_f32_16x16x32_bf16 v[106:109], v[158:161], v[206:209], v[106:109]
	v_mfma_f32_16x16x32_bf16 v[126:129], v[150:153], v[214:217], v[126:129]
	v_mfma_f32_16x16x32_bf16 v[122:125], v[158:161], v[214:217], v[122:125]
	v_mfma_f32_16x16x32_bf16 v[58:61], v[162:165], v[186:189], v[58:61]
	v_mfma_f32_16x16x32_bf16 v[46:49], v[170:173], v[186:189], v[46:49]
	v_mfma_f32_16x16x32_bf16 v[74:77], v[162:165], v[194:197], v[74:77]
	v_mfma_f32_16x16x32_bf16 v[66:69], v[170:173], v[194:197], v[66:69]
	v_mfma_f32_16x16x32_bf16 v[90:93], v[162:165], v[202:205], v[90:93]
	v_mfma_f32_16x16x32_bf16 v[82:85], v[170:173], v[202:205], v[82:85]
	v_mfma_f32_16x16x32_bf16 v[118:121], v[162:165], v[210:213], v[118:121]
	v_mfma_f32_16x16x32_bf16 v[114:117], v[170:173], v[210:213], v[114:117]
	v_mfma_f32_16x16x32_bf16 v[58:61], v[166:169], v[190:193], v[58:61]
	v_mfma_f32_16x16x32_bf16 v[46:49], v[174:177], v[190:193], v[46:49]
	v_mfma_f32_16x16x32_bf16 v[74:77], v[166:169], v[198:201], v[74:77]
	v_mfma_f32_16x16x32_bf16 v[66:69], v[174:177], v[198:201], v[66:69]
	v_mfma_f32_16x16x32_bf16 v[90:93], v[166:169], v[206:209], v[90:93]
	v_mfma_f32_16x16x32_bf16 v[82:85], v[174:177], v[206:209], v[82:85]
	v_mfma_f32_16x16x32_bf16 v[118:121], v[166:169], v[214:217], v[118:121]
	v_mfma_f32_16x16x32_bf16 v[114:117], v[174:177], v[214:217], v[114:117]
	s_barrier
; #define PG8_STAGE(bufoff, gbase, voff) do { _Pragma("unroll") for (int _i = 0; _i < 2; ++_i) \
;         __builtin_amdgcn_global_load_lds((const unsigned*)((const char*)(gbase) + (voff)[_i]), (LAS unsigned*)(lds + (bufoff) + ldsw + _i * 8192), 16, 0, 0); } while (0)
; #define PG8_LDA(dst, b, h) do { _Pragma("unroll") for (int m = 0; m < 4; ++m) _Pragma("unroll") for (int k = 0; k < 2; ++k) dst[m][k] = *(const LAS bf16x8*)(lds + PG8_SA(b, h) + aoff + m * 2048 + k * 1024); } while (0)
; #define PG8_LDB(dst, b, h) do { _Pragma("unroll") for (int n = 0; n < 2; ++n) _Pragma("unroll") for (int k = 0; k < 2; ++k) dst[n][k] = *(const LAS bf16x8*)(lds + PG8_SB(b, h) + boff + n * 2048 + k * 1024); } while (0)
; #define PG8_MMA(ai, bj, At, Bt) do { __builtin_amdgcn_s_setprio(1); _Pragma("unroll") for (int m = 0; m < 4; ++m) _Pragma("unroll") for (int n = 0; n < 2; ++n) _Pragma("unroll") for (int k = 0; k < 2; ++k) \
;         acc[ai][bj][m][n] = __builtin_amdgcn_mfma_f32_16x16x32_bf16(Bt[n][k], At[m][k], acc[ai][bj][m][n], 0, 0, 0); __builtin_amdgcn_s_setprio(0); } while (0)
; #define PG8_WAIT_V(n) asm volatile("s_waitcnt vmcnt(" #n ")" ::: "memory")
; #define PG8_WAIT_L(n) asm volatile("s_waitcnt lgkmcnt(" #n ")" ::: "memory")
; #define PG8_BAR __builtin_amdgcn_s_barrier()
; #define PG8_SCHED __builtin_amdgcn_sched_barrier(0)
; template <class Epi, class Sched, bool ALIGN_EPI, class Hook = NoHook>
; __device__ __forceinline__ void gemm_phase(LAS unsigned char* lds, const Gemm g, const Sched& S, const Epi& E, const Hook& H = Hook()) {
;     ...
;             PG8_LDB(B0, 1, 0); PG8_LDB(B1, 1, 1); PG8_SCHED; PG8_LDA(At, 1, 0); PG8_STAGE(PG8_SA(0, 1), a2 + hA, voffA);
;             PG8_WAIT_V(8); PG8_WAIT_L(0); PG8_BAR; PG8_MMA(0, 0, At, B0); PG8_MMA(0, 1, At, B1); PG8_BAR; PG8_SCHED;
;             PG8_LDA(At, 1, 1); PG8_STAGE(PG8_SB(1, 0), b3, voffB); PG8_STAGE(PG8_SB(1, 1), b3 + hB, voffB); PG8_STAGE(PG8_SA(1, 0), a3, voffA);
;             PG8_WAIT_V(8); PG8_WAIT_L(0); PG8_BAR; PG8_MMA(1, 0, At, B0); PG8_MMA(1, 1, At, B1); PG8_BAR; PG8_SCHED;
;         }
	ds_read_b128 v[146:149], v144
	ds_read_b128 v[150:153], v144 offset:1024
	s_add_u32 s22, s22, 0x100000
	s_addc_u32 s23, s23, 0
	s_mov_b32 m0, s38
	s_nop 0
	global_load_lds_dwordx4 v130, s[22:23]
	ds_read_b128 v[154:157], v144 offset:2048
	ds_read_b128 v[158:161], v144 offset:3072
	ds_read_b128 v[162:165], v145
	ds_read_b128 v[166:169], v145 offset:1024
	ds_read_b128 v[170:173], v145 offset:2048
	ds_read_b128 v[174:177], v145 offset:3072
	ds_read_b128 v[186:189], v143 offset:32768
	s_mov_b32 m0, s39
	s_nop 0
	global_load_lds_dwordx4 v134, s[22:23]
	ds_read_b128 v[190:193], v143 offset:33792
	ds_read_b128 v[194:197], v143 offset:34816
	ds_read_b128 v[198:201], v143 offset:35840
	ds_read_b128 v[202:205], v143 offset:36864
	ds_read_b128 v[206:209], v143 offset:37888
	ds_read_b128 v[210:213], v143 offset:38912
	ds_read_b128 v[214:217], v143 offset:39936
	s_waitcnt vmcnt(8) lgkmcnt(0)
	s_barrier
	v_mfma_f32_16x16x32_bf16 v[54:57], v[146:149], v[186:189], v[54:57]
	v_mfma_f32_16x16x32_bf16 v[34:37], v[154:157], v[186:189], v[34:37]
	v_mfma_f32_16x16x32_bf16 v[42:45], v[146:149], v[194:197], v[42:45]
	v_mfma_f32_16x16x32_bf16 v[30:33], v[154:157], v[194:197], v[30:33]
	v_mfma_f32_16x16x32_bf16 v[62:65], v[146:149], v[202:205], v[62:65]
	v_mfma_f32_16x16x32_bf16 v[50:53], v[154:157], v[202:205], v[50:53]
	v_mfma_f32_16x16x32_bf16 v[78:81], v[146:149], v[210:213], v[78:81]
	v_mfma_f32_16x16x32_bf16 v[70:73], v[154:157], v[210:213], v[70:73]
	v_mfma_f32_16x16x32_bf16 v[54:57], v[150:153], v[190:193], v[54:57]
	v_mfma_f32_16x16x32_bf16 v[34:37], v[158:161], v[190:193], v[34:37]
	v_mfma_f32_16x16x32_bf16 v[42:45], v[150:153], v[198:201], v[42:45]
	v_mfma_f32_16x16x32_bf16 v[30:33], v[158:161], v[198:201], v[30:33]
	v_mfma_f32_16x16x32_bf16 v[62:65], v[150:153], v[206:209], v[62:65]
	v_mfma_f32_16x16x32_bf16 v[50:53], v[158:161], v[206:209], v[50:53]
	v_mfma_f32_16x16x32_bf16 v[78:81], v[150:153], v[214:217], v[78:81]
	v_mfma_f32_16x16x32_bf16 v[70:73], v[158:161], v[214:217], v[70:73]
	v_mfma_f32_16x16x32_bf16 v[10:13], v[162:165], v[186:189], v[10:13]
	v_mfma_f32_16x16x32_bf16 v[2:5], v[170:173], v[186:189], v[2:5]
	v_mfma_f32_16x16x32_bf16 v[14:17], v[162:165], v[194:197], v[14:17]
	v_mfma_f32_16x16x32_bf16 v[6:9], v[170:173], v[194:197], v[6:9]
	v_mfma_f32_16x16x32_bf16 v[22:25], v[162:165], v[202:205], v[22:25]
	v_mfma_f32_16x16x32_bf16 v[18:21], v[170:173], v[202:205], v[18:21]
	v_mfma_f32_16x16x32_bf16 v[38:41], v[162:165], v[210:213], v[38:41]
	v_mfma_f32_16x16x32_bf16 v[26:29], v[170:173], v[210:213], v[26:29]
	v_mfma_f32_16x16x32_bf16 v[10:13], v[166:169], v[190:193], v[10:13]
	v_mfma_f32_16x16x32_bf16 v[2:5], v[174:177], v[190:193], v[2:5]
	v_mfma_f32_16x16x32_bf16 v[14:17], v[166:169], v[198:201], v[14:17]
	v_mfma_f32_16x16x32_bf16 v[6:9], v[174:177], v[198:201], v[6:9]
	v_mfma_f32_16x16x32_bf16 v[22:25], v[166:169], v[206:209], v[22:25]
	v_mfma_f32_16x16x32_bf16 v[18:21], v[174:177], v[206:209], v[18:21]
	v_mfma_f32_16x16x32_bf16 v[38:41], v[166:169], v[214:217], v[38:41]
	v_mfma_f32_16x16x32_bf16 v[26:29], v[174:177], v[214:217], v[26:29]
	s_barrier
	s_mov_b32 m0, s49
	s_add_u32 s56, s20, s4
	s_addc_u32 s57, s21, s5
	s_add_u32 s20, s20, 0x100080
	ds_read_b128 v[186:189], v143 offset:49152
	ds_read_b128 v[190:193], v143 offset:50176
	global_load_lds_dwordx4 v132, s[56:57]
	ds_read_b128 v[194:197], v143 offset:51200
	s_mov_b32 m0, s50
	s_addc_u32 s21, s21, 0
	global_load_lds_dwordx4 v136, s[56:57]
	ds_read_b128 v[198:201], v143 offset:52224
	s_mov_b32 m0, s51
	s_nop 0
	global_load_lds_dwordx4 v132, s[20:21]
	ds_read_b128 v[202:205], v143 offset:53248
	s_mov_b32 m0, s52
	s_nop 0
	global_load_lds_dwordx4 v136, s[20:21]
	ds_read_b128 v[206:209], v143 offset:54272
	s_mov_b32 m0, s40
	s_nop 0
	global_load_lds_dwordx4 v130, s[58:59]
	ds_read_b128 v[210:213], v143 offset:55296
	s_mov_b32 m0, s41
	s_nop 0
	global_load_lds_dwordx4 v134, s[58:59]
	s_add_i32 s42, s42, 2
	s_add_u32 s6, s6, 0x100
	s_addc_u32 s7, s7, 0
	s_cmp_gt_u32 s42, 61
	ds_read_b128 v[214:217], v143 offset:56320
	s_waitcnt vmcnt(8) lgkmcnt(0)
	s_barrier
	v_mfma_f32_16x16x32_bf16 v[94:97], v[146:149], v[186:189], v[94:97]
	v_mfma_f32_16x16x32_bf16 v[86:89], v[154:157], v[186:189], v[86:89]
	v_mfma_f32_16x16x32_bf16 v[102:105], v[146:149], v[194:197], v[102:105]
	v_mfma_f32_16x16x32_bf16 v[98:101], v[154:157], v[194:197], v[98:101]
	v_mfma_f32_16x16x32_bf16 v[110:113], v[146:149], v[202:205], v[110:113]
	v_mfma_f32_16x16x32_bf16 v[106:109], v[154:157], v[202:205], v[106:109]
	v_mfma_f32_16x16x32_bf16 v[126:129], v[146:149], v[210:213], v[126:129]
	v_mfma_f32_16x16x32_bf16 v[122:125], v[154:157], v[210:213], v[122:125]
	v_mfma_f32_16x16x32_bf16 v[94:97], v[150:153], v[190:193], v[94:97]
	v_mfma_f32_16x16x32_bf16 v[86:89], v[158:161], v[190:193], v[86:89]
	v_mfma_f32_16x16x32_bf16 v[102:105], v[150:153], v[198:201], v[102:105]
	v_mfma_f32_16x16x32_bf16 v[98:101], v[158:161], v[198:201], v[98:101]
	v_mfma_f32_16x16x32_bf16 v[110:113], v[150:153], v[206:209], v[110:113]
	v_mfma_f32_16x16x32_bf16 v[106:109], v[158:161], v[206:209], v[106:109]
	v_mfma_f32_16x16x32_bf16 v[126:129], v[150:153], v[214:217], v[126:129]
	v_mfma_f32_16x16x32_bf16 v[122:125], v[158:161], v[214:217], v[122:125]
	v_mfma_f32_16x16x32_bf16 v[58:61], v[162:165], v[186:189], v[58:61]
	v_mfma_f32_16x16x32_bf16 v[46:49], v[170:173], v[186:189], v[46:49]
	v_mfma_f32_16x16x32_bf16 v[74:77], v[162:165], v[194:197], v[74:77]
	v_mfma_f32_16x16x32_bf16 v[66:69], v[170:173], v[194:197], v[66:69]
	v_mfma_f32_16x16x32_bf16 v[90:93], v[162:165], v[202:205], v[90:93]
	v_mfma_f32_16x16x32_bf16 v[82:85], v[170:173], v[202:205], v[82:85]
	v_mfma_f32_16x16x32_bf16 v[118:121], v[162:165], v[210:213], v[118:121]
	v_mfma_f32_16x16x32_bf16 v[114:117], v[170:173], v[210:213], v[114:117]
	v_mfma_f32_16x16x32_bf16 v[58:61], v[166:169], v[190:193], v[58:61]
	v_mfma_f32_16x16x32_bf16 v[46:49], v[174:177], v[190:193], v[46:49]
	v_mfma_f32_16x16x32_bf16 v[74:77], v[166:169], v[198:201], v[74:77]
	v_mfma_f32_16x16x32_bf16 v[66:69], v[174:177], v[198:201], v[66:69]
	v_mfma_f32_16x16x32_bf16 v[90:93], v[166:169], v[206:209], v[90:93]
	v_mfma_f32_16x16x32_bf16 v[82:85], v[174:177], v[206:209], v[82:85]
	v_mfma_f32_16x16x32_bf16 v[118:121], v[166:169], v[214:217], v[118:121]
	v_mfma_f32_16x16x32_bf16 v[114:117], v[174:177], v[214:217], v[114:117]
	s_barrier
	s_cbranch_scc0 .LBB0_850
	s_cmpk_lt_u32 s26, 0x100
	s_cbranch_scc0 .LBB0_853
	s_barrier

; #define PG8_STAGE(bufoff, gbase, voff) do { _Pragma("unroll") for (int _i = 0; _i < 2; ++_i) \
;         __builtin_amdgcn_global_load_lds((const unsigned*)((const char*)(gbase) + (voff)[_i]), (LAS unsigned*)(lds + (bufoff) + ldsw + _i * 8192), 16, 0, 0); } while (0)
; #define PG8_LDA(dst, b, h) do { _Pragma("unroll") for (int m = 0; m < 4; ++m) _Pragma("unroll") for (int k = 0; k < 2; ++k) dst[m][k] = *(const LAS bf16x8*)(lds + PG8_SA(b, h) + aoff + m * 2048 + k * 1024); } while (0)
; #define PG8_LDB(dst, b, h) do { _Pragma("unroll") for (int n = 0; n < 2; ++n) _Pragma("unroll") for (int k = 0; k < 2; ++k) dst[n][k] = *(const LAS bf16x8*)(lds + PG8_SB(b, h) + boff + n * 2048 + k * 1024); } while (0)
; #define PG8_MMA(ai, bj, At, Bt) do { __builtin_amdgcn_s_setprio(1); _Pragma("unroll") for (int m = 0; m < 4; ++m) _Pragma("unroll") for (int n = 0; n < 2; ++n) _Pragma("unroll") for (int k = 0; k < 2; ++k) \
;         acc[ai][bj][m][n] = __builtin_amdgcn_mfma_f32_16x16x32_bf16(Bt[n][k], At[m][k], acc[ai][bj][m][n], 0, 0, 0); __builtin_amdgcn_s_setprio(0); } while (0)
; #define PG8_WAIT_V(n) asm volatile("s_waitcnt vmcnt(" #n ")" ::: "memory")
; #define PG8_WAIT_L(n) asm volatile("s_waitcnt lgkmcnt(" #n ")" ::: "memory")
; #define PG8_BAR __builtin_amdgcn_s_barrier()
; #define PG8_SCHED __builtin_amdgcn_sched_barrier(0)
; template <class Epi, class Sched, bool ALIGN_EPI, class Hook = NoHook>
; __device__ __forceinline__ void gemm_phase(LAS unsigned char* lds, const Gemm g, const Sched& S, const Epi& E, const Hook& H = Hook()) {
;     ...
;             PG8_LDB(B0, 0, 0); PG8_LDB(B1, 0, 1); PG8_SCHED; PG8_LDA(At, 0, 0); PG8_STAGE(PG8_SA(1, 1), a1 + hA, voffA);
;             PG8_WAIT_V(8); PG8_WAIT_L(0); PG8_BAR; PG8_MMA(0, 0, At, B0); PG8_MMA(0, 1, At, B1); PG8_BAR; PG8_SCHED;
;             PG8_LDA(At, 0, 1); PG8_STAGE(PG8_SB(0, 0), b2, voffB); PG8_STAGE(PG8_SB(0, 1), b2 + hB, voffB); PG8_STAGE(PG8_SA(0, 0), a2, voffA);
;             PG8_WAIT_V(8); PG8_WAIT_L(0); PG8_BAR; PG8_MMA(1, 0, At, B0); PG8_MMA(1, 1, At, B1); PG8_BAR; PG8_SCHED;
.LBB0_896:
	ds_read_b128 v[146:149], v140
	ds_read_b128 v[150:153], v140 offset:1024
	s_add_u32 s10, s6, 0x87c00080
	s_addc_u32 s11, s7, -1
	s_cmp_lg_u32 s18, 60
	s_cselect_b32 s10, s10, 0
	s_cselect_b32 s11, s11, 0
	s_add_u32 s16, s2, s10
	s_addc_u32 s17, s3, s11
	s_add_u32 s10, s14, s10
	s_addc_u32 s11, s15, s11
	s_mov_b32 m0, s19
	ds_read_b128 v[154:157], v140 offset:2048
	ds_read_b128 v[158:161], v140 offset:3072
	ds_read_b128 v[162:165], v141
	ds_read_b128 v[166:169], v141 offset:1024
	ds_read_b128 v[170:173], v141 offset:2048
	ds_read_b128 v[174:177], v141 offset:3072
	v_lshl_add_u64 v[178:179], v[136:137], 0, s[6:7]
	global_load_lds_dwordx4 v[178:179], off
	ds_read_b128 v[186:189], v142
	ds_read_b128 v[190:193], v142 offset:1024
	ds_read_b128 v[194:197], v142 offset:2048
	ds_read_b128 v[198:201], v142 offset:3072
	ds_read_b128 v[202:205], v142 offset:4096
	ds_read_b128 v[206:209], v142 offset:5120
	ds_read_b128 v[210:213], v142 offset:6144
	ds_read_b128 v[214:217], v142 offset:7168
	v_lshl_add_u64 v[178:179], v[138:139], 0, s[6:7]
	s_mov_b32 m0, s31
	s_nop 0
	global_load_lds_dwordx4 v[178:179], off
	s_waitcnt vmcnt(8) lgkmcnt(0)
	s_barrier
	v_mfma_f32_16x16x32_bf16 v[54:57], v[146:149], v[186:189], v[54:57]
	v_mfma_f32_16x16x32_bf16 v[34:37], v[154:157], v[186:189], v[34:37]
	v_mfma_f32_16x16x32_bf16 v[42:45], v[146:149], v[194:197], v[42:45]
	v_mfma_f32_16x16x32_bf16 v[30:33], v[154:157], v[194:197], v[30:33]
	v_mfma_f32_16x16x32_bf16 v[62:65], v[146:149], v[202:205], v[62:65]
	v_mfma_f32_16x16x32_bf16 v[50:53], v[154:157], v[202:205], v[50:53]
	v_mfma_f32_16x16x32_bf16 v[78:81], v[146:149], v[210:213], v[78:81]
	v_mfma_f32_16x16x32_bf16 v[70:73], v[154:157], v[210:213], v[70:73]
	v_mfma_f32_16x16x32_bf16 v[54:57], v[150:153], v[190:193], v[54:57]
	v_mfma_f32_16x16x32_bf16 v[34:37], v[158:161], v[190:193], v[34:37]
	v_mfma_f32_16x16x32_bf16 v[42:45], v[150:153], v[198:201], v[42:45]
	v_mfma_f32_16x16x32_bf16 v[30:33], v[158:161], v[198:201], v[30:33]
	v_mfma_f32_16x16x32_bf16 v[62:65], v[150:153], v[206:209], v[62:65]
	v_mfma_f32_16x16x32_bf16 v[50:53], v[158:161], v[206:209], v[50:53]
	v_mfma_f32_16x16x32_bf16 v[78:81], v[150:153], v[214:217], v[78:81]
	v_mfma_f32_16x16x32_bf16 v[70:73], v[158:161], v[214:217], v[70:73]
	v_mfma_f32_16x16x32_bf16 v[10:13], v[162:165], v[186:189], v[10:13]
	v_mfma_f32_16x16x32_bf16 v[2:5], v[170:173], v[186:189], v[2:5]
	v_mfma_f32_16x16x32_bf16 v[14:17], v[162:165], v[194:197], v[14:17]
	v_mfma_f32_16x16x32_bf16 v[6:9], v[170:173], v[194:197], v[6:9]
	v_mfma_f32_16x16x32_bf16 v[22:25], v[162:165], v[202:205], v[22:25]
	v_mfma_f32_16x16x32_bf16 v[18:21], v[170:173], v[202:205], v[18:21]
	v_mfma_f32_16x16x32_bf16 v[38:41], v[162:165], v[210:213], v[38:41]
	v_mfma_f32_16x16x32_bf16 v[26:29], v[170:173], v[210:213], v[26:29]
	v_mfma_f32_16x16x32_bf16 v[10:13], v[166:169], v[190:193], v[10:13]
	v_mfma_f32_16x16x32_bf16 v[2:5], v[174:177], v[190:193], v[2:5]
	v_mfma_f32_16x16x32_bf16 v[14:17], v[166:169], v[198:201], v[14:17]
	v_mfma_f32_16x16x32_bf16 v[6:9], v[174:177], v[198:201], v[6:9]
	v_mfma_f32_16x16x32_bf16 v[22:25], v[166:169], v[206:209], v[22:25]
	v_mfma_f32_16x16x32_bf16 v[18:21], v[174:177], v[206:209], v[18:21]
	v_mfma_f32_16x16x32_bf16 v[38:41], v[166:169], v[214:217], v[38:41]
	v_mfma_f32_16x16x32_bf16 v[26:29], v[174:177], v[214:217], v[26:29]
	s_barrier
	s_mov_b32 m0, s33
	s_add_u32 s46, s10, 0x100000
	ds_read_b128 v[186:189], v142 offset:16384
	ds_read_b128 v[190:193], v142 offset:17408
	global_load_lds_dwordx4 v180, s[10:11]
	ds_read_b128 v[194:197], v142 offset:18432
	s_mov_b32 m0, s34
	s_addc_u32 s47, s11, 0
	global_load_lds_dwordx4 v134, s[10:11]
	ds_read_b128 v[198:201], v142 offset:19456
	s_mov_b32 m0, s35
	s_nop 0
	global_load_lds_dwordx4 v180, s[46:47]
	ds_read_b128 v[202:205], v142 offset:20480
	s_mov_b32 m0, s42
	s_nop 0
	global_load_lds_dwordx4 v134, s[46:47]
	ds_read_b128 v[206:209], v142 offset:21504
	s_add_u32 s50, s16, s4
	s_addc_u32 s51, s17, s5
	s_mov_b32 m0, s27
	s_nop 0
	global_load_lds_dwordx4 v130, s[16:17]
	ds_read_b128 v[210:213], v142 offset:22528
	s_mov_b32 m0, s28
	s_nop 0
	global_load_lds_dwordx4 v132, s[16:17]
	ds_read_b128 v[214:217], v142 offset:23552
	s_waitcnt vmcnt(8) lgkmcnt(0)
	s_barrier
	v_mfma_f32_16x16x32_bf16 v[94:97], v[146:149], v[186:189], v[94:97]
	v_mfma_f32_16x16x32_bf16 v[86:89], v[154:157], v[186:189], v[86:89]
	v_mfma_f32_16x16x32_bf16 v[102:105], v[146:149], v[194:197], v[102:105]
	v_mfma_f32_16x16x32_bf16 v[98:101], v[154:157], v[194:197], v[98:101]
	v_mfma_f32_16x16x32_bf16 v[110:113], v[146:149], v[202:205], v[110:113]
	v_mfma_f32_16x16x32_bf16 v[106:109], v[154:157], v[202:205], v[106:109]
	v_mfma_f32_16x16x32_bf16 v[126:129], v[146:149], v[210:213], v[126:129]
	v_mfma_f32_16x16x32_bf16 v[122:125], v[154:157], v[210:213], v[122:125]
	v_mfma_f32_16x16x32_bf16 v[94:97], v[150:153], v[190:193], v[94:97]
	v_mfma_f32_16x16x32_bf16 v[86:89], v[158:161], v[190:193], v[86:89]
	v_mfma_f32_16x16x32_bf16 v[102:105], v[150:153], v[198:201], v[102:105]
	v_mfma_f32_16x16x32_bf16 v[98:101], v[158:161], v[198:201], v[98:101]
	v_mfma_f32_16x16x32_bf16 v[110:113], v[150:153], v[206:209], v[110:113]
	v_mfma_f32_16x16x32_bf16 v[106:109], v[158:161], v[206:209], v[106:109]
	v_mfma_f32_16x16x32_bf16 v[126:129], v[150:153], v[214:217], v[126:129]
	v_mfma_f32_16x16x32_bf16 v[122:125], v[158:161], v[214:217], v[122:125]
	v_mfma_f32_16x16x32_bf16 v[58:61], v[162:165], v[186:189], v[58:61]
	v_mfma_f32_16x16x32_bf16 v[46:49], v[170:173], v[186:189], v[46:49]
	v_mfma_f32_16x16x32_bf16 v[74:77], v[162:165], v[194:197], v[74:77]
	v_mfma_f32_16x16x32_bf16 v[66:69], v[170:173], v[194:197], v[66:69]
	v_mfma_f32_16x16x32_bf16 v[90:93], v[162:165], v[202:205], v[90:93]
	v_mfma_f32_16x16x32_bf16 v[82:85], v[170:173], v[202:205], v[82:85]
	v_mfma_f32_16x16x32_bf16 v[118:121], v[162:165], v[210:213], v[118:121]
	v_mfma_f32_16x16x32_bf16 v[114:117], v[170:173], v[210:213], v[114:117]
	v_mfma_f32_16x16x32_bf16 v[58:61], v[166:169], v[190:193], v[58:61]
	v_mfma_f32_16x16x32_bf16 v[46:49], v[174:177], v[190:193], v[46:49]
	v_mfma_f32_16x16x32_bf16 v[74:77], v[166:169], v[198:201], v[74:77]
	v_mfma_f32_16x16x32_bf16 v[66:69], v[174:177], v[198:201], v[66:69]
	v_mfma_f32_16x16x32_bf16 v[90:93], v[166:169], v[206:209], v[90:93]
	v_mfma_f32_16x16x32_bf16 v[82:85], v[174:177], v[206:209], v[82:85]
	v_mfma_f32_16x16x32_bf16 v[118:121], v[166:169], v[214:217], v[118:121]
	v_mfma_f32_16x16x32_bf16 v[114:117], v[174:177], v[214:217], v[114:117]
	s_barrier
; #define PG8_STAGE(bufoff, gbase, voff) do { _Pragma("unroll") for (int _i = 0; _i < 2; ++_i) \
;         __builtin_amdgcn_global_load_lds((const unsigned*)((const char*)(gbase) + (voff)[_i]), (LAS unsigned*)(lds + (bufoff) + ldsw + _i * 8192), 16, 0, 0); } while (0)
; #define PG8_LDA(dst, b, h) do { _Pragma("unroll") for (int m = 0; m < 4; ++m) _Pragma("unroll") for (int k = 0; k < 2; ++k) dst[m][k] = *(const LAS bf16x8*)(lds + PG8_SA(b, h) + aoff + m * 2048 + k * 1024); } while (0)
; #define PG8_LDB(dst, b, h) do { _Pragma("unroll") for (int n = 0; n < 2; ++n) _Pragma("unroll") for (int k = 0; k < 2; ++k) dst[n][k] = *(const LAS bf16x8*)(lds + PG8_SB(b, h) + boff + n * 2048 + k * 1024); } while (0)
; #define PG8_MMA(ai, bj, At, Bt) do { __builtin_amdgcn_s_setprio(1); _Pragma("unroll") for (int m = 0; m < 4; ++m) _Pragma("unroll") for (int n = 0; n < 2; ++n) _Pragma("unroll") for (int k = 0; k < 2; ++k) \
;         acc[ai][bj][m][n] = __builtin_amdgcn_mfma_f32_16x16x32_bf16(Bt[n][k], At[m][k], acc[ai][bj][m][n], 0, 0, 0); __builtin_amdgcn_s_setprio(0); } while (0)
; #define PG8_WAIT_V(n) asm volatile("s_waitcnt vmcnt(" #n ")" ::: "memory")
; #define PG8_WAIT_L(n) asm volatile("s_waitcnt lgkmcnt(" #n ")" ::: "memory")
; #define PG8_BAR __builtin_amdgcn_s_barrier()
; #define PG8_SCHED __builtin_amdgcn_sched_barrier(0)
; template <class Epi, class Sched, bool ALIGN_EPI, class Hook = NoHook>
; __device__ __forceinline__ void gemm_phase(LAS unsigned char* lds, const Gemm g, const Sched& S, const Epi& E, const Hook& H = Hook()) {
;     ...
;             PG8_LDB(B0, 1, 0); PG8_LDB(B1, 1, 1); PG8_SCHED; PG8_LDA(At, 1, 0); PG8_STAGE(PG8_SA(0, 1), a2 + hA, voffA);
;             PG8_WAIT_V(8); PG8_WAIT_L(0); PG8_BAR; PG8_MMA(0, 0, At, B0); PG8_MMA(0, 1, At, B1); PG8_BAR; PG8_SCHED;
;             PG8_LDA(At, 1, 1); PG8_STAGE(PG8_SB(1, 0), b3, voffB); PG8_STAGE(PG8_SB(1, 1), b3 + hB, voffB); PG8_STAGE(PG8_SA(1, 0), a3, voffA);
;             PG8_WAIT_V(8); PG8_WAIT_L(0); PG8_BAR; PG8_MMA(1, 0, At, B0); PG8_MMA(1, 1, At, B1); PG8_BAR; PG8_SCHED;
;         }
	ds_read_b128 v[146:149], v143
	ds_read_b128 v[150:153], v143 offset:1024
	s_add_u32 s16, s16, 0x100000
	s_addc_u32 s17, s17, 0
	s_mov_b32 m0, s29
	s_nop 0
	global_load_lds_dwordx4 v130, s[16:17]
	ds_read_b128 v[154:157], v143 offset:2048
	ds_read_b128 v[158:161], v143 offset:3072
	ds_read_b128 v[162:165], v144
	ds_read_b128 v[166:169], v144 offset:1024
	ds_read_b128 v[170:173], v144 offset:2048
	ds_read_b128 v[174:177], v144 offset:3072
	ds_read_b128 v[186:189], v142 offset:32768
	s_mov_b32 m0, s39
	s_nop 0
	global_load_lds_dwordx4 v132, s[16:17]
	ds_read_b128 v[190:193], v142 offset:33792
	ds_read_b128 v[194:197], v142 offset:34816
	ds_read_b128 v[198:201], v142 offset:35840
	ds_read_b128 v[202:205], v142 offset:36864
	ds_read_b128 v[206:209], v142 offset:37888
	ds_read_b128 v[210:213], v142 offset:38912
	ds_read_b128 v[214:217], v142 offset:39936
	s_waitcnt vmcnt(8) lgkmcnt(0)
	s_barrier
	v_mfma_f32_16x16x32_bf16 v[54:57], v[146:149], v[186:189], v[54:57]
	v_mfma_f32_16x16x32_bf16 v[34:37], v[154:157], v[186:189], v[34:37]
	v_mfma_f32_16x16x32_bf16 v[42:45], v[146:149], v[194:197], v[42:45]
	v_mfma_f32_16x16x32_bf16 v[30:33], v[154:157], v[194:197], v[30:33]
	v_mfma_f32_16x16x32_bf16 v[62:65], v[146:149], v[202:205], v[62:65]
	v_mfma_f32_16x16x32_bf16 v[50:53], v[154:157], v[202:205], v[50:53]
	v_mfma_f32_16x16x32_bf16 v[78:81], v[146:149], v[210:213], v[78:81]
	v_mfma_f32_16x16x32_bf16 v[70:73], v[154:157], v[210:213], v[70:73]
	v_mfma_f32_16x16x32_bf16 v[54:57], v[150:153], v[190:193], v[54:57]
	v_mfma_f32_16x16x32_bf16 v[34:37], v[158:161], v[190:193], v[34:37]
	v_mfma_f32_16x16x32_bf16 v[42:45], v[150:153], v[198:201], v[42:45]
	v_mfma_f32_16x16x32_bf16 v[30:33], v[158:161], v[198:201], v[30:33]
	v_mfma_f32_16x16x32_bf16 v[62:65], v[150:153], v[206:209], v[62:65]
	v_mfma_f32_16x16x32_bf16 v[50:53], v[158:161], v[206:209], v[50:53]
	v_mfma_f32_16x16x32_bf16 v[78:81], v[150:153], v[214:217], v[78:81]
	v_mfma_f32_16x16x32_bf16 v[70:73], v[158:161], v[214:217], v[70:73]
	v_mfma_f32_16x16x32_bf16 v[10:13], v[162:165], v[186:189], v[10:13]
	v_mfma_f32_16x16x32_bf16 v[2:5], v[170:173], v[186:189], v[2:5]
	v_mfma_f32_16x16x32_bf16 v[14:17], v[162:165], v[194:197], v[14:17]
	v_mfma_f32_16x16x32_bf16 v[6:9], v[170:173], v[194:197], v[6:9]
	v_mfma_f32_16x16x32_bf16 v[22:25], v[162:165], v[202:205], v[22:25]
	v_mfma_f32_16x16x32_bf16 v[18:21], v[170:173], v[202:205], v[18:21]
	v_mfma_f32_16x16x32_bf16 v[38:41], v[162:165], v[210:213], v[38:41]
	v_mfma_f32_16x16x32_bf16 v[26:29], v[170:173], v[210:213], v[26:29]
	v_mfma_f32_16x16x32_bf16 v[10:13], v[166:169], v[190:193], v[10:13]
	v_mfma_f32_16x16x32_bf16 v[2:5], v[174:177], v[190:193], v[2:5]
	v_mfma_f32_16x16x32_bf16 v[14:17], v[166:169], v[198:201], v[14:17]
	v_mfma_f32_16x16x32_bf16 v[6:9], v[174:177], v[198:201], v[6:9]
	v_mfma_f32_16x16x32_bf16 v[22:25], v[166:169], v[206:209], v[22:25]
	v_mfma_f32_16x16x32_bf16 v[18:21], v[174:177], v[206:209], v[18:21]
	v_mfma_f32_16x16x32_bf16 v[38:41], v[166:169], v[214:217], v[38:41]
	v_mfma_f32_16x16x32_bf16 v[26:29], v[174:177], v[214:217], v[26:29]
	s_barrier
	s_mov_b32 m0, s36
	s_add_u32 s48, s10, s4
	s_addc_u32 s49, s11, s5
	s_add_u32 s10, s10, 0x100080
	ds_read_b128 v[186:189], v142 offset:49152
	ds_read_b128 v[190:193], v142 offset:50176
	global_load_lds_dwordx4 v180, s[48:49]
	ds_read_b128 v[194:197], v142 offset:51200
	s_mov_b32 m0, s43
	s_addc_u32 s11, s11, 0
	global_load_lds_dwordx4 v134, s[48:49]
	ds_read_b128 v[198:201], v142 offset:52224
	s_mov_b32 m0, s37
	s_nop 0
	global_load_lds_dwordx4 v180, s[10:11]
	ds_read_b128 v[202:205], v142 offset:53248
	s_mov_b32 m0, s44
	s_nop 0
	global_load_lds_dwordx4 v134, s[10:11]
	ds_read_b128 v[206:209], v142 offset:54272
	s_mov_b32 m0, s40
	s_nop 0
	global_load_lds_dwordx4 v130, s[50:51]
	ds_read_b128 v[210:213], v142 offset:55296
	s_mov_b32 m0, s41
	s_nop 0
	global_load_lds_dwordx4 v132, s[50:51]
	s_add_i32 s18, s18, 2
	s_add_u32 s6, s6, 0x100
	s_addc_u32 s7, s7, 0
	s_cmp_gt_u32 s18, 61
	ds_read_b128 v[214:217], v142 offset:56320
	s_waitcnt vmcnt(8) lgkmcnt(0)
	s_barrier
	v_mfma_f32_16x16x32_bf16 v[94:97], v[146:149], v[186:189], v[94:97]
	v_mfma_f32_16x16x32_bf16 v[86:89], v[154:157], v[186:189], v[86:89]
	v_mfma_f32_16x16x32_bf16 v[102:105], v[146:149], v[194:197], v[102:105]
	v_mfma_f32_16x16x32_bf16 v[98:101], v[154:157], v[194:197], v[98:101]
	v_mfma_f32_16x16x32_bf16 v[110:113], v[146:149], v[202:205], v[110:113]
	v_mfma_f32_16x16x32_bf16 v[106:109], v[154:157], v[202:205], v[106:109]
	v_mfma_f32_16x16x32_bf16 v[126:129], v[146:149], v[210:213], v[126:129]
	v_mfma_f32_16x16x32_bf16 v[122:125], v[154:157], v[210:213], v[122:125]
	v_mfma_f32_16x16x32_bf16 v[94:97], v[150:153], v[190:193], v[94:97]
	v_mfma_f32_16x16x32_bf16 v[86:89], v[158:161], v[190:193], v[86:89]
	v_mfma_f32_16x16x32_bf16 v[102:105], v[150:153], v[198:201], v[102:105]
	v_mfma_f32_16x16x32_bf16 v[98:101], v[158:161], v[198:201], v[98:101]
	v_mfma_f32_16x16x32_bf16 v[110:113], v[150:153], v[206:209], v[110:113]
	v_mfma_f32_16x16x32_bf16 v[106:109], v[158:161], v[206:209], v[106:109]
	v_mfma_f32_16x16x32_bf16 v[126:129], v[150:153], v[214:217], v[126:129]
	v_mfma_f32_16x16x32_bf16 v[122:125], v[158:161], v[214:217], v[122:125]
	v_mfma_f32_16x16x32_bf16 v[58:61], v[162:165], v[186:189], v[58:61]
	v_mfma_f32_16x16x32_bf16 v[46:49], v[170:173], v[186:189], v[46:49]
	v_mfma_f32_16x16x32_bf16 v[74:77], v[162:165], v[194:197], v[74:77]
	v_mfma_f32_16x16x32_bf16 v[66:69], v[170:173], v[194:197], v[66:69]
	v_mfma_f32_16x16x32_bf16 v[90:93], v[162:165], v[202:205], v[90:93]
	v_mfma_f32_16x16x32_bf16 v[82:85], v[170:173], v[202:205], v[82:85]
	v_mfma_f32_16x16x32_bf16 v[118:121], v[162:165], v[210:213], v[118:121]
	v_mfma_f32_16x16x32_bf16 v[114:117], v[170:173], v[210:213], v[114:117]
	v_mfma_f32_16x16x32_bf16 v[58:61], v[166:169], v[190:193], v[58:61]
	v_mfma_f32_16x16x32_bf16 v[46:49], v[174:177], v[190:193], v[46:49]
	v_mfma_f32_16x16x32_bf16 v[74:77], v[166:169], v[198:201], v[74:77]
	v_mfma_f32_16x16x32_bf16 v[66:69], v[174:177], v[198:201], v[66:69]
	v_mfma_f32_16x16x32_bf16 v[90:93], v[166:169], v[206:209], v[90:93]
	v_mfma_f32_16x16x32_bf16 v[82:85], v[174:177], v[206:209], v[82:85]
	v_mfma_f32_16x16x32_bf16 v[118:121], v[166:169], v[214:217], v[118:121]
	v_mfma_f32_16x16x32_bf16 v[114:117], v[174:177], v[214:217], v[114:117]
	s_barrier
	s_cbranch_scc0 .LBB0_896
	s_cmpk_lt_u32 s22, 0x100
	s_cbranch_scc0 .LBB0_899
	s_barrier

; #define PG8_STAGE(bufoff, gbase, voff) do { _Pragma("unroll") for (int _i = 0; _i < 2; ++_i) \
;         __builtin_amdgcn_global_load_lds((const unsigned*)((const char*)(gbase) + (voff)[_i]), (LAS unsigned*)(lds + (bufoff) + ldsw + _i * 8192), 16, 0, 0); } while (0)
; #define PG8_LDA(dst, b, h) do { _Pragma("unroll") for (int m = 0; m < 4; ++m) _Pragma("unroll") for (int k = 0; k < 2; ++k) dst[m][k] = *(const LAS bf16x8*)(lds + PG8_SA(b, h) + aoff + m * 2048 + k * 1024); } while (0)
; #define PG8_LDB(dst, b, h) do { _Pragma("unroll") for (int n = 0; n < 2; ++n) _Pragma("unroll") for (int k = 0; k < 2; ++k) dst[n][k] = *(const LAS bf16x8*)(lds + PG8_SB(b, h) + boff + n * 2048 + k * 1024); } while (0)
; #define PG8_MMA(ai, bj, At, Bt) do { __builtin_amdgcn_s_setprio(1); _Pragma("unroll") for (int m = 0; m < 4; ++m) _Pragma("unroll") for (int n = 0; n < 2; ++n) _Pragma("unroll") for (int k = 0; k < 2; ++k) \
;         acc[ai][bj][m][n] = __builtin_amdgcn_mfma_f32_16x16x32_bf16(Bt[n][k], At[m][k], acc[ai][bj][m][n], 0, 0, 0); __builtin_amdgcn_s_setprio(0); } while (0)
; #define PG8_WAIT_V(n) asm volatile("s_waitcnt vmcnt(" #n ")" ::: "memory")
; #define PG8_WAIT_L(n) asm volatile("s_waitcnt lgkmcnt(" #n ")" ::: "memory")
; #define PG8_BAR __builtin_amdgcn_s_barrier()
; #define PG8_SCHED __builtin_amdgcn_sched_barrier(0)
; template <class Epi, class Sched, bool ALIGN_EPI, class Hook = NoHook>
; __device__ __forceinline__ void gemm_phase(LAS unsigned char* lds, const Gemm g, const Sched& S, const Epi& E, const Hook& H = Hook()) {
;     ...
;             PG8_LDB(B0, 0, 0); PG8_LDB(B1, 0, 1); PG8_SCHED; PG8_LDA(At, 0, 0); PG8_STAGE(PG8_SA(1, 1), a1 + hA, voffA);
;             PG8_WAIT_V(8); PG8_WAIT_L(0); PG8_BAR; PG8_MMA(0, 0, At, B0); PG8_MMA(0, 1, At, B1); PG8_BAR; PG8_SCHED;
;             PG8_LDA(At, 0, 1); PG8_STAGE(PG8_SB(0, 0), b2, voffB); PG8_STAGE(PG8_SB(0, 1), b2 + hB, voffB); PG8_STAGE(PG8_SA(0, 0), a2, voffA);
;             PG8_WAIT_V(8); PG8_WAIT_L(0); PG8_BAR; PG8_MMA(1, 0, At, B0); PG8_MMA(1, 1, At, B1); PG8_BAR; PG8_SCHED;
.LBB0_1001:
	ds_read_b128 v[106:109], v246
	ds_read_b128 v[110:113], v246 offset:1024
	s_add_u32 s42, s6, 0x100
	s_addc_u32 s43, s7, 0
	s_cmp_eq_u32 s70, 60
	s_cselect_b32 s47, s35, s43
	s_cselect_b32 s46, s66, s42
	s_cselect_b32 s45, s31, s69
	s_cselect_b32 s44, s67, s68
	s_add_i32 m0, s51, 0xc000
	s_nop 0
	global_load_lds_dwordx4 v236, s[6:7]
	ds_read_b128 v[114:117], v246 offset:2048
	ds_read_b128 v[118:121], v246 offset:3072
	ds_read_b128 v[122:125], v247
	ds_read_b128 v[126:129], v247 offset:1024
	ds_read_b128 v[130:133], v247 offset:2048
	ds_read_b128 v[134:137], v247 offset:3072
	ds_read_b128 v[138:141], v248
	s_add_i32 m0, s51, 0xe000
	s_nop 0
	global_load_lds_dwordx4 v238, s[6:7]
	ds_read_b128 v[142:145], v248 offset:1024
	ds_read_b128 v[146:149], v248 offset:2048
	ds_read_b128 v[150:153], v248 offset:3072
	ds_read_b128 v[154:157], v248 offset:4096
	ds_read_b128 v[158:161], v248 offset:5120
	ds_read_b128 v[162:165], v248 offset:6144
	ds_read_b128 v[170:173], v248 offset:7168
	s_waitcnt vmcnt(8) lgkmcnt(0)
	s_barrier
	v_mfma_f32_16x16x32_bf16 v[190:193], v[106:109], v[138:141], v[190:193]
	v_mfma_f32_16x16x32_bf16 v[178:181], v[114:117], v[138:141], v[178:181]
	v_mfma_f32_16x16x32_bf16 v[182:185], v[106:109], v[146:149], v[182:185]
	v_mfma_f32_16x16x32_bf16 v[98:101], v[114:117], v[146:149], v[98:101]
	v_mfma_f32_16x16x32_bf16 v[102:105], v[106:109], v[154:157], v[102:105]
	v_mfma_f32_16x16x32_bf16 v[86:89], v[114:117], v[154:157], v[86:89]
	v_mfma_f32_16x16x32_bf16 v[78:81], v[106:109], v[162:165], v[78:81]
	v_mfma_f32_16x16x32_bf16 v[70:73], v[114:117], v[162:165], v[70:73]
	v_mfma_f32_16x16x32_bf16 v[190:193], v[110:113], v[142:145], v[190:193]
	v_mfma_f32_16x16x32_bf16 v[178:181], v[118:121], v[142:145], v[178:181]
	v_mfma_f32_16x16x32_bf16 v[182:185], v[110:113], v[150:153], v[182:185]
	v_mfma_f32_16x16x32_bf16 v[98:101], v[118:121], v[150:153], v[98:101]
	v_mfma_f32_16x16x32_bf16 v[102:105], v[110:113], v[158:161], v[102:105]
	v_mfma_f32_16x16x32_bf16 v[86:89], v[118:121], v[158:161], v[86:89]
	v_mfma_f32_16x16x32_bf16 v[78:81], v[110:113], v[170:173], v[78:81]
	v_mfma_f32_16x16x32_bf16 v[70:73], v[118:121], v[170:173], v[70:73]
	v_mfma_f32_16x16x32_bf16 v[186:189], v[122:125], v[138:141], v[186:189]
	v_mfma_f32_16x16x32_bf16 v[138:141], v[130:133], v[138:141], v[174:177]
	v_mfma_f32_16x16x32_bf16 v[94:97], v[130:133], v[146:149], v[94:97]
	v_mfma_f32_16x16x32_bf16 v[90:93], v[122:125], v[154:157], v[90:93]
	v_mfma_f32_16x16x32_bf16 v[82:85], v[130:133], v[154:157], v[82:85]
	v_mfma_f32_16x16x32_bf16 v[74:77], v[122:125], v[162:165], v[74:77]
	v_mfma_f32_16x16x32_bf16 v[66:69], v[130:133], v[162:165], v[66:69]
	v_mfma_f32_16x16x32_bf16 v[186:189], v[126:129], v[142:145], v[186:189]
	v_mfma_f32_16x16x32_bf16 v[138:141], v[134:137], v[142:145], v[138:141]
	v_mfma_f32_16x16x32_bf16 v[142:145], v[122:125], v[146:149], v[166:169]
	v_mfma_f32_16x16x32_bf16 v[94:97], v[134:137], v[150:153], v[94:97]
	v_mfma_f32_16x16x32_bf16 v[90:93], v[126:129], v[158:161], v[90:93]
	v_mfma_f32_16x16x32_bf16 v[82:85], v[134:137], v[158:161], v[82:85]
	v_mfma_f32_16x16x32_bf16 v[74:77], v[126:129], v[170:173], v[74:77]
	v_mfma_f32_16x16x32_bf16 v[66:69], v[134:137], v[170:173], v[66:69]
	v_mfma_f32_16x16x32_bf16 v[142:145], v[126:129], v[150:153], v[142:145]
	s_barrier
	s_add_i32 s6, s63, s29
	s_mov_b32 m0, s6
	ds_read_b128 v[146:149], v248 offset:16384
	ds_read_b128 v[150:153], v248 offset:17408
	global_load_lds_dwordx4 v232, s[44:45]
	ds_read_b128 v[154:157], v248 offset:18432
	s_add_i32 m0, s6, 0x2000
	s_add_u32 s6, s44, 0x100000
	s_addc_u32 s7, s45, 0
	s_add_i32 s71, s64, s29
	global_load_lds_dwordx4 v228, s[44:45]
	ds_read_b128 v[158:161], v248 offset:19456
	s_mov_b32 m0, s71
	s_nop 0
	global_load_lds_dwordx4 v232, s[6:7]
	ds_read_b128 v[162:165], v248 offset:20480
	s_add_i32 m0, s71, 0x2000
	s_nop 0
	global_load_lds_dwordx4 v228, s[6:7]
	ds_read_b128 v[166:169], v248 offset:21504
	s_mov_b32 m0, s51
	s_nop 0
	global_load_lds_dwordx4 v234, s[46:47]
	ds_read_b128 v[170:173], v248 offset:22528
	s_mov_b32 m0, s52
	s_nop 0
	global_load_lds_dwordx4 v230, s[46:47]
	ds_read_b128 v[174:177], v248 offset:23552
	s_waitcnt vmcnt(8) lgkmcnt(0)
	s_barrier
	v_mfma_f32_16x16x32_bf16 v[62:65], v[106:109], v[146:149], v[62:65]
	v_mfma_f32_16x16x32_bf16 v[54:57], v[114:117], v[146:149], v[54:57]
	v_mfma_f32_16x16x32_bf16 v[46:49], v[106:109], v[154:157], v[46:49]
	v_mfma_f32_16x16x32_bf16 v[22:25], v[114:117], v[154:157], v[22:25]
	v_mfma_f32_16x16x32_bf16 v[42:45], v[106:109], v[162:165], v[42:45]
	v_mfma_f32_16x16x32_bf16 v[10:13], v[114:117], v[162:165], v[10:13]
	v_mfma_f32_16x16x32_bf16 v[38:41], v[106:109], v[170:173], v[38:41]
	v_mfma_f32_16x16x32_bf16 v[14:17], v[114:117], v[170:173], v[14:17]
	v_mfma_f32_16x16x32_bf16 v[62:65], v[110:113], v[150:153], v[62:65]
	v_mfma_f32_16x16x32_bf16 v[54:57], v[118:121], v[150:153], v[54:57]
	v_mfma_f32_16x16x32_bf16 v[46:49], v[110:113], v[158:161], v[46:49]
	v_mfma_f32_16x16x32_bf16 v[22:25], v[118:121], v[158:161], v[22:25]
	v_mfma_f32_16x16x32_bf16 v[42:45], v[110:113], v[166:169], v[42:45]
	v_mfma_f32_16x16x32_bf16 v[10:13], v[118:121], v[166:169], v[10:13]
	v_mfma_f32_16x16x32_bf16 v[38:41], v[110:113], v[174:177], v[38:41]
	v_mfma_f32_16x16x32_bf16 v[14:17], v[118:121], v[174:177], v[14:17]
	v_mfma_f32_16x16x32_bf16 v[58:61], v[122:125], v[146:149], v[58:61]
	v_mfma_f32_16x16x32_bf16 v[50:53], v[130:133], v[146:149], v[50:53]
	v_mfma_f32_16x16x32_bf16 v[34:37], v[122:125], v[154:157], v[34:37]
	v_mfma_f32_16x16x32_bf16 v[18:21], v[130:133], v[154:157], v[18:21]
	v_mfma_f32_16x16x32_bf16 v[30:33], v[122:125], v[162:165], v[30:33]
	v_mfma_f32_16x16x32_bf16 v[2:5], v[130:133], v[162:165], v[2:5]
	v_mfma_f32_16x16x32_bf16 v[26:29], v[122:125], v[170:173], v[26:29]
	v_mfma_f32_16x16x32_bf16 v[6:9], v[130:133], v[170:173], v[6:9]
	v_mfma_f32_16x16x32_bf16 v[58:61], v[126:129], v[150:153], v[58:61]
	v_mfma_f32_16x16x32_bf16 v[50:53], v[134:137], v[150:153], v[50:53]
	v_mfma_f32_16x16x32_bf16 v[34:37], v[126:129], v[158:161], v[34:37]
	v_mfma_f32_16x16x32_bf16 v[18:21], v[134:137], v[158:161], v[18:21]
	v_mfma_f32_16x16x32_bf16 v[30:33], v[126:129], v[166:169], v[30:33]
	v_mfma_f32_16x16x32_bf16 v[2:5], v[134:137], v[166:169], v[2:5]
	v_mfma_f32_16x16x32_bf16 v[26:29], v[126:129], v[174:177], v[26:29]
	v_mfma_f32_16x16x32_bf16 v[6:9], v[134:137], v[174:177], v[6:9]
	s_barrier
; #define PG8_STAGE(bufoff, gbase, voff) do { _Pragma("unroll") for (int _i = 0; _i < 2; ++_i) \
;         __builtin_amdgcn_global_load_lds((const unsigned*)((const char*)(gbase) + (voff)[_i]), (LAS unsigned*)(lds + (bufoff) + ldsw + _i * 8192), 16, 0, 0); } while (0)
; #define PG8_LDA(dst, b, h) do { _Pragma("unroll") for (int m = 0; m < 4; ++m) _Pragma("unroll") for (int k = 0; k < 2; ++k) dst[m][k] = *(const LAS bf16x8*)(lds + PG8_SA(b, h) + aoff + m * 2048 + k * 1024); } while (0)
; #define PG8_LDB(dst, b, h) do { _Pragma("unroll") for (int n = 0; n < 2; ++n) _Pragma("unroll") for (int k = 0; k < 2; ++k) dst[n][k] = *(const LAS bf16x8*)(lds + PG8_SB(b, h) + boff + n * 2048 + k * 1024); } while (0)
; #define PG8_MMA(ai, bj, At, Bt) do { __builtin_amdgcn_s_setprio(1); _Pragma("unroll") for (int m = 0; m < 4; ++m) _Pragma("unroll") for (int n = 0; n < 2; ++n) _Pragma("unroll") for (int k = 0; k < 2; ++k) \
;         acc[ai][bj][m][n] = __builtin_amdgcn_mfma_f32_16x16x32_bf16(Bt[n][k], At[m][k], acc[ai][bj][m][n], 0, 0, 0); __builtin_amdgcn_s_setprio(0); } while (0)
; #define PG8_WAIT_V(n) asm volatile("s_waitcnt vmcnt(" #n ")" ::: "memory")
; #define PG8_WAIT_L(n) asm volatile("s_waitcnt lgkmcnt(" #n ")" ::: "memory")
; #define PG8_BAR __builtin_amdgcn_s_barrier()
; #define PG8_SCHED __builtin_amdgcn_sched_barrier(0)
; template <class Epi, class Sched, bool ALIGN_EPI, class Hook = NoHook>
; __device__ __forceinline__ void gemm_phase(LAS unsigned char* lds, const Gemm g, const Sched& S, const Epi& E, const Hook& H = Hook()) {
;     ...
;             PG8_LDB(B0, 1, 0); PG8_LDB(B1, 1, 1); PG8_SCHED; PG8_LDA(At, 1, 0); PG8_STAGE(PG8_SA(0, 1), a2 + hA, voffA);
;             PG8_WAIT_V(8); PG8_WAIT_L(0); PG8_BAR; PG8_MMA(0, 0, At, B0); PG8_MMA(0, 1, At, B1); PG8_BAR; PG8_SCHED;
;             PG8_LDA(At, 1, 1); PG8_STAGE(PG8_SB(1, 0), b3, voffB); PG8_STAGE(PG8_SB(1, 1), b3 + hB, voffB); PG8_STAGE(PG8_SA(1, 0), a3, voffA);
;             PG8_WAIT_V(8); PG8_WAIT_L(0); PG8_BAR; PG8_MMA(1, 0, At, B0); PG8_MMA(1, 1, At, B1); PG8_BAR; PG8_SCHED;
;         }
	s_add_i32 s71, 0, 0x18000
	s_add_i32 s72, 0, 0x1c000
	v_add_u32_e32 v118, s71, v245
	v_add_u32_e32 v134, s72, v245
	ds_read_b128 v[106:109], v118
	ds_read_b128 v[110:113], v118 offset:1024
	s_add_u32 s6, s46, 0x8000
	s_addc_u32 s7, s47, 0
	s_mov_b32 m0, s53
	s_nop 0
	global_load_lds_dwordx4 v234, s[6:7]
	ds_read_b128 v[114:117], v118 offset:2048
	ds_read_b128 v[118:121], v118 offset:3072
	ds_read_b128 v[122:125], v134
	ds_read_b128 v[126:129], v134 offset:1024
	ds_read_b128 v[130:133], v134 offset:2048
	ds_read_b128 v[134:137], v134 offset:3072
	ds_read_b128 v[146:149], v248 offset:32768
	s_mov_b32 m0, s54
	s_nop 0
	global_load_lds_dwordx4 v230, s[6:7]
	ds_read_b128 v[150:153], v248 offset:33792
	ds_read_b128 v[154:157], v248 offset:34816
	ds_read_b128 v[158:161], v248 offset:35840
	ds_read_b128 v[162:165], v248 offset:36864
	ds_read_b128 v[170:173], v248 offset:37888
	ds_read_b128 v[194:197], v248 offset:38912
	ds_read_b128 v[198:201], v248 offset:39936
	s_waitcnt vmcnt(8) lgkmcnt(0)
	s_barrier
	v_mfma_f32_16x16x32_bf16 v[166:169], v[106:109], v[146:149], v[190:193]
	v_mfma_f32_16x16x32_bf16 v[190:193], v[110:113], v[150:153], v[166:169]
	v_mfma_f32_16x16x32_bf16 v[166:169], v[114:117], v[146:149], v[178:181]
	v_mfma_f32_16x16x32_bf16 v[178:181], v[118:121], v[150:153], v[166:169]
	v_mfma_f32_16x16x32_bf16 v[166:169], v[106:109], v[154:157], v[182:185]
	v_mfma_f32_16x16x32_bf16 v[98:101], v[114:117], v[154:157], v[98:101]
	v_mfma_f32_16x16x32_bf16 v[102:105], v[106:109], v[162:165], v[102:105]
	v_mfma_f32_16x16x32_bf16 v[86:89], v[114:117], v[162:165], v[86:89]
	v_mfma_f32_16x16x32_bf16 v[78:81], v[106:109], v[194:197], v[78:81]
	v_mfma_f32_16x16x32_bf16 v[70:73], v[114:117], v[194:197], v[70:73]
	v_mfma_f32_16x16x32_bf16 v[182:185], v[110:113], v[158:161], v[166:169]
	v_mfma_f32_16x16x32_bf16 v[98:101], v[118:121], v[158:161], v[98:101]
	v_mfma_f32_16x16x32_bf16 v[102:105], v[110:113], v[170:173], v[102:105]
	v_mfma_f32_16x16x32_bf16 v[86:89], v[118:121], v[170:173], v[86:89]
	v_mfma_f32_16x16x32_bf16 v[78:81], v[110:113], v[198:201], v[78:81]
	v_mfma_f32_16x16x32_bf16 v[70:73], v[118:121], v[198:201], v[70:73]
	v_mfma_f32_16x16x32_bf16 v[138:141], v[130:133], v[146:149], v[138:141]
	v_mfma_f32_16x16x32_bf16 v[166:169], v[122:125], v[146:149], v[186:189]
	v_mfma_f32_16x16x32_bf16 v[174:177], v[134:137], v[150:153], v[138:141]
	v_mfma_f32_16x16x32_bf16 v[138:141], v[122:125], v[154:157], v[142:145]
	v_mfma_f32_16x16x32_bf16 v[94:97], v[130:133], v[154:157], v[94:97]
	v_mfma_f32_16x16x32_bf16 v[90:93], v[122:125], v[162:165], v[90:93]
	v_mfma_f32_16x16x32_bf16 v[82:85], v[130:133], v[162:165], v[82:85]
	v_mfma_f32_16x16x32_bf16 v[74:77], v[122:125], v[194:197], v[74:77]
	v_mfma_f32_16x16x32_bf16 v[66:69], v[130:133], v[194:197], v[66:69]
	v_mfma_f32_16x16x32_bf16 v[186:189], v[126:129], v[150:153], v[166:169]
	v_mfma_f32_16x16x32_bf16 v[166:169], v[126:129], v[158:161], v[138:141]
	v_mfma_f32_16x16x32_bf16 v[94:97], v[134:137], v[158:161], v[94:97]
	v_mfma_f32_16x16x32_bf16 v[90:93], v[126:129], v[170:173], v[90:93]
	v_mfma_f32_16x16x32_bf16 v[82:85], v[134:137], v[170:173], v[82:85]
	v_mfma_f32_16x16x32_bf16 v[74:77], v[126:129], v[198:201], v[74:77]
	v_mfma_f32_16x16x32_bf16 v[66:69], v[134:137], v[198:201], v[66:69]
	s_barrier
	s_add_i32 s6, s71, s29
	s_add_u32 s74, s44, s14
	s_addc_u32 s75, s45, s15
	s_mov_b32 m0, s6
	ds_read_b128 v[138:141], v248 offset:49152
	ds_read_b128 v[142:145], v248 offset:50176
	global_load_lds_dwordx4 v232, s[74:75]
	ds_read_b128 v[146:149], v248 offset:51200
	s_add_i32 m0, s6, 0x2000
	s_add_u32 s6, s44, 0x100080
	s_addc_u32 s7, s45, 0
	s_add_i32 s44, s72, s29
	global_load_lds_dwordx4 v228, s[74:75]
	ds_read_b128 v[150:153], v248 offset:52224
	s_mov_b32 m0, s44
	s_nop 0
	global_load_lds_dwordx4 v232, s[6:7]
	ds_read_b128 v[154:157], v248 offset:53248
	s_add_i32 m0, s44, 0x2000
	s_nop 0
	global_load_lds_dwordx4 v228, s[6:7]
	ds_read_b128 v[158:161], v248 offset:54272
	s_add_u32 s78, s46, s14
	s_addc_u32 s79, s47, s15
	s_mov_b32 m0, s57
	s_nop 0
	global_load_lds_dwordx4 v234, s[78:79]
	ds_read_b128 v[162:165], v248 offset:55296
	s_mov_b32 m0, s58
	s_nop 0
	global_load_lds_dwordx4 v230, s[78:79]
	s_add_i32 s70, s70, 2
	s_add_u32 s68, s68, 0x100
	s_addc_u32 s69, s69, 0
	s_cmp_gt_u32 s70, 61
	s_mov_b64 s[6:7], s[42:43]
	ds_read_b128 v[170:173], v248 offset:56320
	s_waitcnt vmcnt(8) lgkmcnt(0)
	s_barrier
	v_mfma_f32_16x16x32_bf16 v[62:65], v[106:109], v[138:141], v[62:65]
	v_mfma_f32_16x16x32_bf16 v[54:57], v[114:117], v[138:141], v[54:57]
	v_mfma_f32_16x16x32_bf16 v[46:49], v[106:109], v[146:149], v[46:49]
	v_mfma_f32_16x16x32_bf16 v[22:25], v[114:117], v[146:149], v[22:25]
	v_mfma_f32_16x16x32_bf16 v[42:45], v[106:109], v[154:157], v[42:45]
	v_mfma_f32_16x16x32_bf16 v[10:13], v[114:117], v[154:157], v[10:13]
	v_mfma_f32_16x16x32_bf16 v[38:41], v[106:109], v[162:165], v[38:41]
	v_mfma_f32_16x16x32_bf16 v[14:17], v[114:117], v[162:165], v[14:17]
	v_mfma_f32_16x16x32_bf16 v[62:65], v[110:113], v[142:145], v[62:65]
	v_mfma_f32_16x16x32_bf16 v[54:57], v[118:121], v[142:145], v[54:57]
	v_mfma_f32_16x16x32_bf16 v[46:49], v[110:113], v[150:153], v[46:49]
	v_mfma_f32_16x16x32_bf16 v[22:25], v[118:121], v[150:153], v[22:25]
	v_mfma_f32_16x16x32_bf16 v[42:45], v[110:113], v[158:161], v[42:45]
	v_mfma_f32_16x16x32_bf16 v[10:13], v[118:121], v[158:161], v[10:13]
	v_mfma_f32_16x16x32_bf16 v[38:41], v[110:113], v[170:173], v[38:41]
	v_mfma_f32_16x16x32_bf16 v[14:17], v[118:121], v[170:173], v[14:17]
	v_mfma_f32_16x16x32_bf16 v[58:61], v[122:125], v[138:141], v[58:61]
	v_mfma_f32_16x16x32_bf16 v[50:53], v[130:133], v[138:141], v[50:53]
	v_mfma_f32_16x16x32_bf16 v[34:37], v[122:125], v[146:149], v[34:37]
	v_mfma_f32_16x16x32_bf16 v[18:21], v[130:133], v[146:149], v[18:21]
	v_mfma_f32_16x16x32_bf16 v[30:33], v[122:125], v[154:157], v[30:33]
	v_mfma_f32_16x16x32_bf16 v[2:5], v[130:133], v[154:157], v[2:5]
	v_mfma_f32_16x16x32_bf16 v[26:29], v[122:125], v[162:165], v[26:29]
	v_mfma_f32_16x16x32_bf16 v[6:9], v[130:133], v[162:165], v[6:9]
	v_mfma_f32_16x16x32_bf16 v[58:61], v[126:129], v[142:145], v[58:61]
	v_mfma_f32_16x16x32_bf16 v[50:53], v[134:137], v[142:145], v[50:53]
	v_mfma_f32_16x16x32_bf16 v[34:37], v[126:129], v[150:153], v[34:37]
	v_mfma_f32_16x16x32_bf16 v[18:21], v[134:137], v[150:153], v[18:21]
	v_mfma_f32_16x16x32_bf16 v[30:33], v[126:129], v[158:161], v[30:33]
	v_mfma_f32_16x16x32_bf16 v[2:5], v[134:137], v[158:161], v[2:5]
	v_mfma_f32_16x16x32_bf16 v[26:29], v[126:129], v[170:173], v[26:29]
	v_mfma_f32_16x16x32_bf16 v[6:9], v[134:137], v[170:173], v[6:9]
	s_barrier
	s_cbranch_scc0 .LBB0_1001
	s_and_b64 vcc, exec, s[2:3]
	s_cbranch_vccz .LBB0_1004
	s_barrier

; #define PG8_STAGE(bufoff, gbase, voff) do { _Pragma("unroll") for (int _i = 0; _i < 2; ++_i) \
;         __builtin_amdgcn_global_load_lds((const unsigned*)((const char*)(gbase) + (voff)[_i]), (LAS unsigned*)(lds + (bufoff) + ldsw + _i * 8192), 16, 0, 0); } while (0)
; #define PG8_LDA(dst, b, h) do { _Pragma("unroll") for (int m = 0; m < 4; ++m) _Pragma("unroll") for (int k = 0; k < 2; ++k) dst[m][k] = *(const LAS bf16x8*)(lds + PG8_SA(b, h) + aoff + m * 2048 + k * 1024); } while (0)
; #define PG8_LDB(dst, b, h) do { _Pragma("unroll") for (int n = 0; n < 2; ++n) _Pragma("unroll") for (int k = 0; k < 2; ++k) dst[n][k] = *(const LAS bf16x8*)(lds + PG8_SB(b, h) + boff + n * 2048 + k * 1024); } while (0)
; #define PG8_MMA(ai, bj, At, Bt) do { __builtin_amdgcn_s_setprio(1); _Pragma("unroll") for (int m = 0; m < 4; ++m) _Pragma("unroll") for (int n = 0; n < 2; ++n) _Pragma("unroll") for (int k = 0; k < 2; ++k) \
;         acc[ai][bj][m][n] = __builtin_amdgcn_mfma_f32_16x16x32_bf16(Bt[n][k], At[m][k], acc[ai][bj][m][n], 0, 0, 0); __builtin_amdgcn_s_setprio(0); } while (0)
; #define PG8_WAIT_V(n) asm volatile("s_waitcnt vmcnt(" #n ")" ::: "memory")
; #define PG8_WAIT_L(n) asm volatile("s_waitcnt lgkmcnt(" #n ")" ::: "memory")
; #define PG8_BAR __builtin_amdgcn_s_barrier()
; #define PG8_SCHED __builtin_amdgcn_sched_barrier(0)
; template <class Epi, class Sched, bool ALIGN_EPI, class Hook = NoHook>
; __device__ __forceinline__ void gemm_phase(LAS unsigned char* lds, const Gemm g, const Sched& S, const Epi& E, const Hook& H = Hook()) {
;     ...
;             PG8_LDB(B0, 0, 0); PG8_LDB(B1, 0, 1); PG8_SCHED; PG8_LDA(At, 0, 0); PG8_STAGE(PG8_SA(1, 1), a1 + hA, voffA);
;             PG8_WAIT_V(8); PG8_WAIT_L(0); PG8_BAR; PG8_MMA(0, 0, At, B0); PG8_MMA(0, 1, At, B1); PG8_BAR; PG8_SCHED;
;             PG8_LDA(At, 0, 1); PG8_STAGE(PG8_SB(0, 0), b2, voffB); PG8_STAGE(PG8_SB(0, 1), b2 + hB, voffB); PG8_STAGE(PG8_SA(0, 0), a2, voffA);
;             PG8_WAIT_V(8); PG8_WAIT_L(0); PG8_BAR; PG8_MMA(1, 0, At, B0); PG8_MMA(1, 1, At, B1); PG8_BAR; PG8_SCHED;
.LBB0_1360:
	ds_read_b128 v[146:149], v1
	ds_read_b128 v[150:153], v1 offset:1024
	s_add_u32 s14, s4, 0xbb050080
	s_addc_u32 s15, s5, -1
	s_cmpk_lg_i32 s41, 0xa8
	s_cselect_b32 s14, s14, 0
	s_cselect_b32 s15, s15, 0
	s_add_u32 s20, s0, s14
	s_addc_u32 s21, s1, s15
	s_add_u32 s14, s12, s14
	s_addc_u32 s15, s13, s15
	s_mov_b32 m0, s42
	ds_read_b128 v[154:157], v1 offset:2048
	ds_read_b128 v[158:161], v1 offset:3072
	ds_read_b128 v[164:167], v142
	ds_read_b128 v[170:173], v142 offset:1024
	ds_read_b128 v[174:177], v142 offset:2048
	ds_read_b128 v[178:181], v142 offset:3072
	v_lshl_add_u64 v[214:215], v[138:139], 0, s[4:5]
	global_load_lds_dwordx4 v[214:215], off
	ds_read_b128 v[182:185], v143
	ds_read_b128 v[186:189], v143 offset:1024
	ds_read_b128 v[190:193], v143 offset:2048
	ds_read_b128 v[194:197], v143 offset:3072
	ds_read_b128 v[198:201], v143 offset:4096
	ds_read_b128 v[202:205], v143 offset:5120
	ds_read_b128 v[206:209], v143 offset:6144
	ds_read_b128 v[210:213], v143 offset:7168
	v_lshl_add_u64 v[214:215], v[140:141], 0, s[4:5]
	s_mov_b32 m0, s43
	s_nop 0
	global_load_lds_dwordx4 v[214:215], off
	s_waitcnt vmcnt(8) lgkmcnt(0)
	s_barrier
	v_mfma_f32_16x16x32_bf16 v[82:85], v[146:149], v[182:185], v[82:85]
	v_mfma_f32_16x16x32_bf16 v[54:57], v[154:157], v[182:185], v[54:57]
	v_mfma_f32_16x16x32_bf16 v[58:61], v[146:149], v[190:193], v[58:61]
	v_mfma_f32_16x16x32_bf16 v[42:45], v[154:157], v[190:193], v[42:45]
	v_mfma_f32_16x16x32_bf16 v[70:73], v[146:149], v[198:201], v[70:73]
	v_mfma_f32_16x16x32_bf16 v[50:53], v[154:157], v[198:201], v[50:53]
	v_mfma_f32_16x16x32_bf16 v[86:89], v[146:149], v[206:209], v[86:89]
	v_mfma_f32_16x16x32_bf16 v[74:77], v[154:157], v[206:209], v[74:77]
	v_mfma_f32_16x16x32_bf16 v[82:85], v[150:153], v[186:189], v[82:85]
	v_mfma_f32_16x16x32_bf16 v[54:57], v[158:161], v[186:189], v[54:57]
	v_mfma_f32_16x16x32_bf16 v[58:61], v[150:153], v[194:197], v[58:61]
	v_mfma_f32_16x16x32_bf16 v[42:45], v[158:161], v[194:197], v[42:45]
	v_mfma_f32_16x16x32_bf16 v[70:73], v[150:153], v[202:205], v[70:73]
	v_mfma_f32_16x16x32_bf16 v[50:53], v[158:161], v[202:205], v[50:53]
	v_mfma_f32_16x16x32_bf16 v[86:89], v[150:153], v[210:213], v[86:89]
	v_mfma_f32_16x16x32_bf16 v[74:77], v[158:161], v[210:213], v[74:77]
	v_mfma_f32_16x16x32_bf16 v[14:17], v[164:167], v[182:185], v[14:17]
	v_mfma_f32_16x16x32_bf16 v[2:5], v[174:177], v[182:185], v[2:5]
	v_mfma_f32_16x16x32_bf16 v[18:21], v[164:167], v[190:193], v[18:21]
	v_mfma_f32_16x16x32_bf16 v[6:9], v[174:177], v[190:193], v[6:9]
	v_mfma_f32_16x16x32_bf16 v[22:25], v[164:167], v[198:201], v[22:25]
	v_mfma_f32_16x16x32_bf16 v[10:13], v[174:177], v[198:201], v[10:13]
	v_mfma_f32_16x16x32_bf16 v[30:33], v[164:167], v[206:209], v[30:33]
	v_mfma_f32_16x16x32_bf16 v[26:29], v[174:177], v[206:209], v[26:29]
	v_mfma_f32_16x16x32_bf16 v[14:17], v[170:173], v[186:189], v[14:17]
	v_mfma_f32_16x16x32_bf16 v[2:5], v[178:181], v[186:189], v[2:5]
	v_mfma_f32_16x16x32_bf16 v[18:21], v[170:173], v[194:197], v[18:21]
	v_mfma_f32_16x16x32_bf16 v[6:9], v[178:181], v[194:197], v[6:9]
	v_mfma_f32_16x16x32_bf16 v[22:25], v[170:173], v[202:205], v[22:25]
	v_mfma_f32_16x16x32_bf16 v[10:13], v[178:181], v[202:205], v[10:13]
	v_mfma_f32_16x16x32_bf16 v[30:33], v[170:173], v[210:213], v[30:33]
	v_mfma_f32_16x16x32_bf16 v[26:29], v[178:181], v[210:213], v[26:29]
	s_barrier
	s_mov_b32 m0, s44
	s_add_u32 s52, s14, 0x2b0000
	ds_read_b128 v[182:185], v143 offset:16384
	ds_read_b128 v[186:189], v143 offset:17408
	global_load_lds_dwordx4 v132, s[14:15]
	ds_read_b128 v[190:193], v143 offset:18432
	s_mov_b32 m0, s45
	s_addc_u32 s53, s15, 0
	global_load_lds_dwordx4 v136, s[14:15]
	ds_read_b128 v[194:197], v143 offset:19456
	s_mov_b32 m0, s46
	s_nop 0
	global_load_lds_dwordx4 v132, s[52:53]
	ds_read_b128 v[198:201], v143 offset:20480
	s_mov_b32 m0, s47
	s_nop 0
	global_load_lds_dwordx4 v136, s[52:53]
	ds_read_b128 v[202:205], v143 offset:21504
	s_add_u32 s56, s20, s2
	s_addc_u32 s57, s21, s3
	s_mov_b32 m0, s25
	s_nop 0
	global_load_lds_dwordx4 v130, s[20:21]
	ds_read_b128 v[206:209], v143 offset:22528
	s_mov_b32 m0, s27
	s_nop 0
	global_load_lds_dwordx4 v134, s[20:21]
	ds_read_b128 v[210:213], v143 offset:23552
	s_waitcnt vmcnt(8) lgkmcnt(0)
	s_barrier
	v_mfma_f32_16x16x32_bf16 v[94:97], v[146:149], v[182:185], v[94:97]
	v_mfma_f32_16x16x32_bf16 v[90:93], v[154:157], v[182:185], v[90:93]
	v_mfma_f32_16x16x32_bf16 v[106:109], v[146:149], v[190:193], v[106:109]
	v_mfma_f32_16x16x32_bf16 v[98:101], v[154:157], v[190:193], v[98:101]
	v_mfma_f32_16x16x32_bf16 v[110:113], v[146:149], v[198:201], v[110:113]
	v_mfma_f32_16x16x32_bf16 v[102:105], v[154:157], v[198:201], v[102:105]
	v_mfma_f32_16x16x32_bf16 v[126:129], v[146:149], v[206:209], v[126:129]
	v_mfma_f32_16x16x32_bf16 v[122:125], v[154:157], v[206:209], v[122:125]
	v_mfma_f32_16x16x32_bf16 v[94:97], v[150:153], v[186:189], v[94:97]
	v_mfma_f32_16x16x32_bf16 v[90:93], v[158:161], v[186:189], v[90:93]
	v_mfma_f32_16x16x32_bf16 v[106:109], v[150:153], v[194:197], v[106:109]
	v_mfma_f32_16x16x32_bf16 v[98:101], v[158:161], v[194:197], v[98:101]
	v_mfma_f32_16x16x32_bf16 v[110:113], v[150:153], v[202:205], v[110:113]
	v_mfma_f32_16x16x32_bf16 v[102:105], v[158:161], v[202:205], v[102:105]
	v_mfma_f32_16x16x32_bf16 v[126:129], v[150:153], v[210:213], v[126:129]
	v_mfma_f32_16x16x32_bf16 v[122:125], v[158:161], v[210:213], v[122:125]
	v_mfma_f32_16x16x32_bf16 v[38:41], v[164:167], v[182:185], v[38:41]
	v_mfma_f32_16x16x32_bf16 v[34:37], v[174:177], v[182:185], v[34:37]
	v_mfma_f32_16x16x32_bf16 v[66:69], v[164:167], v[190:193], v[66:69]
	v_mfma_f32_16x16x32_bf16 v[46:49], v[174:177], v[190:193], v[46:49]
	v_mfma_f32_16x16x32_bf16 v[78:81], v[164:167], v[198:201], v[78:81]
	v_mfma_f32_16x16x32_bf16 v[62:65], v[174:177], v[198:201], v[62:65]
	v_mfma_f32_16x16x32_bf16 v[118:121], v[164:167], v[206:209], v[118:121]
	v_mfma_f32_16x16x32_bf16 v[114:117], v[174:177], v[206:209], v[114:117]
	v_mfma_f32_16x16x32_bf16 v[38:41], v[170:173], v[186:189], v[38:41]
	v_mfma_f32_16x16x32_bf16 v[34:37], v[178:181], v[186:189], v[34:37]
	v_mfma_f32_16x16x32_bf16 v[66:69], v[170:173], v[194:197], v[66:69]
	v_mfma_f32_16x16x32_bf16 v[46:49], v[178:181], v[194:197], v[46:49]
	v_mfma_f32_16x16x32_bf16 v[78:81], v[170:173], v[202:205], v[78:81]
	v_mfma_f32_16x16x32_bf16 v[62:65], v[178:181], v[202:205], v[62:65]
	v_mfma_f32_16x16x32_bf16 v[118:121], v[170:173], v[210:213], v[118:121]
	v_mfma_f32_16x16x32_bf16 v[114:117], v[178:181], v[210:213], v[114:117]
	s_barrier
; #define PG8_STAGE(bufoff, gbase, voff) do { _Pragma("unroll") for (int _i = 0; _i < 2; ++_i) \
;         __builtin_amdgcn_global_load_lds((const unsigned*)((const char*)(gbase) + (voff)[_i]), (LAS unsigned*)(lds + (bufoff) + ldsw + _i * 8192), 16, 0, 0); } while (0)
; #define PG8_LDA(dst, b, h) do { _Pragma("unroll") for (int m = 0; m < 4; ++m) _Pragma("unroll") for (int k = 0; k < 2; ++k) dst[m][k] = *(const LAS bf16x8*)(lds + PG8_SA(b, h) + aoff + m * 2048 + k * 1024); } while (0)
; #define PG8_LDB(dst, b, h) do { _Pragma("unroll") for (int n = 0; n < 2; ++n) _Pragma("unroll") for (int k = 0; k < 2; ++k) dst[n][k] = *(const LAS bf16x8*)(lds + PG8_SB(b, h) + boff + n * 2048 + k * 1024); } while (0)
; #define PG8_MMA(ai, bj, At, Bt) do { __builtin_amdgcn_s_setprio(1); _Pragma("unroll") for (int m = 0; m < 4; ++m) _Pragma("unroll") for (int n = 0; n < 2; ++n) _Pragma("unroll") for (int k = 0; k < 2; ++k) \
;         acc[ai][bj][m][n] = __builtin_amdgcn_mfma_f32_16x16x32_bf16(Bt[n][k], At[m][k], acc[ai][bj][m][n], 0, 0, 0); __builtin_amdgcn_s_setprio(0); } while (0)
; #define PG8_WAIT_V(n) asm volatile("s_waitcnt vmcnt(" #n ")" ::: "memory")
; #define PG8_WAIT_L(n) asm volatile("s_waitcnt lgkmcnt(" #n ")" ::: "memory")
; #define PG8_BAR __builtin_amdgcn_s_barrier()
; #define PG8_SCHED __builtin_amdgcn_sched_barrier(0)
; template <class Epi, class Sched, bool ALIGN_EPI, class Hook = NoHook>
; __device__ __forceinline__ void gemm_phase(LAS unsigned char* lds, const Gemm g, const Sched& S, const Epi& E, const Hook& H = Hook()) {
;     ...
;             PG8_LDB(B0, 1, 0); PG8_LDB(B1, 1, 1); PG8_SCHED; PG8_LDA(At, 1, 0); PG8_STAGE(PG8_SA(0, 1), a2 + hA, voffA);
;             PG8_WAIT_V(8); PG8_WAIT_L(0); PG8_BAR; PG8_MMA(0, 0, At, B0); PG8_MMA(0, 1, At, B1); PG8_BAR; PG8_SCHED;
;             PG8_LDA(At, 1, 1); PG8_STAGE(PG8_SB(1, 0), b3, voffB); PG8_STAGE(PG8_SB(1, 1), b3 + hB, voffB); PG8_STAGE(PG8_SA(1, 0), a3, voffA);
;             PG8_WAIT_V(8); PG8_WAIT_L(0); PG8_BAR; PG8_MMA(1, 0, At, B0); PG8_MMA(1, 1, At, B1); PG8_BAR; PG8_SCHED;
;         }
	ds_read_b128 v[146:149], v144
	ds_read_b128 v[150:153], v144 offset:1024
	s_add_u32 s20, s20, 0x2b0000
	s_addc_u32 s21, s21, 0
	s_mov_b32 m0, s28
	s_nop 0
	global_load_lds_dwordx4 v130, s[20:21]
	ds_read_b128 v[154:157], v144 offset:2048
	ds_read_b128 v[158:161], v144 offset:3072
	ds_read_b128 v[164:167], v145
	ds_read_b128 v[170:173], v145 offset:1024
	ds_read_b128 v[174:177], v145 offset:2048
	ds_read_b128 v[178:181], v145 offset:3072
	ds_read_b128 v[182:185], v143 offset:32768
	s_mov_b32 m0, s38
	s_nop 0
	global_load_lds_dwordx4 v134, s[20:21]
	ds_read_b128 v[186:189], v143 offset:33792
	ds_read_b128 v[190:193], v143 offset:34816
	ds_read_b128 v[194:197], v143 offset:35840
	ds_read_b128 v[198:201], v143 offset:36864
	ds_read_b128 v[202:205], v143 offset:37888
	ds_read_b128 v[206:209], v143 offset:38912
	ds_read_b128 v[210:213], v143 offset:39936
	s_waitcnt vmcnt(8) lgkmcnt(0)
	s_barrier
	v_mfma_f32_16x16x32_bf16 v[82:85], v[146:149], v[182:185], v[82:85]
	v_mfma_f32_16x16x32_bf16 v[54:57], v[154:157], v[182:185], v[54:57]
	v_mfma_f32_16x16x32_bf16 v[58:61], v[146:149], v[190:193], v[58:61]
	v_mfma_f32_16x16x32_bf16 v[42:45], v[154:157], v[190:193], v[42:45]
	v_mfma_f32_16x16x32_bf16 v[70:73], v[146:149], v[198:201], v[70:73]
	v_mfma_f32_16x16x32_bf16 v[50:53], v[154:157], v[198:201], v[50:53]
	v_mfma_f32_16x16x32_bf16 v[86:89], v[146:149], v[206:209], v[86:89]
	v_mfma_f32_16x16x32_bf16 v[74:77], v[154:157], v[206:209], v[74:77]
	v_mfma_f32_16x16x32_bf16 v[82:85], v[150:153], v[186:189], v[82:85]
	v_mfma_f32_16x16x32_bf16 v[54:57], v[158:161], v[186:189], v[54:57]
	v_mfma_f32_16x16x32_bf16 v[58:61], v[150:153], v[194:197], v[58:61]
	v_mfma_f32_16x16x32_bf16 v[42:45], v[158:161], v[194:197], v[42:45]
	v_mfma_f32_16x16x32_bf16 v[70:73], v[150:153], v[202:205], v[70:73]
	v_mfma_f32_16x16x32_bf16 v[50:53], v[158:161], v[202:205], v[50:53]
	v_mfma_f32_16x16x32_bf16 v[86:89], v[150:153], v[210:213], v[86:89]
	v_mfma_f32_16x16x32_bf16 v[74:77], v[158:161], v[210:213], v[74:77]
	v_mfma_f32_16x16x32_bf16 v[14:17], v[164:167], v[182:185], v[14:17]
	v_mfma_f32_16x16x32_bf16 v[2:5], v[174:177], v[182:185], v[2:5]
	v_mfma_f32_16x16x32_bf16 v[18:21], v[164:167], v[190:193], v[18:21]
	v_mfma_f32_16x16x32_bf16 v[6:9], v[174:177], v[190:193], v[6:9]
	v_mfma_f32_16x16x32_bf16 v[22:25], v[164:167], v[198:201], v[22:25]
	v_mfma_f32_16x16x32_bf16 v[10:13], v[174:177], v[198:201], v[10:13]
	v_mfma_f32_16x16x32_bf16 v[30:33], v[164:167], v[206:209], v[30:33]
	v_mfma_f32_16x16x32_bf16 v[26:29], v[174:177], v[206:209], v[26:29]
	v_mfma_f32_16x16x32_bf16 v[14:17], v[170:173], v[186:189], v[14:17]
	v_mfma_f32_16x16x32_bf16 v[2:5], v[178:181], v[186:189], v[2:5]
	v_mfma_f32_16x16x32_bf16 v[18:21], v[170:173], v[194:197], v[18:21]
	v_mfma_f32_16x16x32_bf16 v[6:9], v[178:181], v[194:197], v[6:9]
	v_mfma_f32_16x16x32_bf16 v[22:25], v[170:173], v[202:205], v[22:25]
	v_mfma_f32_16x16x32_bf16 v[10:13], v[178:181], v[202:205], v[10:13]
	v_mfma_f32_16x16x32_bf16 v[30:33], v[170:173], v[210:213], v[30:33]
	v_mfma_f32_16x16x32_bf16 v[26:29], v[178:181], v[210:213], v[26:29]
	s_barrier
	s_mov_b32 m0, s48
	s_add_u32 s54, s14, s2
	s_addc_u32 s55, s15, s3
	s_add_u32 s14, s14, 0x2b0080
	ds_read_b128 v[182:185], v143 offset:49152
	ds_read_b128 v[186:189], v143 offset:50176
	global_load_lds_dwordx4 v132, s[54:55]
	ds_read_b128 v[190:193], v143 offset:51200
	s_mov_b32 m0, s49
	s_addc_u32 s15, s15, 0
	global_load_lds_dwordx4 v136, s[54:55]
	ds_read_b128 v[194:197], v143 offset:52224
	s_mov_b32 m0, s50
	s_nop 0
	global_load_lds_dwordx4 v132, s[14:15]
	ds_read_b128 v[198:201], v143 offset:53248
	s_mov_b32 m0, s51
	s_nop 0
	global_load_lds_dwordx4 v136, s[14:15]
	ds_read_b128 v[202:205], v143 offset:54272
	s_mov_b32 m0, s39
	s_nop 0
	global_load_lds_dwordx4 v130, s[56:57]
	ds_read_b128 v[206:209], v143 offset:55296
	s_mov_b32 m0, s40
	s_nop 0
	global_load_lds_dwordx4 v134, s[56:57]
	s_add_i32 s41, s41, 2
	s_add_u32 s4, s4, 0x100
	s_addc_u32 s5, s5, 0
	s_cmpk_gt_u32 s41, 0xa9
	ds_read_b128 v[210:213], v143 offset:56320
	s_waitcnt vmcnt(8) lgkmcnt(0)
	s_barrier
	v_mfma_f32_16x16x32_bf16 v[94:97], v[146:149], v[182:185], v[94:97]
	v_mfma_f32_16x16x32_bf16 v[90:93], v[154:157], v[182:185], v[90:93]
	v_mfma_f32_16x16x32_bf16 v[106:109], v[146:149], v[190:193], v[106:109]
	v_mfma_f32_16x16x32_bf16 v[98:101], v[154:157], v[190:193], v[98:101]
	v_mfma_f32_16x16x32_bf16 v[110:113], v[146:149], v[198:201], v[110:113]
	v_mfma_f32_16x16x32_bf16 v[102:105], v[154:157], v[198:201], v[102:105]
	v_mfma_f32_16x16x32_bf16 v[126:129], v[146:149], v[206:209], v[126:129]
	v_mfma_f32_16x16x32_bf16 v[122:125], v[154:157], v[206:209], v[122:125]
	v_mfma_f32_16x16x32_bf16 v[94:97], v[150:153], v[186:189], v[94:97]
	v_mfma_f32_16x16x32_bf16 v[90:93], v[158:161], v[186:189], v[90:93]
	v_mfma_f32_16x16x32_bf16 v[106:109], v[150:153], v[194:197], v[106:109]
	v_mfma_f32_16x16x32_bf16 v[98:101], v[158:161], v[194:197], v[98:101]
	v_mfma_f32_16x16x32_bf16 v[110:113], v[150:153], v[202:205], v[110:113]
	v_mfma_f32_16x16x32_bf16 v[102:105], v[158:161], v[202:205], v[102:105]
	v_mfma_f32_16x16x32_bf16 v[126:129], v[150:153], v[210:213], v[126:129]
	v_mfma_f32_16x16x32_bf16 v[122:125], v[158:161], v[210:213], v[122:125]
	v_mfma_f32_16x16x32_bf16 v[38:41], v[164:167], v[182:185], v[38:41]
	v_mfma_f32_16x16x32_bf16 v[34:37], v[174:177], v[182:185], v[34:37]
	v_mfma_f32_16x16x32_bf16 v[66:69], v[164:167], v[190:193], v[66:69]
	v_mfma_f32_16x16x32_bf16 v[46:49], v[174:177], v[190:193], v[46:49]
	v_mfma_f32_16x16x32_bf16 v[78:81], v[164:167], v[198:201], v[78:81]
	v_mfma_f32_16x16x32_bf16 v[62:65], v[174:177], v[198:201], v[62:65]
	v_mfma_f32_16x16x32_bf16 v[118:121], v[164:167], v[206:209], v[118:121]
	v_mfma_f32_16x16x32_bf16 v[114:117], v[174:177], v[206:209], v[114:117]
	v_mfma_f32_16x16x32_bf16 v[38:41], v[170:173], v[186:189], v[38:41]
	v_mfma_f32_16x16x32_bf16 v[34:37], v[178:181], v[186:189], v[34:37]
	v_mfma_f32_16x16x32_bf16 v[66:69], v[170:173], v[194:197], v[66:69]
	v_mfma_f32_16x16x32_bf16 v[46:49], v[178:181], v[194:197], v[46:49]
	v_mfma_f32_16x16x32_bf16 v[78:81], v[170:173], v[202:205], v[78:81]
	v_mfma_f32_16x16x32_bf16 v[62:65], v[178:181], v[202:205], v[62:65]
	v_mfma_f32_16x16x32_bf16 v[118:121], v[170:173], v[210:213], v[118:121]
	v_mfma_f32_16x16x32_bf16 v[114:117], v[178:181], v[210:213], v[114:117]
	s_barrier
	s_cbranch_scc0 .LBB0_1360
	s_cmpk_lt_u32 s26, 0x100
	s_cbranch_scc0 .LBB0_1363
	s_barrier

; #define PG8_STAGE(bufoff, gbase, voff) do { _Pragma("unroll") for (int _i = 0; _i < 2; ++_i) \
;         __builtin_amdgcn_global_load_lds((const unsigned*)((const char*)(gbase) + (voff)[_i]), (LAS unsigned*)(lds + (bufoff) + ldsw + _i * 8192), 16, 0, 0); } while (0)
; #define PG8_LDA(dst, b, h) do { _Pragma("unroll") for (int m = 0; m < 4; ++m) _Pragma("unroll") for (int k = 0; k < 2; ++k) dst[m][k] = *(const LAS bf16x8*)(lds + PG8_SA(b, h) + aoff + m * 2048 + k * 1024); } while (0)
; #define PG8_LDB(dst, b, h) do { _Pragma("unroll") for (int n = 0; n < 2; ++n) _Pragma("unroll") for (int k = 0; k < 2; ++k) dst[n][k] = *(const LAS bf16x8*)(lds + PG8_SB(b, h) + boff + n * 2048 + k * 1024); } while (0)
; #define PG8_MMA(ai, bj, At, Bt) do { __builtin_amdgcn_s_setprio(1); _Pragma("unroll") for (int m = 0; m < 4; ++m) _Pragma("unroll") for (int n = 0; n < 2; ++n) _Pragma("unroll") for (int k = 0; k < 2; ++k) \
;         acc[ai][bj][m][n] = __builtin_amdgcn_mfma_f32_16x16x32_bf16(Bt[n][k], At[m][k], acc[ai][bj][m][n], 0, 0, 0); __builtin_amdgcn_s_setprio(0); } while (0)
; #define PG8_WAIT_V(n) asm volatile("s_waitcnt vmcnt(" #n ")" ::: "memory")
; #define PG8_WAIT_L(n) asm volatile("s_waitcnt lgkmcnt(" #n ")" ::: "memory")
; #define PG8_BAR __builtin_amdgcn_s_barrier()
; #define PG8_SCHED __builtin_amdgcn_sched_barrier(0)
; template <class Epi, class Sched, bool ALIGN_EPI, class Hook = NoHook>
; __device__ __forceinline__ void gemm_phase(LAS unsigned char* lds, const Gemm g, const Sched& S, const Epi& E, const Hook& H = Hook()) {
;     ...
;             PG8_LDB(B0, 0, 0); PG8_LDB(B1, 0, 1); PG8_SCHED; PG8_LDA(At, 0, 0); PG8_STAGE(PG8_SA(1, 1), a1 + hA, voffA);
;             PG8_WAIT_V(8); PG8_WAIT_L(0); PG8_BAR; PG8_MMA(0, 0, At, B0); PG8_MMA(0, 1, At, B1); PG8_BAR; PG8_SCHED;
;             PG8_LDA(At, 0, 1); PG8_STAGE(PG8_SB(0, 0), b2, voffB); PG8_STAGE(PG8_SB(0, 1), b2 + hB, voffB); PG8_STAGE(PG8_SA(0, 0), a2, voffA);
;             PG8_WAIT_V(8); PG8_WAIT_L(0); PG8_BAR; PG8_MMA(1, 0, At, B0); PG8_MMA(1, 1, At, B1); PG8_BAR; PG8_SCHED;
.LBB0_1406:
	ds_read_b128 v[146:149], v140
	ds_read_b128 v[150:153], v140 offset:1024
	s_add_u32 s10, s4, 0xbb050080
	s_addc_u32 s11, s5, -1
	s_cmpk_lg_i32 s18, 0xa8
	s_cselect_b32 s10, s10, 0
	s_cselect_b32 s11, s11, 0
	s_add_u32 s16, s0, s10
	s_addc_u32 s17, s1, s11
	s_add_u32 s10, s12, s10
	s_addc_u32 s11, s13, s11
	s_mov_b32 m0, s19
	ds_read_b128 v[154:157], v140 offset:2048
	ds_read_b128 v[158:161], v140 offset:3072
	ds_read_b128 v[170:173], v141
	ds_read_b128 v[174:177], v141 offset:1024
	ds_read_b128 v[178:181], v141 offset:2048
	ds_read_b128 v[182:185], v141 offset:3072
	v_lshl_add_u64 v[218:219], v[136:137], 0, s[4:5]
	global_load_lds_dwordx4 v[218:219], off
	ds_read_b128 v[186:189], v142
	ds_read_b128 v[190:193], v142 offset:1024
	ds_read_b128 v[194:197], v142 offset:2048
	ds_read_b128 v[198:201], v142 offset:3072
	ds_read_b128 v[202:205], v142 offset:4096
	ds_read_b128 v[206:209], v142 offset:5120
	ds_read_b128 v[210:213], v142 offset:6144
	ds_read_b128 v[214:217], v142 offset:7168
	v_lshl_add_u64 v[218:219], v[138:139], 0, s[4:5]
	s_mov_b32 m0, s31
	s_nop 0
	global_load_lds_dwordx4 v[218:219], off
	s_waitcnt vmcnt(8) lgkmcnt(0)
	s_barrier
	v_mfma_f32_16x16x32_bf16 v[82:85], v[146:149], v[186:189], v[82:85]
	v_mfma_f32_16x16x32_bf16 v[54:57], v[154:157], v[186:189], v[54:57]
	v_mfma_f32_16x16x32_bf16 v[58:61], v[146:149], v[194:197], v[58:61]
	v_mfma_f32_16x16x32_bf16 v[42:45], v[154:157], v[194:197], v[42:45]
	v_mfma_f32_16x16x32_bf16 v[70:73], v[146:149], v[202:205], v[70:73]
	v_mfma_f32_16x16x32_bf16 v[50:53], v[154:157], v[202:205], v[50:53]
	v_mfma_f32_16x16x32_bf16 v[86:89], v[146:149], v[210:213], v[86:89]
	v_mfma_f32_16x16x32_bf16 v[74:77], v[154:157], v[210:213], v[74:77]
	v_mfma_f32_16x16x32_bf16 v[82:85], v[150:153], v[190:193], v[82:85]
	v_mfma_f32_16x16x32_bf16 v[54:57], v[158:161], v[190:193], v[54:57]
	v_mfma_f32_16x16x32_bf16 v[58:61], v[150:153], v[198:201], v[58:61]
	v_mfma_f32_16x16x32_bf16 v[42:45], v[158:161], v[198:201], v[42:45]
	v_mfma_f32_16x16x32_bf16 v[70:73], v[150:153], v[206:209], v[70:73]
	v_mfma_f32_16x16x32_bf16 v[50:53], v[158:161], v[206:209], v[50:53]
	v_mfma_f32_16x16x32_bf16 v[86:89], v[150:153], v[214:217], v[86:89]
	v_mfma_f32_16x16x32_bf16 v[74:77], v[158:161], v[214:217], v[74:77]
	v_mfma_f32_16x16x32_bf16 v[14:17], v[170:173], v[186:189], v[14:17]
	v_mfma_f32_16x16x32_bf16 v[2:5], v[178:181], v[186:189], v[2:5]
	v_mfma_f32_16x16x32_bf16 v[18:21], v[170:173], v[194:197], v[18:21]
	v_mfma_f32_16x16x32_bf16 v[6:9], v[178:181], v[194:197], v[6:9]
	v_mfma_f32_16x16x32_bf16 v[22:25], v[170:173], v[202:205], v[22:25]
	v_mfma_f32_16x16x32_bf16 v[10:13], v[178:181], v[202:205], v[10:13]
	v_mfma_f32_16x16x32_bf16 v[30:33], v[170:173], v[210:213], v[30:33]
	v_mfma_f32_16x16x32_bf16 v[26:29], v[178:181], v[210:213], v[26:29]
	v_mfma_f32_16x16x32_bf16 v[14:17], v[174:177], v[190:193], v[14:17]
	v_mfma_f32_16x16x32_bf16 v[2:5], v[182:185], v[190:193], v[2:5]
	v_mfma_f32_16x16x32_bf16 v[18:21], v[174:177], v[198:201], v[18:21]
	v_mfma_f32_16x16x32_bf16 v[6:9], v[182:185], v[198:201], v[6:9]
	v_mfma_f32_16x16x32_bf16 v[22:25], v[174:177], v[206:209], v[22:25]
	v_mfma_f32_16x16x32_bf16 v[10:13], v[182:185], v[206:209], v[10:13]
	v_mfma_f32_16x16x32_bf16 v[30:33], v[174:177], v[214:217], v[30:33]
	v_mfma_f32_16x16x32_bf16 v[26:29], v[182:185], v[214:217], v[26:29]
	s_barrier
	s_mov_b32 m0, s33
	s_add_u32 s46, s10, 0x2b0000
	ds_read_b128 v[186:189], v142 offset:16384
	ds_read_b128 v[190:193], v142 offset:17408
	global_load_lds_dwordx4 v162, s[10:11]
	ds_read_b128 v[194:197], v142 offset:18432
	s_mov_b32 m0, s34
	s_addc_u32 s47, s11, 0
	global_load_lds_dwordx4 v134, s[10:11]
	ds_read_b128 v[198:201], v142 offset:19456
	s_mov_b32 m0, s35
	s_nop 0
	global_load_lds_dwordx4 v162, s[46:47]
	ds_read_b128 v[202:205], v142 offset:20480
	s_mov_b32 m0, s43
	s_nop 0
	global_load_lds_dwordx4 v134, s[46:47]
	ds_read_b128 v[206:209], v142 offset:21504
	s_add_u32 s54, s16, s2
	s_addc_u32 s55, s17, s3
	s_mov_b32 m0, s27
	s_nop 0
	global_load_lds_dwordx4 v130, s[16:17]
	ds_read_b128 v[210:213], v142 offset:22528
	s_mov_b32 m0, s28
	s_nop 0
	global_load_lds_dwordx4 v132, s[16:17]
	ds_read_b128 v[214:217], v142 offset:23552
	s_waitcnt vmcnt(8) lgkmcnt(0)
	s_barrier
	v_mfma_f32_16x16x32_bf16 v[94:97], v[146:149], v[186:189], v[94:97]
	v_mfma_f32_16x16x32_bf16 v[90:93], v[154:157], v[186:189], v[90:93]
	v_mfma_f32_16x16x32_bf16 v[118:121], v[146:149], v[194:197], v[118:121]
	v_mfma_f32_16x16x32_bf16 v[98:101], v[154:157], v[194:197], v[98:101]
	v_mfma_f32_16x16x32_bf16 v[126:129], v[146:149], v[202:205], v[126:129]
	v_mfma_f32_16x16x32_bf16 v[110:113], v[154:157], v[202:205], v[110:113]
	v_mfma_f32_16x16x32_bf16 v[122:125], v[146:149], v[210:213], v[122:125]
	v_mfma_f32_16x16x32_bf16 v[114:117], v[154:157], v[210:213], v[114:117]
	v_mfma_f32_16x16x32_bf16 v[94:97], v[150:153], v[190:193], v[94:97]
	v_mfma_f32_16x16x32_bf16 v[90:93], v[158:161], v[190:193], v[90:93]
	v_mfma_f32_16x16x32_bf16 v[118:121], v[150:153], v[198:201], v[118:121]
	v_mfma_f32_16x16x32_bf16 v[98:101], v[158:161], v[198:201], v[98:101]
	v_mfma_f32_16x16x32_bf16 v[126:129], v[150:153], v[206:209], v[126:129]
	v_mfma_f32_16x16x32_bf16 v[110:113], v[158:161], v[206:209], v[110:113]
	v_mfma_f32_16x16x32_bf16 v[122:125], v[150:153], v[214:217], v[122:125]
	v_mfma_f32_16x16x32_bf16 v[114:117], v[158:161], v[214:217], v[114:117]
	v_mfma_f32_16x16x32_bf16 v[38:41], v[170:173], v[186:189], v[38:41]
	v_mfma_f32_16x16x32_bf16 v[34:37], v[178:181], v[186:189], v[34:37]
	v_mfma_f32_16x16x32_bf16 v[66:69], v[170:173], v[194:197], v[66:69]
	v_mfma_f32_16x16x32_bf16 v[46:49], v[178:181], v[194:197], v[46:49]
	v_mfma_f32_16x16x32_bf16 v[78:81], v[170:173], v[202:205], v[78:81]
	v_mfma_f32_16x16x32_bf16 v[62:65], v[178:181], v[202:205], v[62:65]
	v_mfma_f32_16x16x32_bf16 v[106:109], v[170:173], v[210:213], v[106:109]
	v_mfma_f32_16x16x32_bf16 v[102:105], v[178:181], v[210:213], v[102:105]
	v_mfma_f32_16x16x32_bf16 v[38:41], v[174:177], v[190:193], v[38:41]
	v_mfma_f32_16x16x32_bf16 v[34:37], v[182:185], v[190:193], v[34:37]
	v_mfma_f32_16x16x32_bf16 v[66:69], v[174:177], v[198:201], v[66:69]
	v_mfma_f32_16x16x32_bf16 v[46:49], v[182:185], v[198:201], v[46:49]
	v_mfma_f32_16x16x32_bf16 v[78:81], v[174:177], v[206:209], v[78:81]
	v_mfma_f32_16x16x32_bf16 v[62:65], v[182:185], v[206:209], v[62:65]
	v_mfma_f32_16x16x32_bf16 v[106:109], v[174:177], v[214:217], v[106:109]
	v_mfma_f32_16x16x32_bf16 v[102:105], v[182:185], v[214:217], v[102:105]
	s_barrier
; #define PG8_STAGE(bufoff, gbase, voff) do { _Pragma("unroll") for (int _i = 0; _i < 2; ++_i) \
;         __builtin_amdgcn_global_load_lds((const unsigned*)((const char*)(gbase) + (voff)[_i]), (LAS unsigned*)(lds + (bufoff) + ldsw + _i * 8192), 16, 0, 0); } while (0)
; #define PG8_LDA(dst, b, h) do { _Pragma("unroll") for (int m = 0; m < 4; ++m) _Pragma("unroll") for (int k = 0; k < 2; ++k) dst[m][k] = *(const LAS bf16x8*)(lds + PG8_SA(b, h) + aoff + m * 2048 + k * 1024); } while (0)
; #define PG8_LDB(dst, b, h) do { _Pragma("unroll") for (int n = 0; n < 2; ++n) _Pragma("unroll") for (int k = 0; k < 2; ++k) dst[n][k] = *(const LAS bf16x8*)(lds + PG8_SB(b, h) + boff + n * 2048 + k * 1024); } while (0)
; #define PG8_MMA(ai, bj, At, Bt) do { __builtin_amdgcn_s_setprio(1); _Pragma("unroll") for (int m = 0; m < 4; ++m) _Pragma("unroll") for (int n = 0; n < 2; ++n) _Pragma("unroll") for (int k = 0; k < 2; ++k) \
;         acc[ai][bj][m][n] = __builtin_amdgcn_mfma_f32_16x16x32_bf16(Bt[n][k], At[m][k], acc[ai][bj][m][n], 0, 0, 0); __builtin_amdgcn_s_setprio(0); } while (0)
; #define PG8_WAIT_V(n) asm volatile("s_waitcnt vmcnt(" #n ")" ::: "memory")
; #define PG8_WAIT_L(n) asm volatile("s_waitcnt lgkmcnt(" #n ")" ::: "memory")
; #define PG8_BAR __builtin_amdgcn_s_barrier()
; #define PG8_SCHED __builtin_amdgcn_sched_barrier(0)
; template <class Epi, class Sched, bool ALIGN_EPI, class Hook = NoHook>
; __device__ __forceinline__ void gemm_phase(LAS unsigned char* lds, const Gemm g, const Sched& S, const Epi& E, const Hook& H = Hook()) {
;     ...
;             PG8_LDB(B0, 1, 0); PG8_LDB(B1, 1, 1); PG8_SCHED; PG8_LDA(At, 1, 0); PG8_STAGE(PG8_SA(0, 1), a2 + hA, voffA);
;             PG8_WAIT_V(8); PG8_WAIT_L(0); PG8_BAR; PG8_MMA(0, 0, At, B0); PG8_MMA(0, 1, At, B1); PG8_BAR; PG8_SCHED;
;             PG8_LDA(At, 1, 1); PG8_STAGE(PG8_SB(1, 0), b3, voffB); PG8_STAGE(PG8_SB(1, 1), b3 + hB, voffB); PG8_STAGE(PG8_SA(1, 0), a3, voffA);
;             PG8_WAIT_V(8); PG8_WAIT_L(0); PG8_BAR; PG8_MMA(1, 0, At, B0); PG8_MMA(1, 1, At, B1); PG8_BAR; PG8_SCHED;
;         }
	ds_read_b128 v[146:149], v143
	ds_read_b128 v[150:153], v143 offset:1024
	s_add_u32 s16, s16, 0x2b0000
	s_addc_u32 s17, s17, 0
	s_mov_b32 m0, s29
	s_nop 0
	global_load_lds_dwordx4 v130, s[16:17]
	ds_read_b128 v[154:157], v143 offset:2048
	ds_read_b128 v[158:161], v143 offset:3072
	ds_read_b128 v[170:173], v144
	ds_read_b128 v[174:177], v144 offset:1024
	ds_read_b128 v[178:181], v144 offset:2048
	ds_read_b128 v[182:185], v144 offset:3072
	ds_read_b128 v[186:189], v142 offset:32768
	s_mov_b32 m0, s39
	s_nop 0
	global_load_lds_dwordx4 v132, s[16:17]
	ds_read_b128 v[190:193], v142 offset:33792
	ds_read_b128 v[194:197], v142 offset:34816
	ds_read_b128 v[198:201], v142 offset:35840
	ds_read_b128 v[202:205], v142 offset:36864
	ds_read_b128 v[206:209], v142 offset:37888
	ds_read_b128 v[210:213], v142 offset:38912
	ds_read_b128 v[214:217], v142 offset:39936
	s_waitcnt vmcnt(8) lgkmcnt(0)
	s_barrier
	v_mfma_f32_16x16x32_bf16 v[82:85], v[146:149], v[186:189], v[82:85]
	v_mfma_f32_16x16x32_bf16 v[54:57], v[154:157], v[186:189], v[54:57]
	v_mfma_f32_16x16x32_bf16 v[58:61], v[146:149], v[194:197], v[58:61]
	v_mfma_f32_16x16x32_bf16 v[42:45], v[154:157], v[194:197], v[42:45]
	v_mfma_f32_16x16x32_bf16 v[70:73], v[146:149], v[202:205], v[70:73]
	v_mfma_f32_16x16x32_bf16 v[50:53], v[154:157], v[202:205], v[50:53]
	v_mfma_f32_16x16x32_bf16 v[86:89], v[146:149], v[210:213], v[86:89]
	v_mfma_f32_16x16x32_bf16 v[74:77], v[154:157], v[210:213], v[74:77]
	v_mfma_f32_16x16x32_bf16 v[82:85], v[150:153], v[190:193], v[82:85]
	v_mfma_f32_16x16x32_bf16 v[54:57], v[158:161], v[190:193], v[54:57]
	v_mfma_f32_16x16x32_bf16 v[58:61], v[150:153], v[198:201], v[58:61]
	v_mfma_f32_16x16x32_bf16 v[42:45], v[158:161], v[198:201], v[42:45]
	v_mfma_f32_16x16x32_bf16 v[70:73], v[150:153], v[206:209], v[70:73]
	v_mfma_f32_16x16x32_bf16 v[50:53], v[158:161], v[206:209], v[50:53]
	v_mfma_f32_16x16x32_bf16 v[86:89], v[150:153], v[214:217], v[86:89]
	v_mfma_f32_16x16x32_bf16 v[74:77], v[158:161], v[214:217], v[74:77]
	v_mfma_f32_16x16x32_bf16 v[14:17], v[170:173], v[186:189], v[14:17]
	v_mfma_f32_16x16x32_bf16 v[2:5], v[178:181], v[186:189], v[2:5]
	v_mfma_f32_16x16x32_bf16 v[18:21], v[170:173], v[194:197], v[18:21]
	v_mfma_f32_16x16x32_bf16 v[6:9], v[178:181], v[194:197], v[6:9]
	v_mfma_f32_16x16x32_bf16 v[22:25], v[170:173], v[202:205], v[22:25]
	v_mfma_f32_16x16x32_bf16 v[10:13], v[178:181], v[202:205], v[10:13]
	v_mfma_f32_16x16x32_bf16 v[30:33], v[170:173], v[210:213], v[30:33]
	v_mfma_f32_16x16x32_bf16 v[26:29], v[178:181], v[210:213], v[26:29]
	v_mfma_f32_16x16x32_bf16 v[14:17], v[174:177], v[190:193], v[14:17]
	v_mfma_f32_16x16x32_bf16 v[2:5], v[182:185], v[190:193], v[2:5]
	v_mfma_f32_16x16x32_bf16 v[18:21], v[174:177], v[198:201], v[18:21]
	v_mfma_f32_16x16x32_bf16 v[6:9], v[182:185], v[198:201], v[6:9]
	v_mfma_f32_16x16x32_bf16 v[22:25], v[174:177], v[206:209], v[22:25]
	v_mfma_f32_16x16x32_bf16 v[10:13], v[182:185], v[206:209], v[10:13]
	v_mfma_f32_16x16x32_bf16 v[30:33], v[174:177], v[214:217], v[30:33]
	v_mfma_f32_16x16x32_bf16 v[26:29], v[182:185], v[214:217], v[26:29]
	s_barrier
	s_mov_b32 m0, s36
	s_add_u32 s52, s10, s2
	s_addc_u32 s53, s11, s3
	s_add_u32 s10, s10, 0x2b0080
	ds_read_b128 v[186:189], v142 offset:49152
	ds_read_b128 v[190:193], v142 offset:50176
	global_load_lds_dwordx4 v162, s[52:53]
	ds_read_b128 v[194:197], v142 offset:51200
	s_mov_b32 m0, s44
	s_addc_u32 s11, s11, 0
	global_load_lds_dwordx4 v134, s[52:53]
	ds_read_b128 v[198:201], v142 offset:52224
	s_mov_b32 m0, s37
	s_nop 0
	global_load_lds_dwordx4 v162, s[10:11]
	ds_read_b128 v[202:205], v142 offset:53248
	s_mov_b32 m0, s45
	s_nop 0
	global_load_lds_dwordx4 v134, s[10:11]
	ds_read_b128 v[206:209], v142 offset:54272
	s_mov_b32 m0, s41
	s_nop 0
	global_load_lds_dwordx4 v130, s[54:55]
	ds_read_b128 v[210:213], v142 offset:55296
	s_mov_b32 m0, s42
	s_nop 0
	global_load_lds_dwordx4 v132, s[54:55]
	s_add_i32 s18, s18, 2
	s_add_u32 s4, s4, 0x100
	s_addc_u32 s5, s5, 0
	s_cmpk_gt_u32 s18, 0xa9
	ds_read_b128 v[214:217], v142 offset:56320
	s_waitcnt vmcnt(8) lgkmcnt(0)
	s_barrier
	v_mfma_f32_16x16x32_bf16 v[94:97], v[146:149], v[186:189], v[94:97]
	v_mfma_f32_16x16x32_bf16 v[90:93], v[154:157], v[186:189], v[90:93]
	v_mfma_f32_16x16x32_bf16 v[118:121], v[146:149], v[194:197], v[118:121]
	v_mfma_f32_16x16x32_bf16 v[98:101], v[154:157], v[194:197], v[98:101]
	v_mfma_f32_16x16x32_bf16 v[126:129], v[146:149], v[202:205], v[126:129]
	v_mfma_f32_16x16x32_bf16 v[110:113], v[154:157], v[202:205], v[110:113]
	v_mfma_f32_16x16x32_bf16 v[122:125], v[146:149], v[210:213], v[122:125]
	v_mfma_f32_16x16x32_bf16 v[114:117], v[154:157], v[210:213], v[114:117]
	v_mfma_f32_16x16x32_bf16 v[94:97], v[150:153], v[190:193], v[94:97]
	v_mfma_f32_16x16x32_bf16 v[90:93], v[158:161], v[190:193], v[90:93]
	v_mfma_f32_16x16x32_bf16 v[118:121], v[150:153], v[198:201], v[118:121]
	v_mfma_f32_16x16x32_bf16 v[98:101], v[158:161], v[198:201], v[98:101]
	v_mfma_f32_16x16x32_bf16 v[126:129], v[150:153], v[206:209], v[126:129]
	v_mfma_f32_16x16x32_bf16 v[110:113], v[158:161], v[206:209], v[110:113]
	v_mfma_f32_16x16x32_bf16 v[122:125], v[150:153], v[214:217], v[122:125]
	v_mfma_f32_16x16x32_bf16 v[114:117], v[158:161], v[214:217], v[114:117]
	v_mfma_f32_16x16x32_bf16 v[38:41], v[170:173], v[186:189], v[38:41]
	v_mfma_f32_16x16x32_bf16 v[34:37], v[178:181], v[186:189], v[34:37]
	v_mfma_f32_16x16x32_bf16 v[66:69], v[170:173], v[194:197], v[66:69]
	v_mfma_f32_16x16x32_bf16 v[46:49], v[178:181], v[194:197], v[46:49]
	v_mfma_f32_16x16x32_bf16 v[78:81], v[170:173], v[202:205], v[78:81]
	v_mfma_f32_16x16x32_bf16 v[62:65], v[178:181], v[202:205], v[62:65]
	v_mfma_f32_16x16x32_bf16 v[106:109], v[170:173], v[210:213], v[106:109]
	v_mfma_f32_16x16x32_bf16 v[102:105], v[178:181], v[210:213], v[102:105]
	v_mfma_f32_16x16x32_bf16 v[38:41], v[174:177], v[190:193], v[38:41]
	v_mfma_f32_16x16x32_bf16 v[34:37], v[182:185], v[190:193], v[34:37]
	v_mfma_f32_16x16x32_bf16 v[66:69], v[174:177], v[198:201], v[66:69]
	v_mfma_f32_16x16x32_bf16 v[46:49], v[182:185], v[198:201], v[46:49]
	v_mfma_f32_16x16x32_bf16 v[78:81], v[174:177], v[206:209], v[78:81]
	v_mfma_f32_16x16x32_bf16 v[62:65], v[182:185], v[206:209], v[62:65]
	v_mfma_f32_16x16x32_bf16 v[106:109], v[174:177], v[214:217], v[106:109]
	v_mfma_f32_16x16x32_bf16 v[102:105], v[182:185], v[214:217], v[102:105]
	s_barrier
	s_cbranch_scc0 .LBB0_1406
	s_cmpk_lt_u32 s22, 0x100
	s_cbranch_scc0 .LBB0_1409
	s_barrier
